# token mixer: hoist SGU LayerNorm gamma/beta loads (16 dwordx4 preloads per tile) instead of 32 serialized load+wait round trips
# speedup vs baseline: 1.0236x; 1.0071x over previous
; __device__ __forceinline__ void p2_block(LAS unsigned char* lds, const bf16_t* __restrict__ PROJ, bf16_t* __restrict__ ATT, bf16_t* __restrict__ SGU, const float* __restrict__ qn, const float* __restrict__ kn, ...
;     ...
;     const int b = item >> 6, n = (item >> 2) & 15, kvh = item & 3;
;     const int lane = tid & 63, w = __builtin_amdgcn_readfirstlane(tid >> 6), fr = lane & 15, fq = lane >> 4;
;     LAS unsigned char* KS = lds; LAS unsigned char* VT = lds + KS_BYTES;
;     const int g = w >> 1, rbase = (w & 1) * 64, hq = kvh * 4 + g;
;     const int kk = tid >> 1, h = tid & 1, s = n * 128 - 128 + kk, sc = s < 0 ? 0 : s;
;     const bf16_t* rowp = PROJ + (size_t)(b * pg8::SEQ + sc) * pg8::IN_W;
;     const bf16_t* kp = rowp + pg8::C_K + kvh * 64 + 16 * h;
;     const u32x4 ka = *(const u32x4*)kp, kb = *(const u32x4*)(kp + 8), kc = *(const u32x4*)(kp + 32), kd = *(const u32x4*)(kp + 40);
;     const bf16_t* vp = rowp + pg8::C_V + kvh * 64 + 32 * h;
;     u32x4 vv[4];
; #pragma unroll
;     for (int c4 = 0; c4 < 4; ++c4) vv[c4] = *(const u32x4*)(vp + 8 * c4);
;     const int sp_ = tid >> 2, q4 = tid & 3;
;     u32x4 sv[2][4];
;     const bf16_t* svsrc = PROJ + ((size_t)b * pg8::SEQ + n * 128 + sp_) * pg8::IN_W + pg8::C_VS + (2 * kvh) * 128 + 32 * q4;
; #pragma unroll
;     for (int c4 = 0; c4 < 4; ++c4) sv[0][c4] = *(const u32x4*)(svsrc + 8 * c4);
;     u32x4 qa[4], qb[4];
; #pragma unroll
;     for (int c = 0; c < 2; ++c) { const bf16_t* qp = PROJ + ((size_t)b * pg8::SEQ + n * 128 + rbase + 16 * c + fr) * pg8::IN_W + hq * 64 + 8 * fq; qa[c] = *(const u32x4*)qp; qb[c] = *(const u32x4*)(qp + 32); }
;     {
;         const float valid = s < 0 ? 0.f : 1.f;
;         float x1[16], x2[16]; unpack8(ka, x1); unpack8(kb, x1 + 8); unpack8(kc, x2); unpack8(kd, x2 + 8);
;         float ss = 0.f;
; #pragma unroll
;         for (int j = 0; j < 16; ++j) ss += x1[j] * x1[j] + x2[j] * x2[j];
;         ss += __shfl_xor(ss, 1);
;         const float rinv = rsqrtf(ss * (1.0f / 64.0f) + pg8::EPS) * valid;
;         const float* cp = COS + sc * 32 + 16 * h; const float* sp = SIN + sc * 32 + 16 * h;
;         float o1[16], o2[16];
; #pragma unroll
;         for (int j = 0; j < 16; ++j) { const float a1 = x1[j] * rinv * kn[16 * h + j], a2 = x2[j] * rinv * kn[32 + 16 * h + j], c = cp[j], sn = sp[j]; o1[j] = a1 * c - a2 * sn; o2[j] = a2 * c + a1 * sn; }
.LBB0_330:
	s_bfe_u32 s27, s2, 0x40002
	v_mov_b32_e32 v160, v204
	s_lshl_b32 s17, s27, 7
	s_add_i32 s4, s17, 0xffffff80
	v_ashrrev_i32_e32 v167, 1, v160
	v_add_u32_e32 v22, s4, v167
	s_ashr_i32 s6, s2, 6
	v_max_i32_e32 v66, 0, v22
	s_and_b32 s73, s2, 3
	v_lshl_add_u32 v0, s6, 11, v66
	s_waitcnt lgkmcnt(0)
	v_mov_b64_e32 v[2:3], s[10:11]
	v_and_b32_e32 v166, 1, v160
	v_mad_i64_i32 v[4:5], s[24:25], v0, s83, v[2:3]
	s_lshl_b32 s4, s73, 7
	v_lshl_add_u64 v[4:5], v[4:5], 0, s[4:5]
	v_lshlrev_b32_e32 v0, 5, v166
	v_lshl_add_u64 v[6:7], v[4:5], 0, v[0:1]
	global_load_dwordx4 v[50:53], v[6:7], off offset:2048
	global_load_dwordx4 v[58:61], v[6:7], off offset:2064
	global_load_dwordx4 v[54:57], v[6:7], off offset:2112
	global_load_dwordx4 v[62:65], v[6:7], off offset:2128
	v_readfirstlane_b32 s16, v160
	s_ashr_i32 s77, s16, 7
	s_lshl_b32 s7, s73, 2
	s_add_i32 s42, s77, s7
	s_ashr_i32 s7, s6, 31
	v_lshlrev_b32_e32 v74, 6, v166
	v_mov_b32_e32 v75, v1
	v_ashrrev_i32_e32 v136, 2, v160
	s_lshl_b64 s[48:49], s[6:7], 11
	v_lshl_add_u64 v[4:5], v[4:5], 0, v[74:75]
	s_or_b32 s24, s48, s17
	s_mov_b32 s25, s49
	v_ashrrev_i32_e32 v137, 31, v136
	s_waitcnt lgkmcnt(0)
	global_load_dwordx4 v[18:21], v[4:5], off offset:2560
	global_load_dwordx4 v[14:17], v[4:5], off offset:2576
	global_load_dwordx4 v[10:13], v[4:5], off offset:2592
	global_load_dwordx4 v[6:9], v[4:5], off offset:2608
	v_lshl_add_u64 v[4:5], s[24:25], 0, v[136:137]
	v_mad_u64_u32 v[2:3], s[6:7], v4, s83, v[2:3]
	v_lshlrev_b32_e32 v4, 5, v160
	v_mad_i32_i24 v3, v5, s83, v3
	s_lshl_b32 s4, s73, 9
	v_and_b32_e32 v165, 0x60, v4
	v_lshl_add_u64 v[2:3], v[2:3], 0, s[4:5]
	v_lshlrev_b32_e32 v4, 1, v165
	v_mov_b32_e32 v5, v1
	v_lshl_add_u64 v[2:3], v[2:3], 0, v[4:5]
	s_mov_b64 s[6:7], 0x1400
	v_lshl_add_u64 v[138:139], v[2:3], 0, s[6:7]
	s_lshl_b32 s6, s42, 6
	s_ashr_i32 s7, s6, 31
	s_and_b32 s26, s16, 64
	s_lshl_b64 s[6:7], s[6:7], 1
	v_bfe_u32 v162, v160, 4, 2
	s_add_u32 s28, s10, s6
	s_movk_i32 s4, 0x1000
	v_and_b32_e32 v137, 15, v160
	s_addc_u32 s29, s11, s7
	v_lshlrev_b32_e32 v132, 4, v162
	v_mov_b32_e32 v133, v1
	v_and_b32_e32 v68, 64, v211
	v_add_co_u32_e32 v2, vcc, s4, v2
	v_or_b32_e32 v161, s26, v137
	v_lshl_add_u64 v[134:135], s[28:29], 0, v[132:133]
	v_xor_b32_e32 v67, 1, v211
	v_add_u32_e32 v133, 64, v68
	v_addc_co_u32_e32 v3, vcc, 0, v3, vcc
	v_or_b32_e32 v163, s24, v161
	v_cmp_lt_i32_e64 s[40:41], v67, v133
	v_cmp_gt_i32_e32 vcc, 0, v22
	v_mad_u64_u32 v[22:23], s[28:29], v163, s83, v[134:135]
	v_cndmask_b32_e64 v67, v211, v67, s[40:41]
	v_mad_i32_i24 v23, s49, v212, v23
	v_lshlrev_b32_e32 v164, 2, v67
	v_lshlrev_b32_e32 v66, 5, v66
	v_mov_b32_e32 v67, v1
	v_readlane_b32 s44, v250, 36
	v_readlane_b32 s46, v250, 38
	global_load_dwordx4 v[46:49], v[2:3], off offset:1024
	global_load_dwordx4 v[34:37], v[138:139], off offset:48
	global_load_dwordx4 v[38:41], v[138:139], off offset:32
	global_load_dwordx4 v[42:45], v[138:139], off offset:16
	s_nop 0
	global_load_dwordx4 v[2:5], v[22:23], off
	global_load_dwordx4 v[30:33], v[22:23], off offset:64
	v_or_b32_e32 v22, 16, v163
	v_lshlrev_b64 v[66:67], 2, v[66:67]
	v_readlane_b32 s45, v250, 37
	v_readlane_b32 s47, v250, 39
	v_mad_u64_u32 v[26:27], s[28:29], v22, s83, v[134:135]
	v_lshl_add_u64 v[68:69], s[44:45], 0, v[66:67]
	v_lshl_add_u64 v[66:67], s[46:47], 0, v[66:67]
	v_mad_i32_i24 v27, s49, v212, v27
	v_lshl_add_u64 v[86:87], v[68:69], 0, v[74:75]
	v_lshl_add_u64 v[126:127], v[66:67], 0, v[74:75]
	global_load_dwordx4 v[22:25], v[26:27], off
	s_nop 0
	global_load_dwordx4 v[26:29], v[26:27], off offset:64
	s_nop 0
	global_load_dwordx4 v[66:69], v74, s[0:1] offset:48
	global_load_dwordx4 v[78:81], v74, s[0:1] offset:32
	global_load_dwordx4 v[94:97], v74, s[0:1] offset:16
	global_load_dwordx4 v[106:109], v74, s[0:1]
	global_load_dwordx4 v[70:73], v74, s[0:1] offset:176
	global_load_dwordx4 v[82:85], v74, s[0:1] offset:160
	global_load_dwordx4 v[98:101], v74, s[0:1] offset:144
	global_load_dwordx4 v[110:113], v74, s[0:1] offset:128
	s_nop 0
	global_load_dwordx4 v[74:77], v[86:87], off offset:48
	global_load_dwordx4 v[90:93], v[86:87], off offset:32
	global_load_dwordx4 v[102:105], v[86:87], off offset:16
	global_load_dwordx4 v[114:117], v[86:87], off
	s_nop 0
	global_load_dwordx4 v[86:89], v[126:127], off offset:48
	global_load_dwordx4 v[118:121], v[126:127], off offset:32
	global_load_dwordx4 v[122:125], v[126:127], off offset:16
	s_nop 0
	global_load_dwordx4 v[126:129], v[126:127], off
	v_cndmask_b32_e64 v180, 1.0, 0, vcc
	s_lshl_b32 s4, s73, 10
	s_waitcnt vmcnt(0)
; __device__ __forceinline__ void unpack8(const u32x4 w, float* f) { f[0] = bf_lo(w.x); f[1] = bf_hi(w.x); f[2] = bf_lo(w.y); f[3] = bf_hi(w.y); f[4] = bf_lo(w.z); f[5] = bf_hi(w.z); f[6] = bf_lo(w.w); f[7] = bf_hi(w.w); }
; __device__ __forceinline__ void p2_block(LAS unsigned char* lds, const bf16_t* __restrict__ PROJ, bf16_t* __restrict__ ATT, bf16_t* __restrict__ SGU, const float* __restrict__ qn, const float* __restrict__ kn, ...
;     ...
;         float x1[16], x2[16]; unpack8(ka, x1); unpack8(kb, x1 + 8); unpack8(kc, x2); unpack8(kd, x2 + 8);
;         float ss = 0.f;
; #pragma unroll
;         for (int j = 0; j < 16; ++j) ss += x1[j] * x1[j] + x2[j] * x2[j];
;         ss += __shfl_xor(ss, 1);
;         const float rinv = rsqrtf(ss * (1.0f / 64.0f) + pg8::EPS) * valid;
;         const float* cp = COS + sc * 32 + 16 * h; const float* sp = SIN + sc * 32 + 16 * h;
;         float o1[16], o2[16];
; #pragma unroll
;         for (int j = 0; j < 16; ++j) { const float a1 = x1[j] * rinv * kn[16 * h + j], a2 = x2[j] * rinv * kn[32 + 16 * h + j], c = cp[j], sn = sp[j]; o1[j] = a1 * c - a2 * sn; o2[j] = a2 * c + a1 * sn; }
	v_lshlrev_b32_e32 v226, 16, v51
	v_lshlrev_b32_e32 v142, 16, v61
	v_and_b32_e32 v140, 0xffff0000, v61
	v_lshlrev_b32_e32 v143, 16, v65
	v_and_b32_e32 v141, 0xffff0000, v65
	v_mov_b32_e32 v150, v141
	v_mov_b32_e32 v151, v143
	v_mov_b32_e32 v148, v140
	v_mov_b32_e32 v149, v142
	v_pk_mul_f32 v[150:151], v[150:151], v[150:151]
	v_and_b32_e32 v61, 0xffff0000, v64
	v_pk_fma_f32 v[182:183], v[148:149], v[148:149], v[150:151]
	v_lshlrev_b32_e32 v149, 16, v64
	v_lshlrev_b32_e32 v148, 16, v60
	v_and_b32_e32 v60, 0xffff0000, v60
	v_mov_b32_e32 v154, v61
	v_mov_b32_e32 v155, v149
	v_mov_b32_e32 v64, v60
	v_mov_b32_e32 v65, v148
	v_pk_mul_f32 v[154:155], v[154:155], v[154:155]
	v_and_b32_e32 v201, 0xffff0000, v57
	v_pk_fma_f32 v[184:185], v[64:65], v[64:65], v[154:155]
	v_lshlrev_b32_e32 v155, 16, v63
	v_and_b32_e32 v65, 0xffff0000, v63
	v_lshlrev_b32_e32 v154, 16, v59
	v_and_b32_e32 v64, 0xffff0000, v59
	v_mov_b32_e32 v188, v65
	v_mov_b32_e32 v189, v155
	v_mov_b32_e32 v186, v64
	v_mov_b32_e32 v187, v154
	v_pk_mul_f32 v[188:189], v[188:189], v[188:189]
	v_and_b32_e32 v59, 0xffff0000, v62
	v_pk_fma_f32 v[186:187], v[186:187], v[186:187], v[188:189]
	v_lshlrev_b32_e32 v189, 16, v62
	v_lshlrev_b32_e32 v188, 16, v58
	v_and_b32_e32 v58, 0xffff0000, v58
	v_mov_b32_e32 v194, v59
	v_mov_b32_e32 v195, v189
	v_mov_b32_e32 v62, v58
	v_mov_b32_e32 v63, v188
	v_pk_mul_f32 v[194:195], v[194:195], v[194:195]
	v_and_b32_e32 v234, 0xffff0000, v51
	v_pk_fma_f32 v[62:63], v[62:63], v[62:63], v[194:195]
	v_lshlrev_b32_e32 v195, 16, v57
	v_lshlrev_b32_e32 v239, 16, v54
	v_lshlrev_b32_e32 v238, 16, v50
	v_and_b32_e32 v51, 0xffff0000, v54
	v_and_b32_e32 v50, 0xffff0000, v50
	v_lshlrev_b32_e32 v194, 16, v53
	v_and_b32_e32 v200, 0xffff0000, v53
	v_mov_b32_e32 v218, v201
	v_mov_b32_e32 v219, v195
	v_lshlrev_b32_e32 v227, 16, v55
	v_and_b32_e32 v235, 0xffff0000, v55
	v_pk_mul_f32 v[240:241], v[238:239], v[238:239]
	v_pk_mul_f32 v[54:55], v[50:51], v[50:51]
	v_mov_b32_e32 v202, v200
	v_mov_b32_e32 v203, v194
	v_pk_mul_f32 v[218:219], v[218:219], v[218:219]
	v_pk_mul_f32 v[228:229], v[226:227], v[226:227]
	v_add_f32_e32 v54, v54, v55
	v_add_f32_e32 v55, v240, v241
	v_pk_fma_f32 v[202:203], v[202:203], v[202:203], v[218:219]
	v_lshlrev_b32_e32 v219, 16, v56
	v_lshlrev_b32_e32 v218, 16, v52
	v_pk_mul_f32 v[236:237], v[234:235], v[234:235]
	v_add_f32_e32 v54, v55, v54
	v_add_f32_e32 v55, v228, v229
	v_mov_b32_e32 v150, v66
	v_pk_mul_f32 v[220:221], v[218:219], v[218:219]
	v_and_b32_e32 v53, 0xffff0000, v56
	v_and_b32_e32 v52, 0xffff0000, v52
	v_add_f32_e32 v66, v236, v237
	v_add_f32_e32 v54, v55, v54
	v_pk_mul_f32 v[56:57], v[52:53], v[52:53]
	v_add_f32_e32 v54, v66, v54
	v_add_f32_e32 v55, v220, v221
	v_add_f32_e32 v54, v55, v54
	v_add_f32_e32 v55, v56, v57
	v_add_f32_e32 v54, v55, v54
	v_add_f32_e32 v54, v203, v54
	v_add_f32_e32 v54, v202, v54
	v_add_f32_e32 v54, v63, v54
	v_add_f32_e32 v54, v62, v54
	v_add_f32_e32 v54, v187, v54
	v_add_f32_e32 v54, v186, v54
	v_add_f32_e32 v54, v185, v54
	v_add_f32_e32 v54, v184, v54
	v_add_f32_e32 v54, v183, v54
	v_add_f32_e32 v54, v182, v54
	ds_bpermute_b32 v55, v164, v54
	v_mov_b32_e32 v242, v106
	v_mov_b32_e32 v243, v110
	v_mov_b32_e32 v244, v114
	v_mov_b32_e32 v245, v126
	s_waitcnt lgkmcnt(0)
	v_add_f32_e32 v54, v54, v55
	v_fmamk_f32 v54, v54, 0x3c800000, v209
	v_cmp_gt_f32_e64 s[40:41], s82, v54
	v_mul_f32_e32 v55, 0x4b800000, v54
	v_mov_b32_e32 v110, v107
	v_cndmask_b32_e64 v54, v54, v55, s[40:41]
	v_rsq_f32_e32 v54, v54
	v_mov_b32_e32 v230, v108
	v_mov_b32_e32 v231, v112
	v_mov_b32_e32 v232, v116
	v_mul_f32_e32 v55, 0x45800000, v54
	v_cndmask_b32_e64 v54, v54, v55, s[40:41]
	v_mul_f32_e32 v54, v180, v54
	v_pk_mul_f32 v[56:57], v[54:55], v[238:239] op_sel_hi:[0,1]
	v_pk_mul_f32 v[56:57], v[242:243], v[56:57]
	v_mov_b32_e32 v233, v128
	v_pk_mul_f32 v[62:63], v[244:245], v[56:57]
	v_mov_b32_e32 v144, v68
	v_sub_f32_e32 v55, v62, v63
	v_mov_b32_e32 v62, v126
	v_mov_b32_e32 v63, v114
	v_pk_mul_f32 v[50:51], v[54:55], v[50:51] op_sel_hi:[0,1]
	v_pk_mul_f32 v[56:57], v[62:63], v[56:57]
	v_pk_mul_f32 v[50:51], v[110:111], v[50:51]
	v_mov_b32_e32 v126, v115
	v_mov_b32_e32 v114, v127
	v_add_f32_e32 v62, v57, v56
	v_pk_mul_f32 v[56:57], v[126:127], v[50:51]
	v_pk_mul_f32 v[50:51], v[114:115], v[50:51]
	v_sub_f32_e32 v63, v56, v57
	v_add_f32_e32 v66, v51, v50
	v_pk_mul_f32 v[50:51], v[54:55], v[226:227] op_sel_hi:[0,1]
	v_pk_mul_f32 v[50:51], v[230:231], v[50:51]
	v_mov_b32_e32 v190, v78
	v_pk_mul_f32 v[56:57], v[232:233], v[50:51]
	v_mov_b32_e32 v112, v109
	v_sub_f32_e32 v68, v56, v57
	v_mov_b32_e32 v56, v128
	v_mov_b32_e32 v57, v116
	v_pk_mul_f32 v[50:51], v[56:57], v[50:51]
	v_mov_b32_e32 v128, v117
	v_add_f32_e32 v78, v51, v50
	v_pk_mul_f32 v[50:51], v[54:55], v[234:235] op_sel_hi:[0,1]
	v_pk_mul_f32 v[50:51], v[112:113], v[50:51]
	v_mov_b32_e32 v116, v129
	v_pk_mul_f32 v[56:57], v[128:129], v[50:51]
	v_pk_mul_f32 v[50:51], v[116:117], v[50:51]
	v_mov_b32_e32 v222, v94
	v_mov_b32_e32 v223, v98
	v_add_f32_e32 v94, v51, v50
	v_pk_mul_f32 v[50:51], v[54:55], v[218:219] op_sel_hi:[0,1]
	v_mov_b32_e32 v224, v102
	v_mov_b32_e32 v225, v122
	v_pk_mul_f32 v[50:51], v[50:51], v[222:223]
	v_mov_b32_e32 v156, v80
	v_sub_f32_e32 v80, v56, v57
	v_pk_mul_f32 v[56:57], v[50:51], v[224:225]
	v_mov_b32_e32 v196, v96
	v_sub_f32_e32 v96, v56, v57
	v_mov_b32_e32 v56, v122
	v_mov_b32_e32 v57, v102
	v_pk_mul_f32 v[50:51], v[50:51], v[56:57]
	v_mov_b32_e32 v98, v95
	v_add_f32_e32 v106, v51, v50
	v_pk_mul_f32 v[50:51], v[54:55], v[52:53] op_sel_hi:[0,1]
	v_pk_mul_f32 v[50:51], v[50:51], v[98:99]
	v_mov_b32_e32 v122, v103
	v_mov_b32_e32 v102, v123
; __device__ __forceinline__ unsigned cvt_pk_bf16(float lo, float hi) { unsigned r; asm volatile("v_cvt_pk_bf16_f32 %0, %1, %2" : "=v"(r) : "v"(lo), "v"(hi)); return r; }
; #define LAS __attribute__((address_space(3)))
; __device__ __forceinline__ void p2_block(LAS unsigned char* lds, const bf16_t* __restrict__ PROJ, bf16_t* __restrict__ ATT, bf16_t* __restrict__ SGU, const float* __restrict__ qn, const float* __restrict__ kn, ...
;     ...
;         for (int j = 0; j < 16; ++j) { const float a1 = x1[j] * rinv * kn[16 * h + j], a2 = x2[j] * rinv * kn[32 + 16 * h + j], c = cp[j], sn = sp[j]; o1[j] = a1 * c - a2 * sn; o2[j] = a2 * c + a1 * sn; }
;         LAS unsigned char* kdst = KS + kk * KS_STRIDE + 32 * h;
;         u32x4 w0, w1;
;         w0.x = cvt_pk_bf16(o1[0], o1[1]); w0.y = cvt_pk_bf16(o1[2], o1[3]); w0.z = cvt_pk_bf16(o1[4], o1[5]); w0.w = cvt_pk_bf16(o1[6], o1[7]);
;         w1.x = cvt_pk_bf16(o1[8], o1[9]); w1.y = cvt_pk_bf16(o1[10], o1[11]); w1.z = cvt_pk_bf16(o1[12], o1[13]); w1.w = cvt_pk_bf16(o1[14], o1[15]);
;         *(LAS u32x4*)kdst = w0; *(LAS u32x4*)(kdst + 16) = w1;
;         w0.x = cvt_pk_bf16(o2[0], o2[1]); w0.y = cvt_pk_bf16(o2[2], o2[3]); w0.z = cvt_pk_bf16(o2[4], o2[5]); w0.w = cvt_pk_bf16(o2[6], o2[7]);
;         w1.x = cvt_pk_bf16(o2[8], o2[9]); w1.y = cvt_pk_bf16(o2[10], o2[11]); w1.z = cvt_pk_bf16(o2[12], o2[13]); w1.w = cvt_pk_bf16(o2[14], o2[15]);
;         *(LAS u32x4*)(kdst + 64) = w0; *(LAS u32x4*)(kdst + 80) = w1;
;     ...
;         const float* gp = lng + gg * 128 + 32 * q4; const float* bp = lnb + gg * 128 + 32 * q4;
	v_pk_mul_f32 v[52:53], v[50:51], v[122:123]
	v_pk_mul_f32 v[50:51], v[50:51], v[102:103]
	v_mov_b32_e32 v197, v100
	v_add_f32_e32 v95, v51, v50
	v_pk_mul_f32 v[50:51], v[54:55], v[194:195] op_sel_hi:[0,1]
	v_mov_b32_e32 v198, v104
	v_mov_b32_e32 v199, v124
	v_pk_mul_f32 v[50:51], v[50:51], v[196:197]
	v_sub_f32_e32 v56, v52, v53
	v_pk_mul_f32 v[52:53], v[50:51], v[198:199]
	v_mov_b32_e32 v100, v97
	v_sub_f32_e32 v57, v52, v53
	v_mov_b32_e32 v52, v124
	v_mov_b32_e32 v53, v104
	v_pk_mul_f32 v[50:51], v[50:51], v[52:53]
	v_mov_b32_e32 v124, v105
	v_add_f32_e32 v98, v51, v50
	v_pk_mul_f32 v[50:51], v[54:55], v[200:201] op_sel_hi:[0,1]
	v_pk_mul_f32 v[50:51], v[50:51], v[100:101]
	v_mov_b32_e32 v104, v125
	v_pk_mul_f32 v[52:53], v[50:51], v[124:125]
	v_pk_mul_f32 v[50:51], v[50:51], v[104:105]
	v_mov_b32_e32 v191, v82
	v_add_f32_e32 v99, v51, v50
	v_pk_mul_f32 v[50:51], v[54:55], v[188:189] op_sel_hi:[0,1]
	v_mov_b32_e32 v192, v90
	v_mov_b32_e32 v193, v118
	v_pk_mul_f32 v[50:51], v[50:51], v[190:191]
	v_sub_f32_e32 v97, v52, v53
	v_pk_mul_f32 v[52:53], v[50:51], v[192:193]
	v_mov_b32_e32 v82, v79
	v_sub_f32_e32 v100, v52, v53
	v_mov_b32_e32 v52, v118
	v_mov_b32_e32 v53, v90
	v_pk_mul_f32 v[50:51], v[50:51], v[52:53]
	v_mov_b32_e32 v118, v91
	v_add_f32_e32 v101, v51, v50
	v_pk_mul_f32 v[50:51], v[54:55], v[58:59] op_sel_hi:[0,1]
	v_pk_mul_f32 v[50:51], v[50:51], v[82:83]
	v_mov_b32_e32 v90, v119
	v_pk_mul_f32 v[52:53], v[50:51], v[118:119]
	v_pk_mul_f32 v[50:51], v[50:51], v[90:91]
	v_mov_b32_e32 v157, v84
	v_add_f32_e32 v59, v51, v50
	v_pk_mul_f32 v[50:51], v[54:55], v[154:155] op_sel_hi:[0,1]
	v_mov_b32_e32 v158, v92
	v_mov_b32_e32 v159, v120
	v_pk_mul_f32 v[50:51], v[50:51], v[156:157]
	v_sub_f32_e32 v58, v52, v53
	v_pk_mul_f32 v[52:53], v[50:51], v[158:159]
	v_mov_b32_e32 v84, v81
	v_sub_f32_e32 v79, v52, v53
	v_mov_b32_e32 v52, v120
	v_mov_b32_e32 v53, v92
	v_pk_mul_f32 v[50:51], v[50:51], v[52:53]
	v_mov_b32_e32 v120, v93
	v_add_f32_e32 v82, v51, v50
	v_pk_mul_f32 v[50:51], v[54:55], v[64:65] op_sel_hi:[0,1]
	v_pk_mul_f32 v[50:51], v[50:51], v[84:85]
	v_mov_b32_e32 v92, v121
	v_pk_mul_f32 v[52:53], v[50:51], v[120:121]
	v_pk_mul_f32 v[50:51], v[50:51], v[92:93]
	v_mov_b32_e32 v151, v70
	v_add_f32_e32 v65, v51, v50
	v_pk_mul_f32 v[50:51], v[54:55], v[148:149] op_sel_hi:[0,1]
	v_mov_b32_e32 v152, v74
	v_mov_b32_e32 v153, v86
	v_pk_mul_f32 v[50:51], v[50:51], v[150:151]
	v_sub_f32_e32 v64, v52, v53
	v_pk_mul_f32 v[52:53], v[50:51], v[152:153]
	v_mov_b32_e32 v70, v67
	v_sub_f32_e32 v81, v52, v53
	v_mov_b32_e32 v52, v86
	v_mov_b32_e32 v53, v74
	v_pk_mul_f32 v[50:51], v[50:51], v[52:53]
	v_mov_b32_e32 v86, v75
	v_add_f32_e32 v83, v51, v50
	v_pk_mul_f32 v[50:51], v[54:55], v[60:61] op_sel_hi:[0,1]
	v_pk_mul_f32 v[50:51], v[50:51], v[70:71]
	v_mov_b32_e32 v74, v87
	v_pk_mul_f32 v[52:53], v[50:51], v[86:87]
	v_pk_mul_f32 v[50:51], v[50:51], v[74:75]
	v_mov_b32_e32 v145, v72
	v_add_f32_e32 v61, v51, v50
	v_pk_mul_f32 v[50:51], v[54:55], v[142:143] op_sel_hi:[0,1]
	v_mov_b32_e32 v146, v76
	v_mov_b32_e32 v147, v88
	v_pk_mul_f32 v[50:51], v[50:51], v[144:145]
	v_sub_f32_e32 v60, v52, v53
	v_pk_mul_f32 v[52:53], v[50:51], v[146:147]
	v_mov_b32_e32 v72, v69
	v_lshl_add_u32 v182, v165, 2, s4
	global_load_dwordx4 v[144:147], v182, s[36:37] offset:0
	global_load_dwordx4 v[148:151], v182, s[36:37] offset:16
	global_load_dwordx4 v[152:155], v182, s[36:37] offset:32
	global_load_dwordx4 v[156:159], v182, s[36:37] offset:48
	global_load_dwordx4 v[184:187], v182, s[36:37] offset:64
	global_load_dwordx4 v[188:191], v182, s[36:37] offset:80
	global_load_dwordx4 v[192:195], v182, s[36:37] offset:96
	global_load_dwordx4 v[196:199], v182, s[36:37] offset:112
	global_load_dwordx4 v[218:221], v182, s[18:19] offset:0
	global_load_dwordx4 v[222:225], v182, s[18:19] offset:16
	global_load_dwordx4 v[226:229], v182, s[18:19] offset:32
	global_load_dwordx4 v[230:233], v182, s[18:19] offset:48
	global_load_dwordx4 v[234:237], v182, s[18:19] offset:64
	global_load_dwordx4 v[238:241], v182, s[18:19] offset:80
	global_load_dwordx4 v[242:245], v182, s[18:19] offset:96
	global_load_dwordx4 v[200:203], v182, s[18:19] offset:112
	v_sub_f32_e32 v67, v52, v53
	v_mov_b32_e32 v52, v88
	v_mov_b32_e32 v53, v76
	v_pk_mul_f32 v[50:51], v[50:51], v[52:53]
	v_mov_b32_e32 v88, v77
	v_add_f32_e32 v70, v51, v50
	v_pk_mul_f32 v[50:51], v[54:55], v[140:141] op_sel_hi:[0,1]
	v_pk_mul_f32 v[50:51], v[50:51], v[72:73]
	v_mov_b32_e32 v76, v89
	v_pk_mul_f32 v[52:53], v[50:51], v[88:89]
	v_pk_mul_f32 v[50:51], v[50:51], v[76:77]
	v_sub_f32_e32 v69, v52, v53
	v_add_f32_e32 v71, v51, v50
	v_mul_lo_u32 v50, v167, s59
	v_add3_u32 v0, 0, v50, v0
	v_cvt_pk_bf16_f32 v50, v55, v63
	v_cvt_pk_bf16_f32 v51, v68, v80
	v_cvt_pk_bf16_f32 v52, v96, v56
	v_cvt_pk_bf16_f32 v53, v57, v97
	v_cvt_pk_bf16_f32 v54, v100, v58
	v_cvt_pk_bf16_f32 v55, v79, v64
	v_cvt_pk_bf16_f32 v56, v81, v60
	v_cvt_pk_bf16_f32 v57, v67, v69
	v_lshlrev_b32_e32 v73, 16, v46
	ds_write_b128 v0, v[50:53]
	ds_write_b128 v0, v[54:57] offset:16
	v_cvt_pk_bf16_f32 v50, v62, v66
	v_cvt_pk_bf16_f32 v51, v78, v94
	v_cvt_pk_bf16_f32 v52, v106, v95
	v_cvt_pk_bf16_f32 v53, v98, v99
	v_cvt_pk_bf16_f32 v54, v101, v59
	v_cvt_pk_bf16_f32 v55, v82, v65
	v_cvt_pk_bf16_f32 v56, v83, v61
	v_cvt_pk_bf16_f32 v57, v70, v71
	v_lshlrev_b32_e32 v70, 16, v48
	v_and_b32_e32 v69, 0xffff0000, v48
	v_lshlrev_b32_e32 v68, 16, v49
	v_and_b32_e32 v67, 0xffff0000, v49
	v_lshlrev_b32_e32 v66, 16, v42
	v_and_b32_e32 v65, 0xffff0000, v42
	v_lshlrev_b32_e32 v64, 16, v43
	v_and_b32_e32 v63, 0xffff0000, v43
	v_lshlrev_b32_e32 v62, 16, v44
	v_and_b32_e32 v61, 0xffff0000, v44
; __device__ __forceinline__ float gelu_f(float x) { const float y2 = 1.5957691216057308f * x * (1.0f + 0.044715f * x * x); return x * sigmoid_f(y2); }
; __device__ __forceinline__ void unpack8(const u32x4 w, float* f) { f[0] = bf_lo(w.x); f[1] = bf_hi(w.x); f[2] = bf_lo(w.y); f[3] = bf_hi(w.y); f[4] = bf_lo(w.z); f[5] = bf_hi(w.z); f[6] = bf_lo(w.w); f[7] = bf_hi(w.w); }
; __device__ __forceinline__ void p2_block(LAS unsigned char* lds, const bf16_t* __restrict__ PROJ, bf16_t* __restrict__ ATT, bf16_t* __restrict__ SGU, const float* __restrict__ qn, const float* __restrict__ kn, ...
;     ...
;         for (int c4 = 0; c4 < 4; ++c4) unpack8(sv[gi][c4], v + 8 * c4);
;         float sm = 0.f;
; #pragma unroll
;         for (int j = 0; j < 32; ++j) { v[j] = gelu_f(v[j]); sm += v[j]; }
	v_lshlrev_b32_e32 v60, 16, v45
	v_and_b32_e32 v59, 0xffff0000, v45
	v_lshlrev_b32_e32 v49, 16, v40
	v_and_b32_e32 v48, 0xffff0000, v40
	v_lshlrev_b32_e32 v45, 16, v41
	v_and_b32_e32 v44, 0xffff0000, v41
	v_lshlrev_b32_e32 v43, 16, v34
	v_and_b32_e32 v42, 0xffff0000, v34
	v_lshlrev_b32_e32 v41, 16, v35
	v_and_b32_e32 v40, 0xffff0000, v35
	v_lshlrev_b32_e32 v35, 16, v37
	v_and_b32_e32 v34, 0xffff0000, v37
	v_mul_f32_e32 v37, 0x3d372713, v73
	ds_write_b128 v0, v[50:53] offset:64
	ds_write_b128 v0, v[54:57] offset:80
	v_lshlrev_b32_e32 v58, 16, v38
	v_and_b32_e32 v57, 0xffff0000, v38
	v_lshlrev_b32_e32 v56, 16, v39
	v_and_b32_e32 v55, 0xffff0000, v39
	v_lshlrev_b32_e32 v39, 16, v36
	v_and_b32_e32 v38, 0xffff0000, v36
	v_mul_f32_e32 v36, 0x3fcc422a, v73
	v_fma_f32 v37, v37, v73, 1.0
	v_mul_f32_e32 v36, v36, v37
	v_mul_f32_e32 v36, 0xbfb8aa3b, v36
	v_exp_f32_e32 v36, v36
	v_and_b32_e32 v74, 0xffff0000, v46
	v_mul_f32_e32 v37, 0x3d372713, v74
	v_fma_f32 v37, v37, v74, 1.0
	v_add_f32_e32 v36, 1.0, v36
	v_rcp_f32_e32 v75, v36
	v_mul_f32_e32 v36, 0x3fcc422a, v74
	v_mul_f32_e32 v36, v36, v37
	v_mul_f32_e32 v36, 0xbfb8aa3b, v36
	v_exp_f32_e32 v36, v36
	v_lshlrev_b32_e32 v72, 16, v47
	v_mul_f32_e32 v37, 0x3d372713, v72
	v_fma_f32 v37, v37, v72, 1.0
	v_add_f32_e32 v36, 1.0, v36
	v_rcp_f32_e32 v76, v36
	v_mul_f32_e32 v36, 0x3fcc422a, v72
	v_mul_f32_e32 v36, v36, v37
	v_mul_f32_e32 v36, 0xbfb8aa3b, v36
	v_exp_f32_e32 v36, v36
	v_and_b32_e32 v71, 0xffff0000, v47
	v_mul_f32_e32 v37, 0x3d372713, v71
	v_fma_f32 v37, v37, v71, 1.0
	v_add_f32_e32 v36, 1.0, v36
	v_rcp_f32_e32 v77, v36
	v_mul_f32_e32 v36, 0x3fcc422a, v71
	v_mul_f32_e32 v36, v36, v37
	v_mul_f32_e32 v36, 0xbfb8aa3b, v36
	v_exp_f32_e32 v36, v36
	v_mul_f32_e32 v37, 0x3d372713, v70
	v_fma_f32 v37, v37, v70, 1.0
	v_fma_f32 v46, v75, v73, 0
	v_add_f32_e32 v36, 1.0, v36
	v_rcp_f32_e32 v78, v36
	v_mul_f32_e32 v36, 0x3fcc422a, v70
	v_mul_f32_e32 v36, v36, v37
	v_mul_f32_e32 v36, 0xbfb8aa3b, v36
	v_exp_f32_e32 v36, v36
	v_mul_f32_e32 v37, 0x3d372713, v69
	v_fma_f32 v37, v37, v69, 1.0
	v_fmac_f32_e32 v46, v76, v74
	v_add_f32_e32 v36, 1.0, v36
	v_rcp_f32_e32 v79, v36
	v_mul_f32_e32 v36, 0x3fcc422a, v69
	v_mul_f32_e32 v36, v36, v37
	v_mul_f32_e32 v36, 0xbfb8aa3b, v36
	v_exp_f32_e32 v36, v36
	v_mul_f32_e32 v37, 0x3d372713, v68
	v_fma_f32 v37, v37, v68, 1.0
	v_fmac_f32_e32 v46, v77, v72
	v_add_f32_e32 v36, 1.0, v36
	v_rcp_f32_e32 v80, v36
	v_mul_f32_e32 v36, 0x3fcc422a, v68
	v_mul_f32_e32 v36, v36, v37
	v_mul_f32_e32 v36, 0xbfb8aa3b, v36
	v_exp_f32_e32 v36, v36
	v_mul_f32_e32 v37, 0x3d372713, v67
	v_fma_f32 v37, v37, v67, 1.0
	v_fmac_f32_e32 v46, v78, v71
	v_add_f32_e32 v36, 1.0, v36
	v_rcp_f32_e32 v81, v36
	v_mul_f32_e32 v36, 0x3fcc422a, v67
	v_mul_f32_e32 v36, v36, v37
	v_mul_f32_e32 v36, 0xbfb8aa3b, v36
	v_exp_f32_e32 v36, v36
	v_mul_f32_e32 v37, 0x3d372713, v66
	v_fma_f32 v37, v37, v66, 1.0
	v_fmac_f32_e32 v46, v79, v70
	v_add_f32_e32 v36, 1.0, v36
	v_rcp_f32_e32 v82, v36
	v_mul_f32_e32 v36, 0x3fcc422a, v66
	v_mul_f32_e32 v36, v36, v37
	v_mul_f32_e32 v36, 0xbfb8aa3b, v36
	v_exp_f32_e32 v36, v36
	v_mul_f32_e32 v37, 0x3d372713, v65
	v_fma_f32 v37, v37, v65, 1.0
	v_fmac_f32_e32 v46, v80, v69
	v_add_f32_e32 v36, 1.0, v36
	v_rcp_f32_e32 v84, v36
	v_mul_f32_e32 v36, 0x3fcc422a, v65
	v_mul_f32_e32 v36, v36, v37
	v_mul_f32_e32 v36, 0xbfb8aa3b, v36
	v_exp_f32_e32 v36, v36
	v_mul_f32_e32 v37, 0x3d372713, v64
	v_fma_f32 v37, v37, v64, 1.0
	v_fmac_f32_e32 v46, v81, v68
	v_add_f32_e32 v36, 1.0, v36
	v_rcp_f32_e32 v85, v36
	v_mul_f32_e32 v36, 0x3fcc422a, v64
	v_mul_f32_e32 v36, v36, v37
	v_mul_f32_e32 v36, 0xbfb8aa3b, v36
	v_exp_f32_e32 v36, v36
	v_mul_f32_e32 v37, 0x3d372713, v63
	v_fma_f32 v37, v37, v63, 1.0
	v_fmac_f32_e32 v46, v82, v67
	v_add_f32_e32 v36, 1.0, v36
	v_rcp_f32_e32 v86, v36
	v_mul_f32_e32 v36, 0x3fcc422a, v63
	v_mul_f32_e32 v36, v36, v37
	v_mul_f32_e32 v36, 0xbfb8aa3b, v36
	v_exp_f32_e32 v36, v36
	v_mul_f32_e32 v37, 0x3d372713, v62
	v_fma_f32 v37, v37, v62, 1.0
	v_fmac_f32_e32 v46, v84, v66
	v_add_f32_e32 v36, 1.0, v36
	v_rcp_f32_e32 v87, v36
	v_mul_f32_e32 v36, 0x3fcc422a, v62
	v_mul_f32_e32 v36, v36, v37
	v_mul_f32_e32 v36, 0xbfb8aa3b, v36
	v_exp_f32_e32 v36, v36
	v_mul_f32_e32 v37, 0x3d372713, v61
	v_fma_f32 v37, v37, v61, 1.0
	v_fmac_f32_e32 v46, v85, v65
	v_add_f32_e32 v36, 1.0, v36
	v_rcp_f32_e32 v88, v36
	v_mul_f32_e32 v36, 0x3fcc422a, v61
	v_mul_f32_e32 v36, v36, v37
	v_mul_f32_e32 v36, 0xbfb8aa3b, v36
	v_exp_f32_e32 v36, v36
	v_mul_f32_e32 v37, 0x3d372713, v60
	v_fma_f32 v37, v37, v60, 1.0
	v_fmac_f32_e32 v46, v86, v64
	v_add_f32_e32 v36, 1.0, v36
	v_rcp_f32_e32 v89, v36
	v_mul_f32_e32 v36, 0x3fcc422a, v60
	v_mul_f32_e32 v36, v36, v37
	v_mul_f32_e32 v36, 0xbfb8aa3b, v36
	v_exp_f32_e32 v36, v36
	v_mul_f32_e32 v37, 0x3d372713, v59
	v_fma_f32 v37, v37, v59, 1.0
	v_mul_f32_e32 v47, 0x3d372713, v42
	v_add_f32_e32 v36, 1.0, v36
	v_rcp_f32_e32 v90, v36
	v_mul_f32_e32 v36, 0x3fcc422a, v59
	v_mul_f32_e32 v36, v36, v37
	v_mul_f32_e32 v36, 0xbfb8aa3b, v36
	v_exp_f32_e32 v36, v36
	v_mul_f32_e32 v37, 0x3d372713, v58
	v_fma_f32 v37, v37, v58, 1.0
	v_fmac_f32_e32 v46, v87, v63
	v_add_f32_e32 v36, 1.0, v36
	v_rcp_f32_e32 v91, v36
	v_mul_f32_e32 v36, 0x3fcc422a, v58
	v_mul_f32_e32 v36, v36, v37
	v_mul_f32_e32 v36, 0xbfb8aa3b, v36
	v_exp_f32_e32 v36, v36
	v_mul_f32_e32 v37, 0x3d372713, v57
	v_fma_f32 v37, v37, v57, 1.0
	v_fma_f32 v47, v47, v42, 1.0
	v_add_f32_e32 v36, 1.0, v36
	v_rcp_f32_e32 v98, v36
	v_mul_f32_e32 v36, 0x3fcc422a, v57
	v_mul_f32_e32 v36, v36, v37
	v_mul_f32_e32 v36, 0xbfb8aa3b, v36
	v_exp_f32_e32 v36, v36
	v_mul_f32_e32 v37, 0x3d372713, v56
	v_fma_f32 v37, v37, v56, 1.0
	v_fmac_f32_e32 v46, v88, v62
; __device__ __forceinline__ float gelu_f(float x) { const float y2 = 1.5957691216057308f * x * (1.0f + 0.044715f * x * x); return x * sigmoid_f(y2); }
; #define LAS __attribute__((address_space(3)))
; __device__ __forceinline__ void unpack8(const u32x4 w, float* f) { f[0] = bf_lo(w.x); f[1] = bf_hi(w.x); f[2] = bf_lo(w.y); f[3] = bf_hi(w.y); f[4] = bf_lo(w.z); f[5] = bf_hi(w.z); f[6] = bf_lo(w.w); f[7] = bf_hi(w.w); }
; __device__ __forceinline__ void p2_block(LAS unsigned char* lds, const bf16_t* __restrict__ PROJ, bf16_t* __restrict__ ATT, bf16_t* __restrict__ SGU, const float* __restrict__ qn, const float* __restrict__ kn, ...
;     ...
;         for (int c4 = 0; c4 < 4; ++c4) { u32x4 t = vv[c4]; if (s < 0) t = (u32x4){0u, 0u, 0u, 0u};
;             LAS unsigned char* vd = VT + (32 * h + 8 * c4) * VT_STRIDE + kk * 2;
;             *(LAS unsigned short*)(vd + 0 * VT_STRIDE) = (unsigned short)(t.x & 0xffffu); *(LAS unsigned short*)(vd + 1 * VT_STRIDE) = (unsigned short)(t.x >> 16);
;             *(LAS unsigned short*)(vd + 2 * VT_STRIDE) = (unsigned short)(t.y & 0xffffu); *(LAS unsigned short*)(vd + 3 * VT_STRIDE) = (unsigned short)(t.y >> 16);
;             *(LAS unsigned short*)(vd + 4 * VT_STRIDE) = (unsigned short)(t.z & 0xffffu); *(LAS unsigned short*)(vd + 5 * VT_STRIDE) = (unsigned short)(t.z >> 16);
;             *(LAS unsigned short*)(vd + 6 * VT_STRIDE) = (unsigned short)(t.w & 0xffffu); *(LAS unsigned short*)(vd + 7 * VT_STRIDE) = (unsigned short)(t.w >> 16); }
;     }
; #pragma unroll
;     for (int gi = 0; gi < 2; ++gi) {
;         const int gg = 2 * kvh + gi;
;         if (gi == 0) {
; #pragma unroll
;             for (int c4 = 0; c4 < 4; ++c4) sv[1][c4] = *(const u32x4*)(svsrc + 128 + 8 * c4); }
;         float v[32];
; #pragma unroll
;         for (int c4 = 0; c4 < 4; ++c4) unpack8(sv[gi][c4], v + 8 * c4);
;         float sm = 0.f;
; #pragma unroll
;         for (int j = 0; j < 32; ++j) { v[j] = gelu_f(v[j]); sm += v[j]; }
;         sm += __shfl_xor(sm, 1); sm += __shfl_xor(sm, 2);
	v_add_f32_e32 v36, 1.0, v36
	v_rcp_f32_e32 v99, v36
	v_mul_f32_e32 v36, 0x3fcc422a, v56
	v_mul_f32_e32 v36, v36, v37
	v_mul_f32_e32 v36, 0xbfb8aa3b, v36
	v_exp_f32_e32 v36, v36
	v_mul_f32_e32 v37, 0x3d372713, v55
	v_fma_f32 v37, v37, v55, 1.0
	v_fmac_f32_e32 v46, v89, v61
	v_add_f32_e32 v36, 1.0, v36
	v_rcp_f32_e32 v100, v36
	v_mul_f32_e32 v36, 0x3fcc422a, v55
	v_mul_f32_e32 v36, v36, v37
	v_mul_f32_e32 v36, 0xbfb8aa3b, v36
	v_exp_f32_e32 v36, v36
	v_mul_f32_e32 v37, 0x3d372713, v49
	v_fma_f32 v37, v37, v49, 1.0
	v_fmac_f32_e32 v46, v90, v60
	v_add_f32_e32 v36, 1.0, v36
	v_rcp_f32_e32 v101, v36
	v_mul_f32_e32 v36, 0x3fcc422a, v49
	v_mul_f32_e32 v36, v36, v37
	v_mul_f32_e32 v36, 0xbfb8aa3b, v36
	v_exp_f32_e32 v36, v36
	v_mul_f32_e32 v37, 0x3d372713, v48
	v_fma_f32 v37, v37, v48, 1.0
	v_fmac_f32_e32 v46, v91, v59
	v_add_f32_e32 v36, 1.0, v36
	v_rcp_f32_e32 v102, v36
	v_mul_f32_e32 v36, 0x3fcc422a, v48
	v_mul_f32_e32 v36, v36, v37
	v_mul_f32_e32 v36, 0xbfb8aa3b, v36
	v_exp_f32_e32 v36, v36
	v_mul_f32_e32 v37, 0x3d372713, v45
	v_fma_f32 v37, v37, v45, 1.0
	v_fmac_f32_e32 v46, v98, v58
	v_add_f32_e32 v36, 1.0, v36
	v_rcp_f32_e32 v103, v36
	v_mul_f32_e32 v36, 0x3fcc422a, v45
	v_mul_f32_e32 v36, v36, v37
	v_mul_f32_e32 v36, 0xbfb8aa3b, v36
	v_exp_f32_e32 v36, v36
	v_mul_f32_e32 v37, 0x3d372713, v44
	v_fma_f32 v37, v37, v44, 1.0
	v_fmac_f32_e32 v46, v99, v57
	v_add_f32_e32 v36, 1.0, v36
	v_rcp_f32_e32 v104, v36
	v_mul_f32_e32 v36, 0x3fcc422a, v44
	v_mul_f32_e32 v36, v36, v37
	v_mul_f32_e32 v36, 0xbfb8aa3b, v36
	v_exp_f32_e32 v36, v36
	v_mul_f32_e32 v37, 0x3d372713, v43
	v_fma_f32 v37, v37, v43, 1.0
	v_fmac_f32_e32 v46, v100, v56
	v_add_f32_e32 v36, 1.0, v36
	v_rcp_f32_e32 v105, v36
	v_mul_f32_e32 v36, 0x3fcc422a, v43
	v_mul_f32_e32 v36, v36, v37
	v_mul_f32_e32 v36, 0xbfb8aa3b, v36
	v_exp_f32_e32 v36, v36
	v_fmac_f32_e32 v46, v101, v55
	v_fmac_f32_e32 v46, v102, v49
	v_fmac_f32_e32 v46, v103, v48
	v_add_f32_e32 v36, 1.0, v36
	v_rcp_f32_e32 v37, v36
	v_mul_f32_e32 v36, 0x3fcc422a, v42
	v_mul_f32_e32 v36, v36, v47
	v_mul_f32_e32 v36, 0xbfb8aa3b, v36
	v_exp_f32_e32 v36, v36
	v_fmac_f32_e32 v46, v104, v45
	v_fmac_f32_e32 v46, v105, v44
	v_mul_f32_e32 v47, 0x3d372713, v41
	v_add_f32_e32 v36, 1.0, v36
	v_rcp_f32_e32 v36, v36
	v_fma_f32 v47, v47, v41, 1.0
	v_mul_f32_e32 v94, 0x3d372713, v38
	v_fma_f32 v94, v94, v38, 1.0
	v_pk_mul_f32 v[92:93], v[36:37], v[42:43]
	v_mul_f32_e32 v96, 0x3d372713, v34
	v_add_f32_e32 v46, v93, v46
	v_add_f32_e32 v83, v92, v46
	v_mul_f32_e32 v46, 0x3fcc422a, v41
	v_mul_f32_e32 v46, v46, v47
	v_mul_f32_e32 v46, 0xbfb8aa3b, v46
	v_exp_f32_e32 v46, v46
	v_mul_f32_e32 v92, 0x3d372713, v40
	v_fma_f32 v92, v92, v40, 1.0
	v_fma_f32 v96, v96, v34, 1.0
	v_add_f32_e32 v46, 1.0, v46
	v_rcp_f32_e32 v47, v46
	v_mul_f32_e32 v46, 0x3fcc422a, v40
	v_mul_f32_e32 v46, v46, v92
	v_mul_f32_e32 v46, 0xbfb8aa3b, v46
	v_exp_f32_e32 v46, v46
	v_and_b32_e32 v0, -2, v160
	v_mul_u32_u24_e32 v50, 0x4200, v166
	v_cndmask_b32_e64 v18, v18, 0, vcc
	v_add_f32_e32 v46, 1.0, v46
	v_rcp_f32_e32 v46, v46
	v_add3_u32 v0, 0, v0, v50
	v_cndmask_b32_e64 v14, v14, 0, vcc
	v_cndmask_b32_e64 v10, v10, 0, vcc
	v_pk_mul_f32 v[92:93], v[46:47], v[40:41]
	v_cndmask_b32_e64 v6, v6, 0, vcc
	v_add_f32_e32 v83, v93, v83
	v_mul_f32_e32 v93, 0x3d372713, v39
	v_add_f32_e32 v83, v92, v83
	v_mul_f32_e32 v92, 0x3fcc422a, v39
	v_fma_f32 v93, v93, v39, 1.0
	v_mul_f32_e32 v92, v92, v93
	v_mul_f32_e32 v92, 0xbfb8aa3b, v92
	v_exp_f32_e32 v92, v92
	v_cndmask_b32_e64 v21, v21, 0, vcc
	v_cndmask_b32_e64 v20, v20, 0, vcc
	v_cndmask_b32_e64 v19, v19, 0, vcc
	v_add_f32_e32 v92, 1.0, v92
	v_rcp_f32_e32 v93, v92
	v_mul_f32_e32 v92, 0x3fcc422a, v38
	v_mul_f32_e32 v92, v92, v94
	v_mul_f32_e32 v92, 0xbfb8aa3b, v92
	v_exp_f32_e32 v92, v92
	ds_write_b16 v0, v18 offset:36864
	ds_write_b16_d16_hi v0, v18 offset:37392
	ds_write_b16 v0, v19 offset:37920
	ds_write_b16_d16_hi v0, v19 offset:38448
	ds_write_b16 v0, v20 offset:38976
	ds_write_b16_d16_hi v0, v20 offset:39504
	ds_write_b16 v0, v21 offset:40032
	ds_write_b16_d16_hi v0, v21 offset:40560
	v_cndmask_b32_e64 v17, v17, 0, vcc
	v_cndmask_b32_e64 v16, v16, 0, vcc
	v_add_f32_e32 v92, 1.0, v92
	v_rcp_f32_e32 v92, v92
	v_cndmask_b32_e64 v15, v15, 0, vcc
	ds_write_b16 v0, v14 offset:41088
	ds_write_b16_d16_hi v0, v14 offset:41616
	ds_write_b16 v0, v15 offset:42144
	ds_write_b16_d16_hi v0, v15 offset:42672
	ds_write_b16 v0, v16 offset:43200
	ds_write_b16_d16_hi v0, v16 offset:43728
	ds_write_b16 v0, v17 offset:44256
	ds_write_b16_d16_hi v0, v17 offset:44784
	v_cndmask_b32_e64 v13, v13, 0, vcc
	v_pk_mul_f32 v[94:95], v[92:93], v[38:39]
	v_cndmask_b32_e64 v12, v12, 0, vcc
	v_add_f32_e32 v83, v95, v83
	v_mul_f32_e32 v95, 0x3d372713, v35
	v_add_f32_e32 v83, v94, v83
	v_mul_f32_e32 v94, 0x3fcc422a, v35
	v_fma_f32 v95, v95, v35, 1.0
	v_mul_f32_e32 v94, v94, v95
	v_mul_f32_e32 v94, 0xbfb8aa3b, v94
	v_exp_f32_e32 v94, v94
	v_cndmask_b32_e64 v11, v11, 0, vcc
	ds_write_b16 v0, v10 offset:45312
	ds_write_b16_d16_hi v0, v10 offset:45840
	ds_write_b16 v0, v11 offset:46368
	ds_write_b16_d16_hi v0, v11 offset:46896
	ds_write_b16 v0, v12 offset:47424
	ds_write_b16_d16_hi v0, v12 offset:47952
	ds_write_b16 v0, v13 offset:48480
	ds_write_b16_d16_hi v0, v13 offset:49008
	v_cndmask_b32_e64 v9, v9, 0, vcc
	v_add_f32_e32 v94, 1.0, v94
	v_rcp_f32_e32 v95, v94
	v_mul_f32_e32 v94, 0x3fcc422a, v34
	v_mul_f32_e32 v94, v94, v96
	v_mul_f32_e32 v94, 0xbfb8aa3b, v94
	v_exp_f32_e32 v94, v94
	v_cndmask_b32_e64 v8, v8, 0, vcc
	v_cndmask_b32_e64 v7, v7, 0, vcc
	ds_write_b16 v0, v6 offset:49536
	ds_write_b16_d16_hi v0, v6 offset:50064
	ds_write_b16 v0, v7 offset:50592
	ds_write_b16_d16_hi v0, v7 offset:51120
	ds_write_b16 v0, v8 offset:51648
	ds_write_b16_d16_hi v0, v8 offset:52176
	ds_write_b16 v0, v9 offset:52704
	ds_write_b16_d16_hi v0, v9 offset:53232
	v_add_f32_e32 v94, 1.0, v94
	v_rcp_f32_e32 v94, v94
	v_xor_b32_e32 v0, 2, v211
	v_cmp_lt_i32_e32 vcc, v0, v133
	v_lshlrev_b32_e32 v6, 1, v136
	v_pk_mul_f32 v[96:97], v[94:95], v[34:35]
	v_cndmask_b32_e32 v0, v211, v0, vcc
	v_add_f32_e32 v83, v97, v83
	v_add_f32_e32 v83, v96, v83
	ds_bpermute_b32 v96, v164, v83
	v_lshlrev_b32_e32 v54, 2, v0
	v_lshlrev_b32_e32 v0, 2, v165
	v_lshl_add_u64 v[50:51], s[36:37], 0, v[0:1]
	v_lshl_add_u64 v[52:53], s[18:19], 0, v[0:1]
	s_waitcnt lgkmcnt(0)
; __device__ __forceinline__ unsigned cvt_pk_bf16(float lo, float hi) { unsigned r; asm volatile("v_cvt_pk_bf16_f32 %0, %1, %2" : "=v"(r) : "v"(lo), "v"(hi)); return r; }
; #define LAS __attribute__((address_space(3)))
; __device__ __forceinline__ void p2_block(LAS unsigned char* lds, const bf16_t* __restrict__ PROJ, bf16_t* __restrict__ ATT, bf16_t* __restrict__ SGU, const float* __restrict__ qn, const float* __restrict__ kn, ...
;     ...
;         const float mu = sm * (1.0f / 128.0f); float q = 0.f;
; #pragma unroll
;         for (int j = 0; j < 32; ++j) { v[j] -= mu; q += v[j] * v[j]; }
;         q += __shfl_xor(q, 1); q += __shfl_xor(q, 2);
;         const float rstd = rsqrtf(q * (1.0f / 128.0f) + pg8::EPS);
;         const float* gp = lng + gg * 128 + 32 * q4; const float* bp = lnb + gg * 128 + 32 * q4;
;         LAS unsigned char* dst = lds + (gi ? VN_OFF1 : VN_OFF0) + (32 * q4) * VN_STRIDE + sp_ * 2;
; #pragma unroll
;         for (int j = 0; j < 32; j += 2) { const unsigned pk = cvt_pk_bf16(v[j] * rstd * gp[j] + bp[j], v[j + 1] * rstd * gp[j + 1] + bp[j + 1]);
;             *(LAS unsigned short*)(dst + j * VN_STRIDE) = (unsigned short)(pk & 0xffffu); *(LAS unsigned short*)(dst + (j + 1) * VN_STRIDE) = (unsigned short)(pk >> 16); }
	v_add_f32_e32 v83, v83, v96
	ds_bpermute_b32 v96, v54, v83
	v_mul_u32_u24_e32 v0, 0x110, v165
	v_add3_u32 v0, 0, v0, v6
	global_load_dwordx4 v[6:9], v[138:139], off offset:304
	global_load_dwordx4 v[10:13], v[138:139], off offset:288
	global_load_dwordx4 v[14:17], v[138:139], off offset:272
	global_load_dwordx4 v[18:21], v[138:139], off offset:256
	s_ashr_i32 s43, s42, 31
	s_waitcnt lgkmcnt(0)
	v_add_f32_e32 v83, v83, v96
	v_mul_f32_e32 v96, 0x3c000000, v83
	v_fma_f32 v83, v76, v74, -v96
	v_fma_f32 v97, v75, v73, -v96
	v_mul_f32_e32 v106, v83, v83
	v_fmac_f32_e32 v106, v97, v97
	v_fma_f32 v77, v77, v72, -v96
	v_fmac_f32_e32 v106, v77, v77
	v_fma_f32 v76, v78, v71, -v96
	v_fmac_f32_e32 v106, v76, v76
	v_fma_f32 v75, v79, v70, -v96
	v_fmac_f32_e32 v106, v75, v75
	v_fma_f32 v74, v80, v69, -v96
	v_fmac_f32_e32 v106, v74, v74
	v_fma_f32 v73, v81, v68, -v96
	v_fmac_f32_e32 v106, v73, v73
	v_fma_f32 v72, v82, v67, -v96
	v_fmac_f32_e32 v106, v72, v72
	v_fma_f32 v71, v84, v66, -v96
	v_fmac_f32_e32 v106, v71, v71
	v_fma_f32 v70, v85, v65, -v96
	v_fmac_f32_e32 v106, v70, v70
	v_fma_f32 v69, v86, v64, -v96
	v_fmac_f32_e32 v106, v69, v69
	v_fma_f32 v68, v87, v63, -v96
	v_fmac_f32_e32 v106, v68, v68
	v_fma_f32 v67, v88, v62, -v96
	v_fmac_f32_e32 v106, v67, v67
	v_fma_f32 v66, v89, v61, -v96
	v_fmac_f32_e32 v106, v66, v66
	v_fma_f32 v65, v90, v60, -v96
	v_fmac_f32_e32 v106, v65, v65
	v_fma_f32 v64, v91, v59, -v96
	v_fmac_f32_e32 v106, v64, v64
	v_fma_f32 v63, v98, v58, -v96
	v_fmac_f32_e32 v106, v63, v63
	v_fma_f32 v62, v99, v57, -v96
	v_fmac_f32_e32 v106, v62, v62
	v_fma_f32 v61, v100, v56, -v96
	v_fmac_f32_e32 v106, v61, v61
	v_fma_f32 v60, v101, v55, -v96
	v_fmac_f32_e32 v106, v60, v60
	v_fma_f32 v59, v102, v49, -v96
	v_fmac_f32_e32 v106, v59, v59
	v_fma_f32 v58, v103, v48, -v96
	v_fmac_f32_e32 v106, v58, v58
	v_fma_f32 v57, v104, v45, -v96
	v_fmac_f32_e32 v106, v57, v57
	v_fma_f32 v56, v105, v44, -v96
	v_pk_fma_f32 v[44:45], v[36:37], v[42:43], v[96:97] op_sel_hi:[1,1,0] neg_lo:[0,0,1] neg_hi:[0,0,1]
	v_fmac_f32_e32 v106, v56, v56
	v_pk_mul_f32 v[36:37], v[44:45], v[44:45]
	v_pk_fma_f32 v[42:43], v[46:47], v[40:41], v[96:97] op_sel_hi:[1,1,0] neg_lo:[0,0,1] neg_hi:[0,0,1]
	v_add_f32_e32 v37, v37, v106
	v_add_f32_e32 v48, v36, v37
	v_pk_mul_f32 v[36:37], v[42:43], v[42:43]
	v_pk_fma_f32 v[40:41], v[92:93], v[38:39], v[96:97] op_sel_hi:[1,1,0] neg_lo:[0,0,1] neg_hi:[0,0,1]
	v_add_f32_e32 v37, v37, v48
	v_add_f32_e32 v46, v36, v37
	v_pk_mul_f32 v[36:37], v[40:41], v[40:41]
	v_pk_fma_f32 v[38:39], v[94:95], v[34:35], v[96:97] op_sel_hi:[1,1,0] neg_lo:[0,0,1] neg_hi:[0,0,1]
	v_add_f32_e32 v37, v37, v46
	v_add_f32_e32 v36, v36, v37
	v_pk_mul_f32 v[34:35], v[38:39], v[38:39]
	v_lshlrev_b32_e32 v105, 16, v3
	v_add_f32_e32 v35, v35, v36
	v_add_f32_e32 v34, v34, v35
	ds_bpermute_b32 v35, v164, v34
	v_lshl_add_u64 v[36:37], v[52:53], 0, s[4:5]
	v_and_b32_e32 v109, 0xffff0000, v3
	v_lshlrev_b32_e32 v113, 16, v2
	v_lshlrev_b32_e32 v112, 16, v30
	s_waitcnt lgkmcnt(0)
	v_add_f32_e32 v34, v34, v35
	ds_bpermute_b32 v35, v54, v34
	v_and_b32_e32 v3, 0xffff0000, v2
	v_and_b32_e32 v2, 0xffff0000, v30
	v_and_b32_e32 v96, 0xffff0000, v33
	s_waitcnt vmcnt(1)
	v_lshlrev_b32_e32 v53, 16, v14
	s_waitcnt lgkmcnt(0)
	v_add_f32_e32 v34, v34, v35
	v_fmamk_f32 v34, v34, 0x3c000000, v209
	v_cmp_gt_f32_e32 vcc, s82, v34
	v_mul_f32_e32 v35, 0x4b800000, v34
	v_and_b32_e32 v52, 0xffff0000, v14
	v_cndmask_b32_e32 v34, v34, v35, vcc
	v_rsq_f32_e32 v34, v34
	v_and_b32_e32 v14, 0xffff0000, v6
	v_lshlrev_b32_e32 v104, 16, v31
	v_and_b32_e32 v108, 0xffff0000, v31
	v_mul_f32_e32 v35, 0x45800000, v34
	v_cndmask_b32_e32 v55, v34, v35, vcc
	v_lshl_add_u64 v[34:35], v[50:51], 0, s[4:5]
	v_mov_b64_e32 v[46:47], v[144:145]
	v_mov_b64_e32 v[48:49], v[218:219]
	v_mul_f32_e32 v51, v97, v55
	v_add_u32_e32 v50, 0x11800, v0
	v_mul_f32_e32 v45, v45, v55
	v_mul_f32_e32 v44, v44, v55
	v_mul_f32_e32 v43, v43, v55
	v_mul_f32_e32 v42, v42, v55
	v_mul_f32_e32 v41, v41, v55
	v_mul_f32_e32 v40, v40, v55
	v_mul_f32_e32 v39, v39, v55
	v_mul_f32_e32 v38, v38, v55
	v_mov_b32_e32 v116, v112
	v_mov_b32_e32 v117, v2
	v_and_b32_e32 v97, 0xffff0000, v5
	v_mov_b32_e32 v110, v108
	v_mov_b32_e32 v111, v104
	v_mov_b32_e32 v30, v113
	v_mov_b32_e32 v31, v3
	v_pk_mul_f32 v[116:117], v[116:117], v[116:117]
	v_lshlrev_b32_e32 v101, 16, v4
	v_lshlrev_b32_e32 v100, 16, v32
	v_pk_mul_f32 v[110:111], v[110:111], v[110:111]
	v_pk_fma_f32 v[30:31], v[30:31], v[30:31], v[116:117]
	v_lshlrev_b32_e32 v130, 3, v162
	v_mov_b32_e32 v131, v1
	s_mov_b32 s4, s5
	s_mov_b32 s52, 0xf149f2ca
	s_waitcnt vmcnt(0)
	v_fma_f32 v46, v46, v51, v48
	v_mul_f32_e32 v48, v83, v55
	v_fmac_f32_e32 v49, v47, v48
	v_add_u32_e32 v47, 0x11910, v0
	v_cvt_pk_bf16_f32 v46, v46, v49
	ds_write_b16 v50, v46
	ds_write_b16_d16_hi v47, v46
	v_mov_b64_e32 v[46:47], v[146:147]
	v_mov_b64_e32 v[48:49], v[220:221]
	v_mul_f32_e32 v50, v77, v55
	v_lshlrev_b32_e32 v51, 16, v15
	s_waitcnt vmcnt(0)
	v_fma_f32 v46, v46, v50, v48
	v_mul_f32_e32 v48, v76, v55
	v_fmac_f32_e32 v49, v47, v48
	v_add_u32_e32 v47, 0x11a20, v0
	v_cvt_pk_bf16_f32 v46, v46, v49
	ds_write_b16 v47, v46
	v_add_u32_e32 v47, 0x11b30, v0
	ds_write_b16_d16_hi v47, v46
	v_mov_b64_e32 v[46:47], v[148:149]
	v_mov_b64_e32 v[48:49], v[222:223]
	v_mul_f32_e32 v50, v75, v55
	s_waitcnt vmcnt(0)
	v_fma_f32 v46, v46, v50, v48
	v_mul_f32_e32 v48, v74, v55
	v_fmac_f32_e32 v49, v47, v48
	v_add_u32_e32 v47, 0x11c40, v0
	v_cvt_pk_bf16_f32 v46, v46, v49
	ds_write_b16 v47, v46
	v_add_u32_e32 v47, 0x11d50, v0
	ds_write_b16_d16_hi v47, v46
	v_mov_b64_e32 v[46:47], v[150:151]
	v_mov_b64_e32 v[48:49], v[224:225]
	v_mul_f32_e32 v50, v73, v55
	s_waitcnt vmcnt(0)
; __device__ __forceinline__ unsigned cvt_pk_bf16(float lo, float hi) { unsigned r; asm volatile("v_cvt_pk_bf16_f32 %0, %1, %2" : "=v"(r) : "v"(lo), "v"(hi)); return r; }
; #define LAS __attribute__((address_space(3)))
; __device__ __forceinline__ void p2_block(LAS unsigned char* lds, const bf16_t* __restrict__ PROJ, bf16_t* __restrict__ ATT, bf16_t* __restrict__ SGU, const float* __restrict__ qn, const float* __restrict__ kn, ...
;     ...
;         for (int j = 0; j < 32; j += 2) { const unsigned pk = cvt_pk_bf16(v[j] * rstd * gp[j] + bp[j], v[j + 1] * rstd * gp[j + 1] + bp[j + 1]);
;             *(LAS unsigned short*)(dst + j * VN_STRIDE) = (unsigned short)(pk & 0xffffu); *(LAS unsigned short*)(dst + (j + 1) * VN_STRIDE) = (unsigned short)(pk >> 16); }
	v_fma_f32 v46, v46, v50, v48
	v_mul_f32_e32 v48, v72, v55
	v_fmac_f32_e32 v49, v47, v48
	v_add_u32_e32 v47, 0x11e60, v0
	v_cvt_pk_bf16_f32 v46, v46, v49
	ds_write_b16 v47, v46
	v_add_u32_e32 v47, 0x11f70, v0
	ds_write_b16_d16_hi v47, v46
	v_mov_b64_e32 v[46:47], v[152:153]
	v_mov_b64_e32 v[48:49], v[226:227]
	v_mul_f32_e32 v50, v71, v55
	s_waitcnt vmcnt(0)
	v_fma_f32 v46, v46, v50, v48
	v_mul_f32_e32 v48, v70, v55
	v_fmac_f32_e32 v49, v47, v48
	v_add_u32_e32 v47, 0x12080, v0
	v_cvt_pk_bf16_f32 v46, v46, v49
	ds_write_b16 v47, v46
	v_add_u32_e32 v47, 0x12190, v0
	ds_write_b16_d16_hi v47, v46
	v_mov_b64_e32 v[46:47], v[154:155]
	v_mov_b64_e32 v[48:49], v[228:229]
	v_mul_f32_e32 v50, v69, v55
	s_waitcnt vmcnt(0)
	v_fma_f32 v46, v46, v50, v48
	v_mul_f32_e32 v48, v68, v55
	v_fmac_f32_e32 v49, v47, v48
	v_add_u32_e32 v47, 0x122a0, v0
	v_cvt_pk_bf16_f32 v46, v46, v49
	ds_write_b16 v47, v46
	v_add_u32_e32 v47, 0x123b0, v0
	ds_write_b16_d16_hi v47, v46
	v_mov_b64_e32 v[46:47], v[156:157]
	v_mov_b64_e32 v[48:49], v[230:231]
	v_mul_f32_e32 v50, v67, v55
	s_waitcnt vmcnt(0)
	v_fma_f32 v46, v46, v50, v48
	v_mul_f32_e32 v48, v66, v55
	v_fmac_f32_e32 v49, v48, v47
	v_add_u32_e32 v47, 0x124c0, v0
	v_cvt_pk_bf16_f32 v46, v46, v49
	ds_write_b16 v47, v46
	v_add_u32_e32 v47, 0x125d0, v0
	ds_write_b16_d16_hi v47, v46
	v_mov_b64_e32 v[46:47], v[158:159]
	v_mov_b64_e32 v[48:49], v[232:233]
	v_mul_f32_e32 v50, v65, v55
	s_waitcnt vmcnt(0)
	v_fma_f32 v46, v50, v46, v48
	v_mul_f32_e32 v48, v64, v55
	v_fmac_f32_e32 v49, v48, v47
	v_add_u32_e32 v47, 0x126e0, v0
	v_cvt_pk_bf16_f32 v46, v46, v49
	ds_write_b16 v47, v46
	v_add_u32_e32 v47, 0x127f0, v0
	ds_write_b16_d16_hi v47, v46
	v_mov_b64_e32 v[46:47], v[184:185]
	v_mov_b64_e32 v[48:49], v[234:235]
	v_mul_f32_e32 v50, v63, v55
	s_waitcnt vmcnt(0)
	v_fma_f32 v46, v50, v46, v48
	v_mul_f32_e32 v48, v62, v55
	v_fmac_f32_e32 v49, v48, v47
	v_add_u32_e32 v47, 0x12900, v0
	v_cvt_pk_bf16_f32 v46, v46, v49
	ds_write_b16 v47, v46
	v_add_u32_e32 v47, 0x12a10, v0
	ds_write_b16_d16_hi v47, v46
	v_mov_b64_e32 v[46:47], v[186:187]
	v_mov_b64_e32 v[48:49], v[236:237]
	v_mul_f32_e32 v50, v61, v55
	v_lshlrev_b32_e32 v61, 16, v18
	v_and_b32_e32 v62, 0xffff0000, v18
	s_waitcnt vmcnt(0)
	v_fma_f32 v46, v50, v46, v48
	v_mul_f32_e32 v48, v60, v55
	v_fmac_f32_e32 v49, v48, v47
	v_add_u32_e32 v47, 0x12b20, v0
	v_cvt_pk_bf16_f32 v46, v46, v49
	ds_write_b16 v47, v46
	v_add_u32_e32 v47, 0x12c30, v0
	ds_write_b16_d16_hi v47, v46
	v_mov_b64_e32 v[46:47], v[188:189]
	v_mov_b64_e32 v[48:49], v[238:239]
	v_mul_f32_e32 v50, v59, v55
	v_lshlrev_b32_e32 v60, 16, v19
	v_and_b32_e32 v59, 0xffff0000, v19
	s_waitcnt vmcnt(0)
	v_fma_f32 v46, v50, v46, v48
	v_mul_f32_e32 v48, v58, v55
	v_fmac_f32_e32 v49, v48, v47
	v_add_u32_e32 v47, 0x12d40, v0
	v_cvt_pk_bf16_f32 v46, v46, v49
	ds_write_b16 v47, v46
	v_add_u32_e32 v47, 0x12e50, v0
	ds_write_b16_d16_hi v47, v46
	v_mov_b64_e32 v[46:47], v[190:191]
	v_mov_b64_e32 v[48:49], v[240:241]
	v_mul_f32_e32 v50, v57, v55
	v_lshlrev_b32_e32 v58, 16, v20
	v_and_b32_e32 v57, 0xffff0000, v20
	s_waitcnt vmcnt(0)
	v_fma_f32 v46, v50, v46, v48
	v_mul_f32_e32 v48, v56, v55
	v_fmac_f32_e32 v49, v48, v47
	v_add_u32_e32 v47, 0x12f60, v0
	v_cvt_pk_bf16_f32 v46, v46, v49
	ds_write_b16 v47, v46
	v_add_u32_e32 v47, 0x13070, v0
	ds_write_b16_d16_hi v47, v46
	v_mov_b64_e32 v[46:47], v[192:193]
	v_mov_b64_e32 v[48:49], v[242:243]
	v_and_b32_e32 v50, 0xffff0000, v15
	v_lshlrev_b32_e32 v15, 16, v6
	v_and_b32_e32 v6, 0xffff0000, v9
	v_lshlrev_b32_e32 v56, 16, v21
	v_and_b32_e32 v55, 0xffff0000, v21
	v_mul_f32_e32 v88, 0x3d372713, v6
	v_fma_f32 v88, v88, v6, 1.0
	s_waitcnt vmcnt(0)
	v_fma_f32 v45, v45, v46, v48
	v_fmac_f32_e32 v49, v44, v47
	v_cvt_pk_bf16_f32 v44, v45, v49
	v_add_u32_e32 v45, 0x13180, v0
	ds_write_b16 v45, v44
	v_add_u32_e32 v45, 0x13290, v0
	ds_write_b16_d16_hi v45, v44
	v_mov_b64_e32 v[44:45], v[194:195]
	v_mov_b64_e32 v[46:47], v[244:245]
	v_lshlrev_b32_e32 v49, 16, v16
	v_and_b32_e32 v48, 0xffff0000, v16
	s_waitcnt vmcnt(0)
	v_fma_f32 v43, v43, v44, v46
	v_fmac_f32_e32 v47, v42, v45
	v_cvt_pk_bf16_f32 v42, v43, v47
	v_add_u32_e32 v43, 0x133a0, v0
	ds_write_b16 v43, v42
	v_add_u32_e32 v43, 0x134b0, v0
	ds_write_b16_d16_hi v43, v42
	v_mov_b64_e32 v[42:43], v[196:197]
	v_mov_b64_e32 v[44:45], v[200:201]
	v_lshlrev_b32_e32 v47, 16, v17
	v_and_b32_e32 v46, 0xffff0000, v17
	v_mul_f32_e32 v17, 0x3d372713, v14
	v_fma_f32 v17, v17, v14, 1.0
	s_waitcnt vmcnt(0)
	v_fma_f32 v41, v41, v42, v44
	v_fmac_f32_e32 v45, v40, v43
	v_cvt_pk_bf16_f32 v40, v41, v45
	v_add_u32_e32 v41, 0x135c0, v0
	ds_write_b16 v41, v40
	v_add_u32_e32 v41, 0x136d0, v0
	ds_write_b16_d16_hi v41, v40
	v_mov_b64_e32 v[40:41], v[198:199]
	v_mov_b64_e32 v[42:43], v[202:203]
	v_lshlrev_b32_e32 v45, 16, v10
	v_and_b32_e32 v44, 0xffff0000, v10
	v_and_b32_e32 v10, 0xffff0000, v8
	s_waitcnt vmcnt(0)
; __device__ __forceinline__ unsigned cvt_pk_bf16(float lo, float hi) { unsigned r; asm volatile("v_cvt_pk_bf16_f32 %0, %1, %2" : "=v"(r) : "v"(lo), "v"(hi)); return r; }
; __device__ __forceinline__ float gelu_f(float x) { const float y2 = 1.5957691216057308f * x * (1.0f + 0.044715f * x * x); return x * sigmoid_f(y2); }
; #define LAS __attribute__((address_space(3)))
; __device__ __forceinline__ void unpack8(const u32x4 w, float* f) { f[0] = bf_lo(w.x); f[1] = bf_hi(w.x); f[2] = bf_lo(w.y); f[3] = bf_hi(w.y); f[4] = bf_lo(w.z); f[5] = bf_hi(w.z); f[6] = bf_lo(w.w); f[7] = bf_hi(w.w); }
; __device__ __forceinline__ void p2_block(LAS unsigned char* lds, const bf16_t* __restrict__ PROJ, bf16_t* __restrict__ ATT, bf16_t* __restrict__ SGU, const float* __restrict__ qn, const float* __restrict__ kn, ...
;     ...
;         for (int c4 = 0; c4 < 4; ++c4) unpack8(sv[gi][c4], v + 8 * c4);
;         float sm = 0.f;
; #pragma unroll
;         for (int j = 0; j < 32; ++j) { v[j] = gelu_f(v[j]); sm += v[j]; }
;         sm += __shfl_xor(sm, 1); sm += __shfl_xor(sm, 2);
;         const float mu = sm * (1.0f / 128.0f); float q = 0.f;
; #pragma unroll
;         for (int j = 0; j < 32; ++j) { v[j] -= mu; q += v[j] * v[j]; }
;         q += __shfl_xor(q, 1); q += __shfl_xor(q, 2);
;         const float rstd = rsqrtf(q * (1.0f / 128.0f) + pg8::EPS);
;         const float* gp = lng + gg * 128 + 32 * q4; const float* bp = lnb + gg * 128 + 32 * q4;
;         LAS unsigned char* dst = lds + (gi ? VN_OFF1 : VN_OFF0) + (32 * q4) * VN_STRIDE + sp_ * 2;
; #pragma unroll
;         for (int j = 0; j < 32; j += 2) { const unsigned pk = cvt_pk_bf16(v[j] * rstd * gp[j] + bp[j], v[j + 1] * rstd * gp[j + 1] + bp[j + 1]);
	global_load_dwordx4 v[144:147], v182, s[36:37] offset:512
	global_load_dwordx4 v[148:151], v182, s[36:37] offset:528
	global_load_dwordx4 v[152:155], v182, s[36:37] offset:544
	global_load_dwordx4 v[156:159], v182, s[36:37] offset:560
	global_load_dwordx4 v[184:187], v182, s[36:37] offset:576
	global_load_dwordx4 v[188:191], v182, s[36:37] offset:592
	global_load_dwordx4 v[192:195], v182, s[36:37] offset:608
	global_load_dwordx4 v[196:199], v182, s[36:37] offset:624
	global_load_dwordx4 v[218:221], v182, s[18:19] offset:512
	global_load_dwordx4 v[222:225], v182, s[18:19] offset:528
	global_load_dwordx4 v[226:229], v182, s[18:19] offset:544
	global_load_dwordx4 v[230:233], v182, s[18:19] offset:560
	global_load_dwordx4 v[234:237], v182, s[18:19] offset:576
	global_load_dwordx4 v[238:241], v182, s[18:19] offset:592
	global_load_dwordx4 v[242:245], v182, s[18:19] offset:608
	global_load_dwordx4 v[200:203], v182, s[18:19] offset:624
	v_fma_f32 v39, v39, v40, v42
	v_fmac_f32_e32 v43, v38, v41
	v_cvt_pk_bf16_f32 v38, v39, v43
	v_add_u32_e32 v39, 0x137e0, v0
	ds_write_b16 v39, v38
	v_add_u32_e32 v39, 0x138f0, v0
	ds_write_b16_d16_hi v39, v38
	v_lshlrev_b32_e32 v41, 16, v12
	v_and_b32_e32 v40, 0xffff0000, v12
	v_lshlrev_b32_e32 v39, 16, v13
	v_and_b32_e32 v38, 0xffff0000, v13
	v_lshlrev_b32_e32 v13, 16, v7
	v_and_b32_e32 v12, 0xffff0000, v7
	v_lshlrev_b32_e32 v7, 16, v9
	v_mul_f32_e32 v9, 0x3d372713, v61
	v_lshlrev_b32_e32 v43, 16, v11
	v_and_b32_e32 v42, 0xffff0000, v11
	v_lshlrev_b32_e32 v11, 16, v8
	v_mul_f32_e32 v8, 0x3fcc422a, v61
	v_fma_f32 v9, v9, v61, 1.0
	v_mul_f32_e32 v8, v8, v9
	v_mul_f32_e32 v8, 0xbfb8aa3b, v8
	v_exp_f32_e32 v8, v8
	v_mul_f32_e32 v9, 0x3d372713, v62
	v_fma_f32 v9, v9, v62, 1.0
	v_add_f32_e32 v8, 1.0, v8
	v_rcp_f32_e32 v63, v8
	v_mul_f32_e32 v8, 0x3fcc422a, v62
	v_mul_f32_e32 v8, v8, v9
	v_mul_f32_e32 v8, 0xbfb8aa3b, v8
	v_exp_f32_e32 v8, v8
	v_mul_f32_e32 v9, 0x3d372713, v60
	v_fma_f32 v9, v9, v60, 1.0
	v_fma_f32 v16, v63, v61, 0
	v_add_f32_e32 v8, 1.0, v8
	v_rcp_f32_e32 v64, v8
	v_mul_f32_e32 v8, 0x3fcc422a, v60
	v_mul_f32_e32 v8, v8, v9
	v_mul_f32_e32 v8, 0xbfb8aa3b, v8
	v_exp_f32_e32 v8, v8
	v_mul_f32_e32 v9, 0x3d372713, v59
	v_fma_f32 v9, v9, v59, 1.0
	v_fmac_f32_e32 v16, v64, v62
	v_add_f32_e32 v8, 1.0, v8
	v_rcp_f32_e32 v65, v8
	v_mul_f32_e32 v8, 0x3fcc422a, v59
	v_mul_f32_e32 v8, v8, v9
	v_mul_f32_e32 v8, 0xbfb8aa3b, v8
	v_exp_f32_e32 v8, v8
	v_mul_f32_e32 v9, 0x3d372713, v58
	v_fma_f32 v9, v9, v58, 1.0
	v_fmac_f32_e32 v16, v65, v60
	v_add_f32_e32 v8, 1.0, v8
	v_rcp_f32_e32 v66, v8
	v_mul_f32_e32 v8, 0x3fcc422a, v58
	v_mul_f32_e32 v8, v8, v9
	v_mul_f32_e32 v8, 0xbfb8aa3b, v8
	v_exp_f32_e32 v8, v8
	v_mul_f32_e32 v9, 0x3d372713, v57
	v_fma_f32 v9, v9, v57, 1.0
	v_fmac_f32_e32 v16, v66, v59
	v_add_f32_e32 v8, 1.0, v8
	v_rcp_f32_e32 v67, v8
	v_mul_f32_e32 v8, 0x3fcc422a, v57
	v_mul_f32_e32 v8, v8, v9
	v_mul_f32_e32 v8, 0xbfb8aa3b, v8
	v_exp_f32_e32 v8, v8
	v_mul_f32_e32 v9, 0x3d372713, v56
	v_fma_f32 v9, v9, v56, 1.0
	v_fmac_f32_e32 v16, v67, v58
	v_add_f32_e32 v8, 1.0, v8
	v_rcp_f32_e32 v68, v8
	v_mul_f32_e32 v8, 0x3fcc422a, v56
	v_mul_f32_e32 v8, v8, v9
	v_mul_f32_e32 v8, 0xbfb8aa3b, v8
	v_exp_f32_e32 v8, v8
	v_mul_f32_e32 v9, 0x3d372713, v55
	v_fma_f32 v9, v9, v55, 1.0
	v_fmac_f32_e32 v16, v68, v57
	v_add_f32_e32 v8, 1.0, v8
	v_rcp_f32_e32 v69, v8
	v_mul_f32_e32 v8, 0x3fcc422a, v55
	v_mul_f32_e32 v8, v8, v9
	v_mul_f32_e32 v8, 0xbfb8aa3b, v8
	v_exp_f32_e32 v8, v8
	v_mul_f32_e32 v9, 0x3d372713, v53
	v_fma_f32 v9, v9, v53, 1.0
	v_fmac_f32_e32 v16, v69, v56
	v_add_f32_e32 v8, 1.0, v8
	v_rcp_f32_e32 v70, v8
	v_mul_f32_e32 v8, 0x3fcc422a, v53
	v_mul_f32_e32 v8, v8, v9
	v_mul_f32_e32 v8, 0xbfb8aa3b, v8
	v_exp_f32_e32 v8, v8
	v_mul_f32_e32 v9, 0x3d372713, v52
	v_fma_f32 v9, v9, v52, 1.0
	v_fmac_f32_e32 v16, v70, v55
	v_add_f32_e32 v8, 1.0, v8
	v_rcp_f32_e32 v71, v8
	v_mul_f32_e32 v8, 0x3fcc422a, v52
	v_mul_f32_e32 v8, v8, v9
	v_mul_f32_e32 v8, 0xbfb8aa3b, v8
	v_exp_f32_e32 v8, v8
	v_mul_f32_e32 v9, 0x3d372713, v51
	v_fma_f32 v9, v9, v51, 1.0
	v_fmac_f32_e32 v16, v71, v53
	v_add_f32_e32 v8, 1.0, v8
	v_rcp_f32_e32 v72, v8
	v_mul_f32_e32 v8, 0x3fcc422a, v51
	v_mul_f32_e32 v8, v8, v9
	v_mul_f32_e32 v8, 0xbfb8aa3b, v8
	v_exp_f32_e32 v8, v8
	v_mul_f32_e32 v9, 0x3d372713, v50
	v_fma_f32 v9, v9, v50, 1.0
	v_fmac_f32_e32 v16, v72, v52
	v_add_f32_e32 v8, 1.0, v8
	v_rcp_f32_e32 v73, v8
	v_mul_f32_e32 v8, 0x3fcc422a, v50
	v_mul_f32_e32 v8, v8, v9
	v_mul_f32_e32 v8, 0xbfb8aa3b, v8
	v_exp_f32_e32 v8, v8
	v_mul_f32_e32 v9, 0x3d372713, v49
	v_fma_f32 v9, v9, v49, 1.0
	v_fmac_f32_e32 v16, v73, v51
	v_add_f32_e32 v8, 1.0, v8
	v_rcp_f32_e32 v74, v8
	v_mul_f32_e32 v8, 0x3fcc422a, v49
	v_mul_f32_e32 v8, v8, v9
	v_mul_f32_e32 v8, 0xbfb8aa3b, v8
	v_exp_f32_e32 v8, v8
	v_mul_f32_e32 v9, 0x3d372713, v48
	v_fma_f32 v9, v9, v48, 1.0
	v_fmac_f32_e32 v16, v74, v50
	v_add_f32_e32 v8, 1.0, v8
	v_rcp_f32_e32 v75, v8
	v_mul_f32_e32 v8, 0x3fcc422a, v48
	v_mul_f32_e32 v8, v8, v9
	v_mul_f32_e32 v8, 0xbfb8aa3b, v8
	v_exp_f32_e32 v8, v8
	v_mul_f32_e32 v9, 0x3d372713, v47
	v_fma_f32 v9, v9, v47, 1.0
	v_fmac_f32_e32 v16, v75, v49
	v_add_f32_e32 v8, 1.0, v8
	v_rcp_f32_e32 v76, v8
	v_mul_f32_e32 v8, 0x3fcc422a, v47
	v_mul_f32_e32 v8, v8, v9
	v_mul_f32_e32 v8, 0xbfb8aa3b, v8
	v_exp_f32_e32 v8, v8
	v_mul_f32_e32 v9, 0x3d372713, v46
	v_fma_f32 v9, v9, v46, 1.0
	v_fmac_f32_e32 v16, v76, v48
	v_add_f32_e32 v8, 1.0, v8
	v_rcp_f32_e32 v77, v8
	v_mul_f32_e32 v8, 0x3fcc422a, v46
	v_mul_f32_e32 v8, v8, v9
	v_mul_f32_e32 v8, 0xbfb8aa3b, v8
	v_exp_f32_e32 v8, v8
	v_mul_f32_e32 v9, 0x3d372713, v45
	v_fma_f32 v9, v9, v45, 1.0
	v_fmac_f32_e32 v16, v77, v47
	v_add_f32_e32 v8, 1.0, v8
; __device__ __forceinline__ float gelu_f(float x) { const float y2 = 1.5957691216057308f * x * (1.0f + 0.044715f * x * x); return x * sigmoid_f(y2); }
; __device__ __forceinline__ void p2_block(LAS unsigned char* lds, const bf16_t* __restrict__ PROJ, bf16_t* __restrict__ ATT, bf16_t* __restrict__ SGU, const float* __restrict__ qn, const float* __restrict__ kn, ...
;     ...
;         for (int j = 0; j < 32; ++j) { v[j] = gelu_f(v[j]); sm += v[j]; }
;         sm += __shfl_xor(sm, 1); sm += __shfl_xor(sm, 2);
	v_rcp_f32_e32 v78, v8
	v_mul_f32_e32 v8, 0x3fcc422a, v45
	v_mul_f32_e32 v8, v8, v9
	v_mul_f32_e32 v8, 0xbfb8aa3b, v8
	v_exp_f32_e32 v8, v8
	v_mul_f32_e32 v9, 0x3d372713, v44
	v_fma_f32 v9, v9, v44, 1.0
	v_fmac_f32_e32 v16, v78, v46
	v_add_f32_e32 v8, 1.0, v8
	v_rcp_f32_e32 v79, v8
	v_mul_f32_e32 v8, 0x3fcc422a, v44
	v_mul_f32_e32 v8, v8, v9
	v_mul_f32_e32 v8, 0xbfb8aa3b, v8
	v_exp_f32_e32 v8, v8
	v_mul_f32_e32 v9, 0x3d372713, v43
	v_fma_f32 v9, v9, v43, 1.0
	v_fmac_f32_e32 v16, v79, v45
	v_add_f32_e32 v8, 1.0, v8
	v_rcp_f32_e32 v80, v8
	v_mul_f32_e32 v8, 0x3fcc422a, v43
	v_mul_f32_e32 v8, v8, v9
	v_mul_f32_e32 v8, 0xbfb8aa3b, v8
	v_exp_f32_e32 v8, v8
	v_mul_f32_e32 v9, 0x3d372713, v42
	v_fma_f32 v9, v9, v42, 1.0
	v_fmac_f32_e32 v16, v80, v44
	v_add_f32_e32 v8, 1.0, v8
	v_rcp_f32_e32 v81, v8
	v_mul_f32_e32 v8, 0x3fcc422a, v42
	v_mul_f32_e32 v8, v8, v9
	v_mul_f32_e32 v8, 0xbfb8aa3b, v8
	v_exp_f32_e32 v8, v8
	v_mul_f32_e32 v9, 0x3d372713, v41
	v_fma_f32 v9, v9, v41, 1.0
	v_fmac_f32_e32 v16, v81, v43
	v_add_f32_e32 v8, 1.0, v8
	v_rcp_f32_e32 v82, v8
	v_mul_f32_e32 v8, 0x3fcc422a, v41
	v_mul_f32_e32 v8, v8, v9
	v_mul_f32_e32 v8, 0xbfb8aa3b, v8
	v_exp_f32_e32 v8, v8
	v_mul_f32_e32 v9, 0x3d372713, v40
	v_fma_f32 v9, v9, v40, 1.0
	v_fmac_f32_e32 v16, v82, v42
	v_add_f32_e32 v8, 1.0, v8
	v_rcp_f32_e32 v83, v8
	v_mul_f32_e32 v8, 0x3fcc422a, v40
	v_mul_f32_e32 v8, v8, v9
	v_mul_f32_e32 v8, 0xbfb8aa3b, v8
	v_exp_f32_e32 v8, v8
	v_mul_f32_e32 v9, 0x3d372713, v39
	v_fma_f32 v9, v9, v39, 1.0
	v_fmac_f32_e32 v16, v83, v41
	v_add_f32_e32 v8, 1.0, v8
	v_rcp_f32_e32 v84, v8
	v_mul_f32_e32 v8, 0x3fcc422a, v39
	v_mul_f32_e32 v8, v8, v9
	v_mul_f32_e32 v8, 0xbfb8aa3b, v8
	v_exp_f32_e32 v8, v8
	v_mul_f32_e32 v9, 0x3d372713, v38
	v_fma_f32 v9, v9, v38, 1.0
	v_fmac_f32_e32 v16, v84, v40
	v_add_f32_e32 v8, 1.0, v8
	v_rcp_f32_e32 v85, v8
	v_mul_f32_e32 v8, 0x3fcc422a, v38
	v_mul_f32_e32 v8, v8, v9
	v_mul_f32_e32 v8, 0xbfb8aa3b, v8
	v_exp_f32_e32 v8, v8
	v_mul_f32_e32 v9, 0x3d372713, v15
	v_fma_f32 v9, v9, v15, 1.0
	v_fmac_f32_e32 v16, v85, v39
	v_add_f32_e32 v8, 1.0, v8
	v_rcp_f32_e32 v86, v8
	v_mul_f32_e32 v8, 0x3fcc422a, v15
	v_mul_f32_e32 v8, v8, v9
	v_mul_f32_e32 v8, 0xbfb8aa3b, v8
	v_exp_f32_e32 v8, v8
	v_fmac_f32_e32 v16, v86, v38
	v_add_f32_e32 v8, 1.0, v8
	v_rcp_f32_e32 v9, v8
	v_mul_f32_e32 v8, 0x3fcc422a, v14
	v_mul_f32_e32 v8, v8, v17
	v_mul_f32_e32 v8, 0xbfb8aa3b, v8
	v_exp_f32_e32 v8, v8
	v_mul_f32_e32 v17, 0x3d372713, v13
	v_fma_f32 v17, v17, v13, 1.0
	v_add_f32_e32 v8, 1.0, v8
	v_rcp_f32_e32 v8, v8
	s_nop 0
	v_pk_mul_f32 v[18:19], v[8:9], v[14:15]
	s_nop 0
	v_add_f32_e32 v16, v19, v16
	v_add_f32_e32 v20, v18, v16
	v_mul_f32_e32 v16, 0x3fcc422a, v13
	v_mul_f32_e32 v16, v16, v17
	v_mul_f32_e32 v16, 0xbfb8aa3b, v16
	v_exp_f32_e32 v16, v16
	v_mul_f32_e32 v18, 0x3d372713, v12
	v_fma_f32 v18, v18, v12, 1.0
	v_add_f32_e32 v16, 1.0, v16
	v_rcp_f32_e32 v17, v16
	v_mul_f32_e32 v16, 0x3fcc422a, v12
	v_mul_f32_e32 v16, v16, v18
	v_mul_f32_e32 v16, 0xbfb8aa3b, v16
	v_exp_f32_e32 v16, v16
	s_nop 0
	v_add_f32_e32 v16, 1.0, v16
	v_rcp_f32_e32 v16, v16
	s_nop 0
	v_pk_mul_f32 v[18:19], v[16:17], v[12:13]
	s_nop 0
	v_add_f32_e32 v19, v19, v20
	v_add_f32_e32 v87, v18, v19
	v_mul_f32_e32 v19, 0x3d372713, v11
	v_mul_f32_e32 v18, 0x3fcc422a, v11
	v_fma_f32 v19, v19, v11, 1.0
	v_mul_f32_e32 v18, v18, v19
	v_mul_f32_e32 v18, 0xbfb8aa3b, v18
	v_exp_f32_e32 v18, v18
	v_mul_f32_e32 v20, 0x3d372713, v10
	v_fma_f32 v20, v20, v10, 1.0
	v_add_f32_e32 v18, 1.0, v18
	v_rcp_f32_e32 v19, v18
	v_mul_f32_e32 v18, 0x3fcc422a, v10
	v_mul_f32_e32 v18, v18, v20
	v_mul_f32_e32 v18, 0xbfb8aa3b, v18
	v_exp_f32_e32 v18, v18
	s_nop 0
	v_add_f32_e32 v18, 1.0, v18
	v_rcp_f32_e32 v18, v18
	s_nop 0
	v_pk_mul_f32 v[20:21], v[18:19], v[10:11]
	s_nop 0
	v_add_f32_e32 v21, v21, v87
	v_add_f32_e32 v87, v20, v21
	v_mul_f32_e32 v21, 0x3d372713, v7
	v_mul_f32_e32 v20, 0x3fcc422a, v7
	v_fma_f32 v21, v21, v7, 1.0
	v_mul_f32_e32 v20, v20, v21
	v_mul_f32_e32 v20, 0xbfb8aa3b, v20
	v_exp_f32_e32 v20, v20
	s_nop 0
	v_add_f32_e32 v20, 1.0, v20
	v_rcp_f32_e32 v21, v20
	v_mul_f32_e32 v20, 0x3fcc422a, v6
	v_mul_f32_e32 v20, v20, v88
	v_mul_f32_e32 v20, 0xbfb8aa3b, v20
	v_exp_f32_e32 v20, v20
	s_nop 0
	v_add_f32_e32 v20, 1.0, v20
	v_rcp_f32_e32 v20, v20
	s_nop 0
	v_pk_mul_f32 v[88:89], v[20:21], v[6:7]
	s_nop 0
	v_add_f32_e32 v87, v89, v87
	v_add_f32_e32 v87, v88, v87
	ds_bpermute_b32 v88, v164, v87
	s_waitcnt lgkmcnt(0)
	v_add_f32_e32 v87, v87, v88
	ds_bpermute_b32 v88, v54, v87
	s_waitcnt lgkmcnt(0)
; __device__ __forceinline__ unsigned cvt_pk_bf16(float lo, float hi) { unsigned r; asm volatile("v_cvt_pk_bf16_f32 %0, %1, %2" : "=v"(r) : "v"(lo), "v"(hi)); return r; }
; #define LAS __attribute__((address_space(3)))
; __device__ __forceinline__ void p2_block(LAS unsigned char* lds, const bf16_t* __restrict__ PROJ, bf16_t* __restrict__ ATT, bf16_t* __restrict__ SGU, const float* __restrict__ qn, const float* __restrict__ kn, ...
;     ...
;         const float mu = sm * (1.0f / 128.0f); float q = 0.f;
; #pragma unroll
;         for (int j = 0; j < 32; ++j) { v[j] -= mu; q += v[j] * v[j]; }
;         q += __shfl_xor(q, 1); q += __shfl_xor(q, 2);
;         const float rstd = rsqrtf(q * (1.0f / 128.0f) + pg8::EPS);
;         const float* gp = lng + gg * 128 + 32 * q4; const float* bp = lnb + gg * 128 + 32 * q4;
;         LAS unsigned char* dst = lds + (gi ? VN_OFF1 : VN_OFF0) + (32 * q4) * VN_STRIDE + sp_ * 2;
; #pragma unroll
;         for (int j = 0; j < 32; j += 2) { const unsigned pk = cvt_pk_bf16(v[j] * rstd * gp[j] + bp[j], v[j + 1] * rstd * gp[j + 1] + bp[j + 1]);
;             *(LAS unsigned short*)(dst + j * VN_STRIDE) = (unsigned short)(pk & 0xffffu); *(LAS unsigned short*)(dst + (j + 1) * VN_STRIDE) = (unsigned short)(pk >> 16); }
	v_add_f32_e32 v87, v87, v88
	v_mul_f32_e32 v88, 0x3c000000, v87
	v_fma_f32 v63, v63, v61, -v88
	v_fma_f32 v61, v64, v62, -v88
	v_mul_f32_e32 v62, v61, v61
	v_fmac_f32_e32 v62, v63, v63
	v_fma_f32 v60, v65, v60, -v88
	v_fmac_f32_e32 v62, v60, v60
	v_fma_f32 v59, v66, v59, -v88
	v_fmac_f32_e32 v62, v59, v59
	v_fma_f32 v58, v67, v58, -v88
	v_fmac_f32_e32 v62, v58, v58
	v_fma_f32 v57, v68, v57, -v88
	v_fmac_f32_e32 v62, v57, v57
	v_fma_f32 v56, v69, v56, -v88
	v_fmac_f32_e32 v62, v56, v56
	v_fma_f32 v55, v70, v55, -v88
	v_fmac_f32_e32 v62, v55, v55
	v_fma_f32 v53, v71, v53, -v88
	v_fmac_f32_e32 v62, v53, v53
	v_fma_f32 v52, v72, v52, -v88
	v_fmac_f32_e32 v62, v52, v52
	v_fma_f32 v51, v73, v51, -v88
	v_fmac_f32_e32 v62, v51, v51
	v_fma_f32 v50, v74, v50, -v88
	v_fmac_f32_e32 v62, v50, v50
	v_fma_f32 v49, v75, v49, -v88
	v_fmac_f32_e32 v62, v49, v49
	v_fma_f32 v48, v76, v48, -v88
	v_fmac_f32_e32 v62, v48, v48
	v_fma_f32 v47, v77, v47, -v88
	v_fmac_f32_e32 v62, v47, v47
	v_fma_f32 v46, v78, v46, -v88
	v_fmac_f32_e32 v62, v46, v46
	v_fma_f32 v45, v79, v45, -v88
	v_fmac_f32_e32 v62, v45, v45
	v_fma_f32 v44, v80, v44, -v88
	v_fmac_f32_e32 v62, v44, v44
	v_fma_f32 v43, v81, v43, -v88
	v_fmac_f32_e32 v62, v43, v43
	v_fma_f32 v42, v82, v42, -v88
	v_fmac_f32_e32 v62, v42, v42
	v_fma_f32 v41, v83, v41, -v88
	v_fmac_f32_e32 v62, v41, v41
	v_fma_f32 v40, v84, v40, -v88
	v_fmac_f32_e32 v62, v40, v40
	v_fma_f32 v39, v85, v39, -v88
	v_fmac_f32_e32 v62, v39, v39
	v_fma_f32 v38, v86, v38, -v88
	v_pk_fma_f32 v[14:15], v[8:9], v[14:15], v[88:89] op_sel_hi:[1,1,0] neg_lo:[0,0,1] neg_hi:[0,0,1]
	v_fmac_f32_e32 v62, v38, v38
	v_pk_mul_f32 v[8:9], v[14:15], v[14:15]
	v_pk_fma_f32 v[12:13], v[16:17], v[12:13], v[88:89] op_sel_hi:[1,1,0] neg_lo:[0,0,1] neg_hi:[0,0,1]
	v_add_f32_e32 v9, v9, v62
	v_add_f32_e32 v62, v8, v9
	v_pk_mul_f32 v[8:9], v[12:13], v[12:13]
	v_pk_fma_f32 v[6:7], v[20:21], v[6:7], v[88:89] op_sel_hi:[1,1,0] neg_lo:[0,0,1] neg_hi:[0,0,1]
	v_add_f32_e32 v9, v9, v62
	v_add_f32_e32 v16, v8, v9
	v_pk_fma_f32 v[8:9], v[18:19], v[10:11], v[88:89] op_sel_hi:[1,1,0] neg_lo:[0,0,1] neg_hi:[0,0,1]
	v_add_u32_e32 v19, 0x1a000, v0
	v_pk_mul_f32 v[10:11], v[8:9], v[8:9]
	v_lshlrev_b32_e32 v78, 16, v33
	v_add_f32_e32 v11, v11, v16
	v_add_f32_e32 v16, v10, v11
	v_pk_mul_f32 v[10:11], v[6:7], v[6:7]
	v_lshlrev_b32_e32 v79, 16, v5
	v_add_f32_e32 v11, v11, v16
	v_add_f32_e32 v10, v10, v11
	ds_bpermute_b32 v11, v164, v10
	v_and_b32_e32 v5, 0xffff0000, v4
	v_and_b32_e32 v4, 0xffff0000, v32
	v_mov_b32_e32 v32, v5
	v_mov_b32_e32 v33, v101
	s_waitcnt lgkmcnt(0)
	v_add_f32_e32 v10, v10, v11
	ds_bpermute_b32 v11, v54, v10
	v_mov_b32_e32 v54, v96
	v_add_u32_e32 v81, 0, v132
	v_lshlrev_b32_e32 v73, 2, v162
	v_sub_u32_e32 v74, v81, v130
	s_waitcnt lgkmcnt(0)
	v_add_f32_e32 v10, v10, v11
	v_fmamk_f32 v10, v10, 0x3c000000, v209
	v_cmp_gt_f32_e32 vcc, s82, v10
	v_mul_f32_e32 v11, 0x4b800000, v10
	v_or_b32_e32 v71, 2, v130
	v_cndmask_b32_e32 v10, v10, v11, vcc
	v_rsq_f32_e32 v10, v10
	v_or_b32_e32 v70, 3, v130
	v_or_b32_e32 v72, 4, v130
	v_mul_f32_e32 v11, 0x45800000, v10
	v_cndmask_b32_e32 v18, v10, v11, vcc
	s_waitcnt vmcnt(0)
	v_mov_b64_e32 v[10:11], v[144:145]
	v_mov_b64_e32 v[16:17], v[218:219]
	v_mul_f32_e32 v20, v63, v18
	v_mul_f32_e32 v15, v15, v18
	v_mul_f32_e32 v14, v14, v18
	v_mul_f32_e32 v13, v13, v18
	v_mul_f32_e32 v12, v12, v18
	v_mul_f32_e32 v9, v9, v18
	v_mul_f32_e32 v8, v8, v18
	v_mul_f32_e32 v7, v7, v18
	v_mul_f32_e32 v6, v6, v18
	s_waitcnt vmcnt(0)
	v_fma_f32 v10, v10, v20, v16
	v_mul_f32_e32 v16, v61, v18
	v_fmac_f32_e32 v17, v11, v16
	v_add_u32_e32 v11, 0x1a110, v0
	v_cvt_pk_bf16_f32 v10, v10, v17
	ds_write_b16 v19, v10
	ds_write_b16_d16_hi v11, v10
	v_mov_b64_e32 v[10:11], v[146:147]
	v_mov_b64_e32 v[16:17], v[220:221]
	v_mul_f32_e32 v19, v60, v18
	s_waitcnt vmcnt(0)
	v_fma_f32 v10, v10, v19, v16
	v_mul_f32_e32 v16, v59, v18
	v_fmac_f32_e32 v17, v11, v16
	v_add_u32_e32 v11, 0x1a220, v0
	v_cvt_pk_bf16_f32 v10, v10, v17
	ds_write_b16 v11, v10
	v_add_u32_e32 v11, 0x1a330, v0
	ds_write_b16_d16_hi v11, v10
	v_mov_b64_e32 v[10:11], v[148:149]
	v_mov_b64_e32 v[16:17], v[222:223]
	v_mul_f32_e32 v19, v58, v18
	s_waitcnt vmcnt(0)
	v_fma_f32 v10, v10, v19, v16
	v_mul_f32_e32 v16, v57, v18
	v_fmac_f32_e32 v17, v11, v16
	v_add_u32_e32 v11, 0x1a440, v0
	v_cvt_pk_bf16_f32 v10, v10, v17
	ds_write_b16 v11, v10
	v_add_u32_e32 v11, 0x1a550, v0
	ds_write_b16_d16_hi v11, v10
	v_mov_b64_e32 v[10:11], v[150:151]
	v_mov_b64_e32 v[16:17], v[224:225]
	v_mul_f32_e32 v19, v56, v18
	v_mov_b32_e32 v56, v109
	v_mov_b32_e32 v57, v105
	v_pk_fma_f32 v[110:111], v[56:57], v[56:57], v[110:111]
	s_waitcnt vmcnt(0)
	v_fma_f32 v10, v10, v19, v16
	v_mul_f32_e32 v16, v55, v18
	v_fmac_f32_e32 v17, v11, v16
	v_add_u32_e32 v11, 0x1a660, v0
	v_cvt_pk_bf16_f32 v10, v10, v17
	ds_write_b16 v11, v10
	v_add_u32_e32 v11, 0x1a770, v0
	ds_write_b16_d16_hi v11, v10
	v_mov_b64_e32 v[10:11], v[152:153]
	v_mov_b64_e32 v[16:17], v[226:227]
	v_mul_f32_e32 v19, v53, v18
	v_mov_b32_e32 v55, v78
	v_pk_mul_f32 v[54:55], v[54:55], v[54:55]
	s_waitcnt vmcnt(0)
	v_fma_f32 v10, v10, v19, v16
	v_mul_f32_e32 v16, v52, v18
	v_fmac_f32_e32 v17, v11, v16
	v_add_u32_e32 v11, 0x1a880, v0
	v_cvt_pk_bf16_f32 v10, v10, v17
	ds_write_b16 v11, v10
	v_add_u32_e32 v11, 0x1a990, v0
	ds_write_b16_d16_hi v11, v10
	v_mov_b64_e32 v[10:11], v[154:155]
	v_mov_b64_e32 v[16:17], v[228:229]
	v_mul_f32_e32 v19, v51, v18
	s_waitcnt vmcnt(0)
	v_fma_f32 v10, v10, v19, v16
	v_mul_f32_e32 v16, v50, v18
	v_fmac_f32_e32 v17, v11, v16
	v_add_u32_e32 v11, 0x1aaa0, v0
	v_cvt_pk_bf16_f32 v10, v10, v17
	ds_write_b16 v11, v10
	v_add_u32_e32 v11, 0x1abb0, v0
	ds_write_b16_d16_hi v11, v10
	v_mov_b64_e32 v[10:11], v[156:157]
	v_mov_b64_e32 v[16:17], v[230:231]
	v_mul_f32_e32 v19, v49, v18
	s_waitcnt vmcnt(0)
; __device__ __forceinline__ unsigned cvt_pk_bf16(float lo, float hi) { unsigned r; asm volatile("v_cvt_pk_bf16_f32 %0, %1, %2" : "=v"(r) : "v"(lo), "v"(hi)); return r; }
; #define LAS __attribute__((address_space(3)))
; __device__ __forceinline__ void unpack8(const u32x4 w, float* f) { f[0] = bf_lo(w.x); f[1] = bf_hi(w.x); f[2] = bf_lo(w.y); f[3] = bf_hi(w.y); f[4] = bf_lo(w.z); f[5] = bf_hi(w.z); f[6] = bf_lo(w.w); f[7] = bf_hi(w.w); }
; __device__ __forceinline__ void p2_block(LAS unsigned char* lds, const bf16_t* __restrict__ PROJ, bf16_t* __restrict__ ATT, bf16_t* __restrict__ SGU, const float* __restrict__ qn, const float* __restrict__ kn, ...
;     ...
;         for (int j = 0; j < 32; j += 2) { const unsigned pk = cvt_pk_bf16(v[j] * rstd * gp[j] + bp[j], v[j + 1] * rstd * gp[j + 1] + bp[j + 1]);
;             *(LAS unsigned short*)(dst + j * VN_STRIDE) = (unsigned short)(pk & 0xffffu); *(LAS unsigned short*)(dst + (j + 1) * VN_STRIDE) = (unsigned short)(pk >> 16); }
;     }
;     __syncthreads();
; #pragma unroll
;     for (int c = 2; c < 4; ++c) { const bf16_t* qp = PROJ + ((size_t)b * pg8::SEQ + n * 128 + rbase + 16 * c + fr) * pg8::IN_W + hq * 64 + 8 * fq; qa[c] = *(const u32x4*)qp; qb[c] = *(const u32x4*)(qp + 32); }
;     const float sink = sinks[hq];
;     constexpr float LOG2E = 1.4426950408889634f;
; #pragma unroll
;     for (int c = 0; c < 4; ++c) {
;         const int i0 = rbase + 16 * c, irow = i0 + fr, pos = n * 128 + irow; const size_t grow = (size_t)b * pg8::SEQ + pos;
;         bf16x8 qf0, qf1;
;         {
;             float x1[8], x2[8]; unpack8(qa[c], x1); unpack8(qb[c], x2);
;             float ss = 0.f;
; #pragma unroll
;             for (int j = 0; j < 8; ++j) ss += x1[j] * x1[j] + x2[j] * x2[j];
;             ss += __shfl_xor(ss, 16); ss += __shfl_xor(ss, 32);
;             const float rinv = rsqrtf(ss * (1.0f / 64.0f) + pg8::EPS) * 0.125f;
;             const float* cp = COS + pos * 32 + 8 * fq; const float* sp = SIN + pos * 32 + 8 * fq;
;             float o1[8], o2[8];
; #pragma unroll
;             for (int j = 0; j < 8; ++j) { const float a1 = x1[j] * rinv * qn[8 * fq + j], a2 = x2[j] * rinv * qn[32 + 8 * fq + j], cc = cp[j], sn = sp[j]; o1[j] = a1 * cc - a2 * sn; o2[j] = a2 * cc + a1 * sn; }
	v_fma_f32 v10, v10, v19, v16
	v_mul_f32_e32 v16, v48, v18
	v_fmac_f32_e32 v17, v16, v11
	v_add_u32_e32 v11, 0x1acc0, v0
	v_cvt_pk_bf16_f32 v10, v10, v17
	ds_write_b16 v11, v10
	v_add_u32_e32 v11, 0x1add0, v0
	ds_write_b16_d16_hi v11, v10
	v_mov_b64_e32 v[10:11], v[158:159]
	v_mov_b64_e32 v[16:17], v[232:233]
	v_mul_f32_e32 v19, v47, v18
	s_waitcnt vmcnt(0)
	v_fma_f32 v10, v19, v10, v16
	v_mul_f32_e32 v16, v46, v18
	v_fmac_f32_e32 v17, v16, v11
	v_add_u32_e32 v11, 0x1aee0, v0
	v_cvt_pk_bf16_f32 v10, v10, v17
	ds_write_b16 v11, v10
	v_add_u32_e32 v11, 0x1aff0, v0
	ds_write_b16_d16_hi v11, v10
	v_mov_b64_e32 v[10:11], v[184:185]
	v_mov_b64_e32 v[16:17], v[234:235]
	v_mul_f32_e32 v19, v45, v18
	s_waitcnt vmcnt(0)
	v_fma_f32 v10, v19, v10, v16
	v_mul_f32_e32 v16, v44, v18
	v_fmac_f32_e32 v17, v16, v11
	v_add_u32_e32 v11, 0x1b100, v0
	v_cvt_pk_bf16_f32 v10, v10, v17
	ds_write_b16 v11, v10
	v_add_u32_e32 v11, 0x1b210, v0
	ds_write_b16_d16_hi v11, v10
	v_mov_b64_e32 v[10:11], v[186:187]
	v_mov_b64_e32 v[16:17], v[236:237]
	v_mul_f32_e32 v19, v43, v18
	v_or_b32_e32 v44, s17, v161
	s_waitcnt vmcnt(0)
	v_fma_f32 v10, v19, v10, v16
	v_mul_f32_e32 v16, v42, v18
	v_fmac_f32_e32 v17, v16, v11
	v_add_u32_e32 v11, 0x1b320, v0
	v_cvt_pk_bf16_f32 v10, v10, v17
	ds_write_b16 v11, v10
	v_add_u32_e32 v11, 0x1b430, v0
	ds_write_b16_d16_hi v11, v10
	v_mov_b64_e32 v[10:11], v[188:189]
	v_mov_b64_e32 v[16:17], v[238:239]
	v_mul_f32_e32 v19, v41, v18
	s_waitcnt vmcnt(0)
	v_fma_f32 v10, v19, v10, v16
	v_mul_f32_e32 v16, v40, v18
	v_fmac_f32_e32 v17, v16, v11
	v_add_u32_e32 v11, 0x1b540, v0
	v_cvt_pk_bf16_f32 v10, v10, v17
	ds_write_b16 v11, v10
	v_add_u32_e32 v11, 0x1b650, v0
	ds_write_b16_d16_hi v11, v10
	v_mov_b64_e32 v[10:11], v[190:191]
	v_mov_b64_e32 v[16:17], v[240:241]
	v_mul_f32_e32 v19, v39, v18
	s_waitcnt vmcnt(0)
	v_fma_f32 v10, v19, v10, v16
	v_mul_f32_e32 v16, v38, v18
	v_fmac_f32_e32 v17, v16, v11
	v_add_u32_e32 v11, 0x1b760, v0
	v_cvt_pk_bf16_f32 v10, v10, v17
	ds_write_b16 v11, v10
	v_add_u32_e32 v11, 0x1b870, v0
	ds_write_b16_d16_hi v11, v10
	v_mov_b64_e32 v[10:11], v[192:193]
	v_mov_b64_e32 v[16:17], v[242:243]
	s_waitcnt vmcnt(0)
	v_fma_f32 v10, v15, v10, v16
	v_fmac_f32_e32 v17, v14, v11
	v_add_u32_e32 v11, 0x1b980, v0
	v_cvt_pk_bf16_f32 v10, v10, v17
	ds_write_b16 v11, v10
	v_add_u32_e32 v11, 0x1ba90, v0
	ds_write_b16_d16_hi v11, v10
	v_mov_b64_e32 v[10:11], v[194:195]
	v_mov_b64_e32 v[14:15], v[244:245]
	s_waitcnt vmcnt(0)
	v_fma_f32 v10, v13, v10, v14
	v_fmac_f32_e32 v15, v12, v11
	v_add_u32_e32 v11, 0x1bba0, v0
	v_cvt_pk_bf16_f32 v10, v10, v15
	ds_write_b16 v11, v10
	v_add_u32_e32 v11, 0x1bcb0, v0
	ds_write_b16_d16_hi v11, v10
	v_mov_b64_e32 v[10:11], v[196:197]
	v_mov_b64_e32 v[12:13], v[200:201]
	v_lshlrev_b32_e32 v14, 7, v44
	v_mov_b32_e32 v15, v1
	v_or_b32_e32 v44, s48, v44
	s_waitcnt vmcnt(0)
	v_fma_f32 v9, v9, v10, v12
	v_fmac_f32_e32 v13, v8, v11
	v_cvt_pk_bf16_f32 v8, v9, v13
	v_add_u32_e32 v9, 0x1bdc0, v0
	ds_write_b16 v9, v8
	v_add_u32_e32 v9, 0x1bed0, v0
	ds_write_b16_d16_hi v9, v8
	v_mov_b64_e32 v[8:9], v[198:199]
	v_mov_b64_e32 v[10:11], v[202:203]
	s_waitcnt vmcnt(0)
	v_fma_f32 v7, v7, v8, v10
	v_fmac_f32_e32 v11, v6, v9
	v_cvt_pk_bf16_f32 v6, v7, v11
	v_add_u32_e32 v7, 0x1bfe0, v0
	v_add_u32_e32 v0, 0x1c0f0, v0
	ds_write_b16_d16_hi v0, v6
	v_or_b32_e32 v0, 32, v163
	ds_write_b16 v7, v6
	v_mad_u64_u32 v[6:7], s[28:29], v0, s83, v[134:135]
	v_mad_i32_i24 v7, s49, v212, v7
	v_or_b32_e32 v0, 48, v163
	s_waitcnt lgkmcnt(0)
	s_barrier
	global_load_dwordx4 v[38:41], v[6:7], off
	global_load_dwordx4 v[34:37], v[6:7], off offset:64
	v_mad_u64_u32 v[6:7], s[28:29], v0, s83, v[134:135]
	v_xor_b32_e32 v0, 16, v211
	v_cmp_lt_i32_e32 vcc, v0, v133
	s_lshl_b64 s[28:29], s[42:43], 2
	s_add_u32 s28, s63, s28
	v_cndmask_b32_e32 v0, v211, v0, vcc
	v_lshlrev_b32_e32 v76, 2, v0
	v_xor_b32_e32 v0, 32, v211
	v_cmp_lt_i32_e32 vcc, v0, v133
	v_mad_i32_i24 v7, s49, v212, v7
	s_addc_u32 s29, s78, s29
	v_cndmask_b32_e32 v0, v211, v0, vcc
	v_lshlrev_b32_e32 v77, 2, v0
	v_lshlrev_b32_e32 v0, 5, v162
	v_lshl_add_u64 v[46:47], s[44:45], 0, v[0:1]
	v_lshl_add_u64 v[48:49], s[46:47], 0, v[0:1]
	global_load_dwordx4 v[10:13], v[6:7], off
	s_nop 0
	global_load_dwordx4 v[6:9], v[6:7], off offset:64
	v_lshl_add_u64 v[50:51], v[46:47], 0, v[14:15]
	global_load_dword v75, v1, s[28:29]
	v_lshl_add_u64 v[52:53], v[48:49], 0, v[14:15]
	global_load_dwordx4 v[14:17], v0, s[38:39] offset:16
	global_load_dwordx4 v[18:21], v0, s[38:39]
	global_load_dwordx4 v[58:61], v0, s[38:39] offset:144
	global_load_dwordx4 v[62:65], v0, s[38:39] offset:128
	global_load_dwordx4 v[66:69], v[50:51], off offset:16
	global_load_dwordx4 v[82:85], v[50:51], off
	global_load_dwordx4 v[86:89], v[52:53], off offset:16
	global_load_dwordx4 v[90:93], v[52:53], off
	v_mov_b32_e32 v52, v97
	v_mov_b32_e32 v53, v79
	v_pk_fma_f32 v[98:99], v[52:53], v[52:53], v[54:55]
	v_mov_b32_e32 v54, v4
	v_mov_b32_e32 v55, v100
	v_pk_mul_f32 v[54:55], v[54:55], v[54:55]
	s_cmp_lg_u32 s27, 0
	v_pk_fma_f32 v[32:33], v[32:33], v[32:33], v[54:55]
	s_cselect_b64 s[50:51], -1, 0
	s_add_u32 s6, s60, s6
	s_addc_u32 s7, s61, s7
	v_lshl_add_u64 v[42:43], s[6:7], 0, v[130:131]
	s_lshr_b32 s29, s26, 4
	s_mov_b32 s6, s5
	s_mov_b32 s7, s5
	s_add_i32 s28, s29, 4
	s_waitcnt vmcnt(7)
	v_mov_b32_e32 v53, v14
	v_add_f32_e32 v14, v30, v31
	v_add_f32_e32 v14, v111, v14
	v_add_f32_e32 v14, v110, v14
	v_add_f32_e32 v14, v33, v14
	v_add_f32_e32 v14, v32, v14
	v_add_f32_e32 v14, v99, v14
	v_add_f32_e32 v14, v98, v14
	v_mov_b32_e32 v51, v16
	ds_bpermute_b32 v16, v76, v14
	s_waitcnt vmcnt(4)
	v_mov_b32_e32 v56, v62
	v_mov_b32_e32 v57, v18
	s_waitcnt vmcnt(2)
; __device__ __forceinline__ unsigned cvt_pk_bf16(float lo, float hi) { unsigned r; asm volatile("v_cvt_pk_bf16_f32 %0, %1, %2" : "=v"(r) : "v"(lo), "v"(hi)); return r; }
; #define LAS __attribute__((address_space(3)))
; #define MFMA16(a, b, c) __builtin_amdgcn_mfma_f32_16x16x32_bf16((a), (b), (c), 0, 0, 0)
; __device__ __forceinline__ void unpack8(const u32x4 w, float* f) { f[0] = bf_lo(w.x); f[1] = bf_hi(w.x); f[2] = bf_lo(w.y); f[3] = bf_hi(w.y); f[4] = bf_lo(w.z); f[5] = bf_hi(w.z); f[6] = bf_lo(w.w); f[7] = bf_hi(w.w); }
; __device__ __forceinline__ void p2_block(LAS unsigned char* lds, const bf16_t* __restrict__ PROJ, bf16_t* __restrict__ ATT, bf16_t* __restrict__ SGU, const float* __restrict__ qn, const float* __restrict__ kn, ...
;     ...
;             float x1[8], x2[8]; unpack8(qa[c], x1); unpack8(qb[c], x2);
;             float ss = 0.f;
; #pragma unroll
;             for (int j = 0; j < 8; ++j) ss += x1[j] * x1[j] + x2[j] * x2[j];
;             ss += __shfl_xor(ss, 16); ss += __shfl_xor(ss, 32);
;             const float rinv = rsqrtf(ss * (1.0f / 64.0f) + pg8::EPS) * 0.125f;
;             const float* cp = COS + pos * 32 + 8 * fq; const float* sp = SIN + pos * 32 + 8 * fq;
;             float o1[8], o2[8];
; #pragma unroll
;             for (int j = 0; j < 8; ++j) { const float a1 = x1[j] * rinv * qn[8 * fq + j], a2 = x2[j] * rinv * qn[32 + 8 * fq + j], cc = cp[j], sn = sp[j]; o1[j] = a1 * cc - a2 * sn; o2[j] = a2 * cc + a1 * sn; }
;             u32x4 w0, w1;
;             w0.x = cvt_pk_bf16(o1[0], o1[1]); w0.y = cvt_pk_bf16(o1[2], o1[3]); w0.z = cvt_pk_bf16(o1[4], o1[5]); w0.w = cvt_pk_bf16(o1[6], o1[7]);
;             w1.x = cvt_pk_bf16(o2[0], o2[1]); w1.y = cvt_pk_bf16(o2[2], o2[3]); w1.z = cvt_pk_bf16(o2[4], o2[5]); w1.w = cvt_pk_bf16(o2[6], o2[7]);
;             qf0 = __builtin_bit_cast(bf16x8, w0); qf1 = __builtin_bit_cast(bf16x8, w1);
;         }
;         const int t0 = (i0 >> 4) < 6 ? (i0 >> 4) : 6;
;         f32x4 sc_[10];
;         const LAS unsigned char* kbase = KS + (16 * t0 + fr) * KS_STRIDE + 16 * fq;
; #pragma unroll
;         for (int t = 0; t < 10; ++t) { const bf16x8 k0 = *(const LAS bf16x8*)(kbase + t * 16 * KS_STRIDE), k1 = *(const LAS bf16x8*)(kbase + t * 16 * KS_STRIDE + 64);
;             f32x4 z = (f32x4){0.f, 0.f, 0.f, 0.f}; z = MFMA16(k0, qf0, z); sc_[t] = MFMA16(k1, qf1, z); }
	v_mov_b32_e32 v114, v82
	s_waitcnt vmcnt(0)
	v_mov_b32_e32 v115, v90
	s_waitcnt lgkmcnt(0)
	v_add_f32_e32 v14, v14, v16
	ds_bpermute_b32 v16, v77, v14
	v_mov_b32_e32 v32, v90
	v_mov_b32_e32 v33, v82
	v_mov_b32_e32 v18, v63
	v_mov_b32_e32 v82, v91
	s_waitcnt lgkmcnt(0)
	v_add_f32_e32 v14, v14, v16
	v_fmamk_f32 v14, v14, 0x3c800000, v209
	v_cmp_gt_f32_e32 vcc, s82, v14
	v_mul_f32_e32 v16, 0x4b800000, v14
	v_mov_b32_e32 v90, v83
	v_cndmask_b32_e32 v14, v14, v16, vcc
	v_rsq_f32_e32 v14, v14
	v_mov_b32_e32 v52, v58
	v_mov_b32_e32 v54, v64
	v_mov_b32_e32 v55, v20
	v_mul_f32_e32 v16, 0x45800000, v14
	v_cndmask_b32_e32 v14, v14, v16, vcc
	v_mul_f32_e32 v16, 0x3e000000, v14
	v_pk_mul_f32 v[30:31], v[16:17], v[112:113] op_sel_hi:[0,1]
	v_pk_mul_f32 v[30:31], v[56:57], v[30:31]
	v_pk_mul_f32 v[2:3], v[16:17], v[2:3] op_sel_hi:[0,1]
	v_pk_mul_f32 v[32:33], v[32:33], v[30:31]
	v_pk_mul_f32 v[30:31], v[114:115], v[30:31]
	v_pk_mul_f32 v[2:3], v[18:19], v[2:3]
	v_add_f32_e32 v45, v30, v31
	v_pk_mul_f32 v[30:31], v[82:83], v[2:3]
	v_pk_mul_f32 v[2:3], v[90:91], v[2:3]
	v_mov_b32_e32 v106, v84
	v_add_f32_e32 v58, v2, v3
	v_pk_mul_f32 v[2:3], v[16:17], v[104:105] op_sel_hi:[0,1]
	v_mov_b32_e32 v107, v92
	v_sub_f32_e32 v32, v33, v32
	v_sub_f32_e32 v33, v31, v30
	v_pk_mul_f32 v[2:3], v[54:55], v[2:3]
	v_mov_b32_e32 v30, v92
	v_mov_b32_e32 v31, v84
	v_pk_mul_f32 v[30:31], v[30:31], v[2:3]
	v_pk_mul_f32 v[2:3], v[106:107], v[2:3]
	v_mov_b32_e32 v20, v65
	v_add_f32_e32 v62, v2, v3
	v_pk_mul_f32 v[2:3], v[16:17], v[108:109] op_sel_hi:[0,1]
	v_pk_mul_f32 v[2:3], v[2:3], v[20:21]
	v_mov_b32_e32 v84, v93
	v_mov_b32_e32 v92, v85
	v_mov_b32_e32 v50, v60
	v_sub_f32_e32 v60, v31, v30
	v_pk_mul_f32 v[30:31], v[2:3], v[84:85]
	v_pk_mul_f32 v[2:3], v[2:3], v[92:93]
	v_mov_b32_e32 v102, v66
	v_add_f32_e32 v64, v2, v3
	v_pk_mul_f32 v[2:3], v[16:17], v[100:101] op_sel_hi:[0,1]
	v_mov_b32_e32 v103, v86
	v_sub_f32_e32 v63, v31, v30
	v_pk_mul_f32 v[2:3], v[2:3], v[52:53]
	v_mov_b32_e32 v30, v86
	v_mov_b32_e32 v31, v66
	v_pk_mul_f32 v[30:31], v[2:3], v[30:31]
	v_pk_mul_f32 v[2:3], v[2:3], v[102:103]
	v_mov_b32_e32 v14, v59
	v_add_f32_e32 v80, v2, v3
	v_pk_mul_f32 v[2:3], v[16:17], v[4:5] op_sel_hi:[0,1]
	v_pk_mul_f32 v[2:3], v[2:3], v[14:15]
	v_mov_b32_e32 v66, v87
	v_mov_b32_e32 v86, v67
	v_pk_mul_f32 v[4:5], v[2:3], v[66:67]
	v_pk_mul_f32 v[2:3], v[2:3], v[86:87]
	v_mov_b32_e32 v94, v68
	v_add_f32_e32 v66, v2, v3
	v_pk_mul_f32 v[2:3], v[16:17], v[78:79] op_sel_hi:[0,1]
	v_mov_b32_e32 v95, v88
	v_sub_f32_e32 v59, v5, v4
	v_pk_mul_f32 v[2:3], v[2:3], v[50:51]
	v_mov_b32_e32 v4, v88
	v_mov_b32_e32 v5, v68
	v_pk_mul_f32 v[4:5], v[2:3], v[4:5]
	v_pk_mul_f32 v[2:3], v[2:3], v[94:95]
	v_mov_b32_e32 v68, v89
	v_add_f32_e32 v78, v2, v3
	v_pk_mul_f32 v[2:3], v[16:17], v[96:97] op_sel_hi:[0,1]
	v_mov_b32_e32 v16, v61
	v_pk_mul_f32 v[2:3], v[2:3], v[16:17]
	v_sub_f32_e32 v67, v5, v4
	v_pk_mul_f32 v[4:5], v[2:3], v[68:69]
	v_mov_b32_e32 v88, v69
	v_sub_f32_e32 v65, v31, v30
	v_sub_f32_e32 v4, v5, v4
	v_pk_mul_f32 v[2:3], v[2:3], v[88:89]
	v_cvt_pk_bf16_f32 v30, v32, v33
	v_cvt_pk_bf16_f32 v31, v60, v63
	v_cvt_pk_bf16_f32 v32, v65, v59
	v_cvt_pk_bf16_f32 v33, v67, v4
	v_cvt_pk_bf16_f32 v58, v45, v58
	v_mad_u32_u24 v45, v161, s59, v81
	v_add_f32_e32 v2, v2, v3
	v_cvt_pk_bf16_f32 v59, v62, v64
	v_cvt_pk_bf16_f32 v60, v80, v66
	v_cvt_pk_bf16_f32 v61, v78, v2
	ds_read_b128 v[62:65], v45
	ds_read_b128 v[66:69], v45 offset:64
	s_waitcnt lgkmcnt(1)
	v_mfma_f32_16x16x32_bf16 v[62:65], v[62:65], v[30:33], 0
	v_mov_b64_e32 v[2:3], s[4:5]
	v_mov_b64_e32 v[4:5], s[6:7]
	s_or_b32 s4, s29, 2
	s_waitcnt lgkmcnt(0)
	v_mfma_f32_16x16x32_bf16 v[62:65], v[66:69], v[58:61], v[62:65]
	ds_read_b128 v[66:69], v45 offset:2304
	ds_read_b128 v[82:85], v45 offset:2368
	s_or_b32 s6, s26, s27
	s_waitcnt lgkmcnt(1)
	v_mfma_f32_16x16x32_bf16 v[66:69], v[66:69], v[30:33], 0
	s_waitcnt lgkmcnt(0)
	v_mfma_f32_16x16x32_bf16 v[66:69], v[82:85], v[58:61], v[66:69]
	ds_read_b128 v[82:85], v45 offset:4608
	ds_read_b128 v[86:89], v45 offset:4672
	s_waitcnt lgkmcnt(1)
	v_mfma_f32_16x16x32_bf16 v[82:85], v[82:85], v[30:33], 0
	s_waitcnt lgkmcnt(0)
	v_mfma_f32_16x16x32_bf16 v[84:87], v[86:89], v[58:61], v[82:85]
	ds_read_b128 v[88:91], v45 offset:6912
	ds_read_b128 v[92:95], v45 offset:6976
	s_nop 3
	v_or_b32_e32 v82, s26, v73
	s_waitcnt lgkmcnt(1)
	v_mfma_f32_16x16x32_bf16 v[88:91], v[88:91], v[30:33], 0
	v_or_b32_e32 v83, 48, v82
	s_waitcnt lgkmcnt(0)
	v_mfma_f32_16x16x32_bf16 v[88:91], v[92:95], v[58:61], v[88:91]
	ds_read_b128 v[92:95], v45 offset:9216
	ds_read_b128 v[96:99], v45 offset:9280
	s_waitcnt lgkmcnt(1)
	v_mfma_f32_16x16x32_bf16 v[92:95], v[92:95], v[30:33], 0
	s_waitcnt lgkmcnt(0)
	v_mfma_f32_16x16x32_bf16 v[92:95], v[96:99], v[58:61], v[92:95]
	ds_read_b128 v[96:99], v45 offset:11520
	ds_read_b128 v[100:103], v45 offset:11584
	s_waitcnt lgkmcnt(1)
	v_mfma_f32_16x16x32_bf16 v[96:99], v[96:99], v[30:33], 0
	s_waitcnt lgkmcnt(0)
	v_mfma_f32_16x16x32_bf16 v[96:99], v[100:103], v[58:61], v[96:99]
	ds_read_b128 v[100:103], v45 offset:13824
	ds_read_b128 v[104:107], v45 offset:13888
	s_waitcnt lgkmcnt(1)
	v_mfma_f32_16x16x32_bf16 v[100:103], v[100:103], v[30:33], 0
	s_waitcnt lgkmcnt(0)
	v_mfma_f32_16x16x32_bf16 v[100:103], v[104:107], v[58:61], v[100:103]
	ds_read_b128 v[104:107], v45 offset:16128
	ds_read_b128 v[108:111], v45 offset:16192
	s_waitcnt lgkmcnt(1)
	v_mfma_f32_16x16x32_bf16 v[104:107], v[104:107], v[30:33], 0
	s_waitcnt lgkmcnt(0)
	v_mfma_f32_16x16x32_bf16 v[104:107], v[108:111], v[58:61], v[104:107]
	ds_read_b128 v[108:111], v45 offset:18432
	ds_read_b128 v[112:115], v45 offset:18496
	s_waitcnt lgkmcnt(1)
; #define LAS __attribute__((address_space(3)))
; #define MFMA16(a, b, c) __builtin_amdgcn_mfma_f32_16x16x32_bf16((a), (b), (c), 0, 0, 0)
; __device__ __forceinline__ void p2_block(LAS unsigned char* lds, const bf16_t* __restrict__ PROJ, bf16_t* __restrict__ ATT, bf16_t* __restrict__ SGU, const float* __restrict__ qn, const float* __restrict__ kn, ...
;     ...
;         const int t0 = (i0 >> 4) < 6 ? (i0 >> 4) : 6;
;         f32x4 sc_[10];
;         const LAS unsigned char* kbase = KS + (16 * t0 + fr) * KS_STRIDE + 16 * fq;
; #pragma unroll
;         for (int t = 0; t < 10; ++t) { const bf16x8 k0 = *(const LAS bf16x8*)(kbase + t * 16 * KS_STRIDE), k1 = *(const LAS bf16x8*)(kbase + t * 16 * KS_STRIDE + 64);
;             f32x4 z = (f32x4){0.f, 0.f, 0.f, 0.f}; z = MFMA16(k0, qf0, z); sc_[t] = MFMA16(k1, qf1, z); }
;         float mx = -1e30f;
; #pragma unroll
;         for (int t = 0; t < 10; ++t)
; #pragma unroll
;             for (int e = 0; e < 4; ++e) { const int kx = 16 * (t0 + t) + 4 * fq + e, d = kx - irow; const bool ok = (d >= 1) && (d <= 128) && (n > 0 || kx >= 128);
;                 const float v = ok ? sc_[t][e] : -1e30f; sc_[t][e] = v; mx = fmaxf(mx, v); }
;         mx = fmaxf(mx, __shfl_xor(mx, 16)); mx = fmaxf(mx, __shfl_xor(mx, 32)); mx = fmaxf(mx, sink);
	v_mfma_f32_16x16x32_bf16 v[108:111], v[108:111], v[30:33], 0
	s_waitcnt lgkmcnt(0)
	v_mfma_f32_16x16x32_bf16 v[108:111], v[112:115], v[58:61], v[108:111]
	ds_read_b128 v[112:115], v45 offset:20736
	ds_read_b128 v[116:119], v45 offset:20800
	v_add_u32_e32 v45, -2, v161
	s_waitcnt lgkmcnt(1)
	v_mfma_f32_16x16x32_bf16 v[30:33], v[112:115], v[30:33], 0
	s_waitcnt lgkmcnt(0)
	v_mfma_f32_16x16x32_bf16 v[58:61], v[116:119], v[58:61], v[30:33]
	s_nop 5
	v_sub_u32_e32 v32, v137, v73
	v_cmp_lt_u32_e32 vcc, s79, v32
	s_and_b64 s[40:41], s[50:51], vcc
	v_sub_u32_e32 v31, v73, v137
	v_cndmask_b32_e64 v30, v213, v62, s[40:41]
	v_cmp_gt_u32_e32 vcc, s84, v31
	v_sub_u32_e32 v62, v45, v82
	s_and_b64 s[42:43], s[50:51], vcc
	v_cmp_lt_u32_e32 vcc, s79, v62
	v_cndmask_b32_e64 v31, v213, v63, s[42:43]
	s_and_b64 vcc, s[50:51], vcc
	v_add_u32_e32 v63, -3, v161
	v_cndmask_b32_e32 v62, v213, v64, vcc
	v_sub_u32_e32 v64, v63, v82
	v_cmp_lt_u32_e32 vcc, s79, v64
	s_and_b64 vcc, s[50:51], vcc
	v_max3_f32 v33, v30, s52, v31
	v_cndmask_b32_e32 v64, v213, v65, vcc
	v_sub_u32_e32 v65, v161, v82
	v_add_u32_e32 v78, -16, v65
	v_cmp_lt_u32_e32 vcc, s79, v78
	s_and_b64 vcc, s[50:51], vcc
	v_subrev_u32_e32 v78, 17, v65
	v_cndmask_b32_e32 v66, v213, v66, vcc
	v_cmp_lt_u32_e32 vcc, s79, v78
	s_and_b64 vcc, s[50:51], vcc
	v_subrev_u32_e32 v78, 18, v65
	v_cndmask_b32_e32 v67, v213, v67, vcc
	v_cmp_lt_u32_e32 vcc, s79, v78
	s_and_b64 vcc, s[50:51], vcc
	v_subrev_u32_e32 v65, 19, v65
	v_cndmask_b32_e32 v68, v213, v68, vcc
	v_cmp_lt_u32_e32 vcc, s79, v65
	s_and_b64 vcc, s[50:51], vcc
	v_max3_f32 v33, v33, v62, v64
	v_cndmask_b32_e32 v65, v213, v69, vcc
	v_lshl_or_b32 v69, s4, 4, v73
	v_sub_u32_e32 v78, v161, v69
	v_cmp_lt_u32_e32 vcc, s79, v78
	s_and_b64 vcc, s[50:51], vcc
	v_sub_u32_e32 v79, v69, v161
	v_cndmask_b32_e32 v78, v213, v84, vcc
	v_cmp_gt_u32_e32 vcc, s84, v79
	s_and_b64 vcc, s[50:51], vcc
	v_sub_u32_e32 v80, v45, v69
	v_cndmask_b32_e32 v79, v213, v85, vcc
	v_cmp_lt_u32_e32 vcc, s79, v80
	s_and_b64 vcc, s[50:51], vcc
	v_sub_u32_e32 v69, v63, v69
	v_cndmask_b32_e32 v80, v213, v86, vcc
	v_cmp_lt_u32_e32 vcc, s79, v69
	s_and_b64 vcc, s[50:51], vcc
	v_sub_u32_e32 v84, v161, v83
	v_cndmask_b32_e32 v69, v213, v87, vcc
	v_cmp_lt_u32_e32 vcc, s79, v84
	v_or_b32_e32 v84, 49, v82
	s_and_b64 vcc, s[50:51], vcc
	v_sub_u32_e32 v85, v161, v84
	v_cndmask_b32_e32 v112, v213, v88, vcc
	v_cmp_lt_u32_e32 vcc, s79, v85
	v_or_b32_e32 v85, 50, v82
	s_and_b64 vcc, s[50:51], vcc
	v_sub_u32_e32 v86, v161, v85
	v_cndmask_b32_e32 v113, v213, v89, vcc
	v_cmp_lt_u32_e32 vcc, s79, v86
	v_or_b32_e32 v87, 51, v82
	s_and_b64 vcc, s[50:51], vcc
	v_sub_u32_e32 v86, v161, v87
	v_cndmask_b32_e32 v114, v213, v90, vcc
	v_cmp_lt_u32_e32 vcc, s79, v86
	s_and_b64 vcc, s[50:51], vcc
	v_lshl_or_b32 v86, s28, 4, v73
	v_sub_u32_e32 v88, v161, v86
	s_cmp_lg_u32 s6, 0
	v_cndmask_b32_e32 v115, v213, v91, vcc
	v_cmp_lt_u32_e32 vcc, s79, v88
	s_cselect_b64 s[6:7], -1, 0
	s_and_b64 vcc, vcc, s[6:7]
	v_sub_u32_e32 v88, v86, v161
	v_cndmask_b32_e32 v116, v213, v92, vcc
	v_cmp_gt_u32_e32 vcc, s84, v88
	s_and_b64 vcc, vcc, s[6:7]
	v_sub_u32_e32 v88, v45, v86
	v_cndmask_b32_e32 v117, v213, v93, vcc
	v_cmp_lt_u32_e32 vcc, s79, v88
	s_and_b64 vcc, vcc, s[6:7]
	v_sub_u32_e32 v86, v63, v86
	s_add_i32 s27, s26, 0x50
	v_cndmask_b32_e32 v118, v213, v94, vcc
	v_cmp_lt_u32_e32 vcc, s79, v86
	v_or_b32_e32 v86, s27, v73
	s_and_b64 vcc, vcc, s[6:7]
	v_sub_u32_e32 v88, v161, v86
	v_cndmask_b32_e32 v119, v213, v95, vcc
	v_cmp_lt_u32_e32 vcc, s79, v88
	s_and_b64 vcc, vcc, s[6:7]
	v_sub_u32_e32 v88, v86, v161
	v_cndmask_b32_e32 v120, v213, v96, vcc
	v_cmp_gt_u32_e32 vcc, s84, v88
	v_or_b32_e32 v89, 2, v86
	s_and_b64 vcc, vcc, s[6:7]
	v_sub_u32_e32 v88, v161, v89
	v_cndmask_b32_e32 v97, v213, v97, vcc
	v_cmp_lt_u32_e32 vcc, s79, v88
	v_or_b32_e32 v90, 3, v86
	s_and_b64 vcc, vcc, s[6:7]
	v_sub_u32_e32 v88, v161, v90
	s_add_i32 s27, s29, 6
	v_cndmask_b32_e32 v98, v213, v98, vcc
	v_cmp_lt_u32_e32 vcc, s79, v88
	v_lshl_or_b32 v88, s27, 4, v73
	s_and_b64 vcc, vcc, s[6:7]
	v_sub_u32_e32 v91, v161, v88
	v_cndmask_b32_e32 v99, v213, v99, vcc
	v_cmp_lt_u32_e32 vcc, s79, v91
	s_and_b64 vcc, vcc, s[6:7]
	v_sub_u32_e32 v91, v88, v161
	v_cndmask_b32_e32 v100, v213, v100, vcc
	v_cmp_gt_u32_e32 vcc, s84, v91
	s_and_b64 vcc, vcc, s[6:7]
	v_sub_u32_e32 v91, v45, v88
	v_cndmask_b32_e32 v101, v213, v101, vcc
	v_cmp_lt_u32_e32 vcc, s79, v91
	s_and_b64 vcc, vcc, s[6:7]
	v_sub_u32_e32 v88, v63, v88
	s_add_i32 s44, s26, 0x70
	v_cndmask_b32_e32 v102, v213, v102, vcc
	v_cmp_lt_u32_e32 vcc, s79, v88
	v_or_b32_e32 v88, s44, v73
	s_and_b64 vcc, vcc, s[6:7]
	v_sub_u32_e32 v91, v161, v88
	v_cndmask_b32_e32 v103, v213, v103, vcc
	v_cmp_lt_u32_e32 vcc, s79, v91
	s_and_b64 vcc, vcc, s[6:7]
	v_sub_u32_e32 v91, v88, v161
	v_cndmask_b32_e32 v104, v213, v104, vcc
	v_cmp_gt_u32_e32 vcc, s84, v91
	v_or_b32_e32 v91, 2, v88
	v_max3_f32 v33, v33, v66, v67
	s_and_b64 vcc, vcc, s[6:7]
	v_sub_u32_e32 v92, v161, v91
	v_max3_f32 v33, v33, v68, v65
	v_cndmask_b32_e32 v105, v213, v105, vcc
	v_cmp_lt_u32_e32 vcc, s79, v92
	v_or_b32_e32 v92, 3, v88
	v_max3_f32 v33, v33, v78, v79
	s_and_b64 vcc, vcc, s[6:7]
	v_sub_u32_e32 v93, v161, v92
	s_or_b32 s29, s29, 8
	v_max3_f32 v33, v33, v80, v69
	v_cndmask_b32_e32 v106, v213, v106, vcc
	v_cmp_lt_u32_e32 vcc, s79, v93
	v_lshl_or_b32 v93, s29, 4, v73
	v_max3_f32 v33, v33, v112, v113
	s_and_b64 vcc, vcc, s[6:7]
	v_sub_u32_e32 v94, v161, v93
	v_max3_f32 v33, v33, v114, v115
	v_cndmask_b32_e32 v107, v213, v107, vcc
	v_cmp_lt_u32_e32 vcc, s79, v94
	v_sub_u32_e32 v94, v93, v161
	v_max3_f32 v33, v33, v116, v117
	v_cndmask_b32_e32 v108, v213, v108, vcc
	v_cmp_gt_u32_e32 vcc, s84, v94
	v_sub_u32_e32 v45, v45, v93
	v_max3_f32 v33, v33, v118, v119
	v_cndmask_b32_e32 v109, v213, v109, vcc
	v_cmp_lt_u32_e32 vcc, s79, v45
	v_sub_u32_e32 v63, v63, v93
	v_or_b32_e32 v93, 0x90, v82
	v_max3_f32 v33, v33, v120, v97
	v_cndmask_b32_e32 v45, v213, v110, vcc
	v_cmp_lt_u32_e32 vcc, s79, v63
	v_sub_u32_e32 v94, v161, v93
	v_max3_f32 v33, v33, v98, v99
	v_cndmask_b32_e32 v63, v213, v111, vcc
	v_cmp_lt_u32_e32 vcc, s79, v94
	v_or_b32_e32 v94, 0x91, v82
	v_max3_f32 v33, v33, v100, v101
	v_sub_u32_e32 v95, v161, v94
	v_max3_f32 v33, v33, v102, v103
	v_cndmask_b32_e32 v58, v213, v58, vcc
	v_cmp_lt_u32_e32 vcc, s79, v95
	v_or_b32_e32 v95, 0x92, v82
	v_max3_f32 v33, v33, v104, v105
	v_sub_u32_e32 v96, v161, v95
	v_max3_f32 v33, v33, v106, v107
	v_cndmask_b32_e32 v59, v213, v59, vcc
	v_cmp_lt_u32_e32 vcc, s79, v96
	v_or_b32_e32 v96, 0x93, v82
	v_max3_f32 v33, v33, v108, v109
	v_sub_u32_e32 v110, v161, v96
	v_max3_f32 v33, v33, v45, v63
	v_cndmask_b32_e32 v60, v213, v60, vcc
	v_cmp_lt_u32_e32 vcc, s79, v110
	v_max3_f32 v33, v33, v58, v59
	s_nop 0
	v_cndmask_b32_e32 v61, v213, v61, vcc
	v_max3_f32 v33, v33, v60, v61
	ds_bpermute_b32 v110, v76, v33
	s_waitcnt lgkmcnt(0)
; __device__ __forceinline__ void p2_block(LAS unsigned char* lds, const bf16_t* __restrict__ PROJ, bf16_t* __restrict__ ATT, bf16_t* __restrict__ SGU, const float* __restrict__ qn, const float* __restrict__ kn, ...
;     ...
;         mx = fmaxf(mx, __shfl_xor(mx, 16)); mx = fmaxf(mx, __shfl_xor(mx, 32)); mx = fmaxf(mx, sink);
;         float sum = 0.f;
; #pragma unroll
;         for (int t = 0; t < 10; ++t)
; #pragma unroll
;             for (int e = 0; e < 4; ++e) { const float p = __builtin_amdgcn_exp2f((sc_[t][e] - mx) * LOG2E); sc_[t][e] = p; sum += p; }
;         sum += __shfl_xor(sum, 16); sum += __shfl_xor(sum, 32);
;         const float inv = 1.0f / (sum + __builtin_amdgcn_exp2f((sink - mx) * LOG2E));
	v_max_f32_e32 v110, v110, v110
	v_max_f32_e32 v33, v33, v110
	ds_bpermute_b32 v110, v77, v33
	s_waitcnt lgkmcnt(0)
	v_max3_f32 v33, v33, v110, v75
	v_sub_f32_e32 v30, v30, v33
	v_mul_f32_e32 v30, 0x3fb8aa3b, v30
	v_sub_f32_e32 v31, v31, v33
	v_exp_f32_e32 v30, v30
	v_mul_f32_e32 v31, 0x3fb8aa3b, v31
	v_sub_f32_e32 v62, v62, v33
	v_exp_f32_e32 v31, v31
	v_mul_f32_e32 v62, 0x3fb8aa3b, v62
	v_sub_f32_e32 v64, v64, v33
	v_exp_f32_e32 v62, v62
	v_mul_f32_e32 v64, 0x3fb8aa3b, v64
	v_sub_f32_e32 v66, v66, v33
	v_exp_f32_e32 v64, v64
	v_mul_f32_e32 v66, 0x3fb8aa3b, v66
	v_sub_f32_e32 v67, v67, v33
	v_add_f32_e32 v110, 0, v30
	v_exp_f32_e32 v66, v66
	v_mul_f32_e32 v67, 0x3fb8aa3b, v67
	v_sub_f32_e32 v68, v68, v33
	v_add_f32_e32 v110, v31, v110
	v_exp_f32_e32 v67, v67
	v_mul_f32_e32 v68, 0x3fb8aa3b, v68
	v_sub_f32_e32 v65, v65, v33
	v_add_f32_e32 v110, v62, v110
	v_exp_f32_e32 v68, v68
	v_mul_f32_e32 v65, 0x3fb8aa3b, v65
	v_sub_f32_e32 v78, v78, v33
	v_add_f32_e32 v110, v64, v110
	v_exp_f32_e32 v65, v65
	v_mul_f32_e32 v78, 0x3fb8aa3b, v78
	v_add_f32_e32 v110, v66, v110
	v_exp_f32_e32 v111, v78
	v_add_f32_e32 v110, v67, v110
	v_add_f32_e32 v110, v68, v110
	v_sub_f32_e32 v79, v79, v33
	v_add_f32_e32 v110, v65, v110
	v_mul_f32_e32 v79, 0x3fb8aa3b, v79
	v_add_f32_e32 v78, v111, v110
	v_exp_f32_e32 v110, v79
	v_sub_f32_e32 v79, v80, v33
	v_mul_f32_e32 v79, 0x3fb8aa3b, v79
	v_sub_f32_e32 v69, v69, v33
	v_exp_f32_e32 v121, v79
	v_mul_f32_e32 v69, 0x3fb8aa3b, v69
	v_exp_f32_e32 v122, v69
	v_add_f32_e32 v78, v110, v78
	v_add_f32_e32 v78, v121, v78
	v_sub_f32_e32 v58, v58, v33
	v_add_f32_e32 v69, v122, v78
	v_sub_f32_e32 v78, v112, v33
	v_mul_f32_e32 v78, 0x3fb8aa3b, v78
	v_exp_f32_e32 v112, v78
	v_sub_f32_e32 v78, v113, v33
	v_mul_f32_e32 v78, 0x3fb8aa3b, v78
	v_exp_f32_e32 v113, v78
	v_sub_f32_e32 v78, v114, v33
	v_mul_f32_e32 v78, 0x3fb8aa3b, v78
	v_exp_f32_e32 v114, v78
	v_sub_f32_e32 v78, v115, v33
	v_mul_f32_e32 v78, 0x3fb8aa3b, v78
	v_exp_f32_e32 v115, v78
	v_sub_f32_e32 v78, v116, v33
	v_mul_f32_e32 v78, 0x3fb8aa3b, v78
	v_exp_f32_e32 v116, v78
	v_sub_f32_e32 v78, v117, v33
	v_mul_f32_e32 v78, 0x3fb8aa3b, v78
	v_exp_f32_e32 v117, v78
	v_sub_f32_e32 v78, v118, v33
	v_mul_f32_e32 v78, 0x3fb8aa3b, v78
	v_exp_f32_e32 v118, v78
	v_sub_f32_e32 v78, v119, v33
	v_mul_f32_e32 v78, 0x3fb8aa3b, v78
	v_exp_f32_e32 v119, v78
	v_sub_f32_e32 v78, v120, v33
	v_mul_f32_e32 v78, 0x3fb8aa3b, v78
	v_exp_f32_e32 v120, v78
	v_sub_f32_e32 v78, v97, v33
	v_mul_f32_e32 v78, 0x3fb8aa3b, v78
	v_exp_f32_e32 v97, v78
	v_sub_f32_e32 v78, v98, v33
	v_mul_f32_e32 v78, 0x3fb8aa3b, v78
	v_exp_f32_e32 v123, v78
	v_sub_f32_e32 v78, v99, v33
	v_mul_f32_e32 v78, 0x3fb8aa3b, v78
	v_exp_f32_e32 v124, v78
	v_sub_f32_e32 v78, v100, v33
	v_mul_f32_e32 v78, 0x3fb8aa3b, v78
	v_exp_f32_e32 v125, v78
	v_sub_f32_e32 v78, v101, v33
	v_add_f32_e32 v69, v112, v69
	v_mul_f32_e32 v78, 0x3fb8aa3b, v78
	v_add_f32_e32 v69, v113, v69
	v_exp_f32_e32 v126, v78
	v_sub_f32_e32 v78, v102, v33
	v_add_f32_e32 v69, v114, v69
	v_mul_f32_e32 v78, 0x3fb8aa3b, v78
	v_add_f32_e32 v69, v115, v69
	v_exp_f32_e32 v127, v78
	v_sub_f32_e32 v78, v103, v33
	v_add_f32_e32 v69, v116, v69
	v_mul_f32_e32 v78, 0x3fb8aa3b, v78
	v_add_f32_e32 v69, v117, v69
	v_exp_f32_e32 v128, v78
	v_sub_f32_e32 v78, v104, v33
	v_add_f32_e32 v69, v118, v69
	v_mul_f32_e32 v78, 0x3fb8aa3b, v78
	v_add_f32_e32 v69, v119, v69
	v_exp_f32_e32 v129, v78
	v_sub_f32_e32 v78, v105, v33
	v_add_f32_e32 v69, v120, v69
	v_mul_f32_e32 v78, 0x3fb8aa3b, v78
	v_add_f32_e32 v69, v97, v69
	v_exp_f32_e32 v131, v78
	v_sub_f32_e32 v78, v106, v33
	v_add_f32_e32 v69, v123, v69
	v_mul_f32_e32 v78, 0x3fb8aa3b, v78
	v_add_f32_e32 v69, v124, v69
	v_exp_f32_e32 v133, v78
	v_sub_f32_e32 v78, v107, v33
	v_add_f32_e32 v69, v125, v69
	v_mul_f32_e32 v78, 0x3fb8aa3b, v78
	v_add_f32_e32 v69, v126, v69
	v_exp_f32_e32 v134, v78
	v_sub_f32_e32 v78, v108, v33
	v_add_f32_e32 v69, v127, v69
	v_mul_f32_e32 v78, 0x3fb8aa3b, v78
	v_add_f32_e32 v69, v128, v69
	v_exp_f32_e32 v135, v78
	v_sub_f32_e32 v78, v109, v33
	v_add_f32_e32 v69, v129, v69
	v_mul_f32_e32 v78, 0x3fb8aa3b, v78
	v_sub_f32_e32 v45, v45, v33
	v_mul_f32_e32 v58, 0x3fb8aa3b, v58
	v_add_f32_e32 v69, v131, v69
	v_exp_f32_e32 v136, v78
	v_mul_f32_e32 v45, 0x3fb8aa3b, v45
	v_sub_f32_e32 v63, v63, v33
	v_exp_f32_e32 v140, v58
	v_sub_f32_e32 v58, v59, v33
	v_add_f32_e32 v69, v133, v69
	v_exp_f32_e32 v138, v45
	v_mul_f32_e32 v63, 0x3fb8aa3b, v63
	v_mul_f32_e32 v58, 0x3fb8aa3b, v58
	v_add_f32_e32 v69, v134, v69
	v_exp_f32_e32 v139, v63
	v_exp_f32_e32 v141, v58
	v_sub_f32_e32 v58, v60, v33
	v_add_f32_e32 v69, v135, v69
	v_mul_f32_e32 v58, 0x3fb8aa3b, v58
	v_add_f32_e32 v69, v136, v69
	v_exp_f32_e32 v142, v58
	v_sub_f32_e32 v58, v61, v33
	v_add_f32_e32 v45, v138, v69
	v_mul_f32_e32 v58, 0x3fb8aa3b, v58
	v_add_f32_e32 v45, v139, v45
	v_exp_f32_e32 v143, v58
	v_add_f32_e32 v45, v140, v45
	v_add_f32_e32 v45, v141, v45
	v_add_f32_e32 v45, v142, v45
	v_add_f32_e32 v45, v143, v45
	ds_bpermute_b32 v58, v76, v45
	v_mad_u32_u24 v80, v137, s81, v214
	v_mad_u32_u24 v79, v137, s81, v215
	v_mad_u32_u24 v78, v137, s81, v216
	v_sub_f32_e32 v33, v75, v33
	s_waitcnt lgkmcnt(0)
	v_add_f32_e32 v45, v45, v58
	ds_bpermute_b32 v58, v77, v45
	v_mul_f32_e32 v33, 0x3fb8aa3b, v33
	v_exp_f32_e32 v33, v33
	s_waitcnt lgkmcnt(0)
; __device__ __forceinline__ unsigned cvt_pk_bf16(float lo, float hi) { unsigned r; asm volatile("v_cvt_pk_bf16_f32 %0, %1, %2" : "=v"(r) : "v"(lo), "v"(hi)); return r; }
; #define LAS __attribute__((address_space(3)))
; #define MFMA16(a, b, c) __builtin_amdgcn_mfma_f32_16x16x32_bf16((a), (b), (c), 0, 0, 0)
; __device__ __forceinline__ void p2_block(LAS unsigned char* lds, const bf16_t* __restrict__ PROJ, bf16_t* __restrict__ ATT, bf16_t* __restrict__ SGU, const float* __restrict__ qn, const float* __restrict__ kn, ...
;     ...
;         const float inv = 1.0f / (sum + __builtin_amdgcn_exp2f((sink - mx) * LOG2E));
;         f32x4 o[4];
; #pragma unroll
;         for (int dt = 0; dt < 4; ++dt) o[dt] = (f32x4){0.f, 0.f, 0.f, 0.f};
; #pragma unroll
;         for (int j = 0; j < 5; ++j) {
;             u32x4 pw; pw.x = cvt_pk_bf16(sc_[2 * j][0], sc_[2 * j][1]); pw.y = cvt_pk_bf16(sc_[2 * j][2], sc_[2 * j][3]); pw.z = cvt_pk_bf16(sc_[2 * j + 1][0], sc_[2 * j + 1][1]); pw.w = cvt_pk_bf16(sc_[2 * j + 1][2], sc_[2 * j + 1][3]);
;             const bf16x8 pf = __builtin_bit_cast(bf16x8, pw);
; #pragma unroll
;             for (int dt = 0; dt < 4; ++dt) { const LAS unsigned char* vb = VT + (16 * dt + fr) * VT_STRIDE + (16 * (t0 + 2 * j) + 4 * fq) * 2;
;                 const u32x2 va = *(const LAS u32x2*)vb, vc = *(const LAS u32x2*)(vb + 32); u32x4 vw; vw.x = va.x; vw.y = va.y; vw.z = vc.x; vw.w = vc.y;
;                 o[dt] = MFMA16(__builtin_bit_cast(bf16x8, vw), pf, o[dt]); }
;         }
	v_add_f32_e32 v45, v45, v58
	v_cvt_pk_bf16_f32 v58, v30, v31
	v_lshl_add_u32 v30, s26, 1, v74
	v_mad_u32_u24 v31, v137, s81, v30
	v_add_u32_e32 v31, 0x9000, v31
	v_cvt_pk_bf16_f32 v59, v62, v64
	v_cvt_pk_bf16_f32 v60, v66, v67
	v_cvt_pk_bf16_f32 v61, v68, v65
	ds_read2_b64 v[62:65], v31 offset1:4
	v_add_u32_e32 v31, v30, v80
	v_add_u32_e32 v31, 0x9000, v31
	ds_read2_b64 v[66:69], v31 offset1:4
	v_add_u32_e32 v31, v30, v79
	v_add_u32_e32 v30, v30, v78
	v_add_u32_e32 v31, 0x9000, v31
	v_add_u32_e32 v30, 0x9000, v30
	ds_read2_b64 v[98:101], v31 offset1:4
	ds_read2_b64 v[102:105], v30 offset1:4
	v_lshl_add_u32 v30, s4, 5, v74
	v_mad_u32_u24 v31, v137, s81, v30
	v_add_u32_e32 v31, 0x9000, v31
	s_waitcnt lgkmcnt(3)
	v_mfma_f32_16x16x32_bf16 v[62:65], v[62:65], v[58:61], 0
	v_add_f32_e32 v33, v33, v45
	v_mov_b32_e32 v45, s49
	s_or_b32 s4, s26, 16
	s_waitcnt lgkmcnt(2)
	v_mfma_f32_16x16x32_bf16 v[66:69], v[66:69], v[58:61], 0
	s_lshr_b32 s49, s4, 4
	s_waitcnt lgkmcnt(1)
	v_mfma_f32_16x16x32_bf16 v[98:101], v[98:101], v[58:61], 0
	s_waitcnt lgkmcnt(0)
	v_mfma_f32_16x16x32_bf16 v[58:61], v[102:105], v[58:61], 0
	v_cvt_pk_bf16_f32 v102, v111, v110
	v_cvt_pk_bf16_f32 v103, v121, v122
	v_cvt_pk_bf16_f32 v104, v112, v113
	v_cvt_pk_bf16_f32 v105, v114, v115
	ds_read2_b64 v[106:109], v31 offset1:4
	v_add_u32_e32 v31, v30, v80
	v_add_u32_e32 v31, 0x9000, v31
	s_waitcnt lgkmcnt(0)
	v_mfma_f32_16x16x32_bf16 v[62:65], v[106:109], v[102:105], v[62:65]
	ds_read2_b64 v[106:109], v31 offset1:4
	v_add_u32_e32 v31, v30, v79
	v_add_u32_e32 v31, 0x9000, v31
	s_waitcnt lgkmcnt(0)
	v_mfma_f32_16x16x32_bf16 v[66:69], v[106:109], v[102:105], v[66:69]
	ds_read2_b64 v[106:109], v31 offset1:4
	v_add_u32_e32 v30, v30, v78
	v_add_u32_e32 v30, 0x9000, v30
	s_waitcnt lgkmcnt(0)
	v_mfma_f32_16x16x32_bf16 v[98:101], v[106:109], v[102:105], v[98:101]
	ds_read2_b64 v[106:109], v30 offset1:4
	v_lshl_add_u32 v30, s28, 5, v74
	v_mad_u32_u24 v31, v137, s81, v30
	v_add_u32_e32 v31, 0x9000, v31
	s_waitcnt lgkmcnt(0)
	v_mfma_f32_16x16x32_bf16 v[58:61], v[106:109], v[102:105], v[58:61]
	v_cvt_pk_bf16_f32 v102, v116, v117
	v_cvt_pk_bf16_f32 v103, v118, v119
	v_cvt_pk_bf16_f32 v104, v120, v97
	v_cvt_pk_bf16_f32 v105, v123, v124
	ds_read2_b64 v[106:109], v31 offset1:4
	v_add_u32_e32 v31, v30, v80
	v_add_u32_e32 v31, 0x9000, v31
	s_waitcnt lgkmcnt(0)
	v_mfma_f32_16x16x32_bf16 v[62:65], v[106:109], v[102:105], v[62:65]
	ds_read2_b64 v[106:109], v31 offset1:4
	v_add_u32_e32 v31, v30, v79
	v_add_u32_e32 v31, 0x9000, v31
	s_waitcnt lgkmcnt(0)
	v_mfma_f32_16x16x32_bf16 v[66:69], v[106:109], v[102:105], v[66:69]
	ds_read2_b64 v[106:109], v31 offset1:4
	v_add_u32_e32 v30, v30, v78
	v_add_u32_e32 v30, 0x9000, v30
	s_waitcnt lgkmcnt(0)
	v_mfma_f32_16x16x32_bf16 v[98:101], v[106:109], v[102:105], v[98:101]
	ds_read2_b64 v[106:109], v30 offset1:4
	v_lshl_add_u32 v30, s27, 5, v74
	v_mad_u32_u24 v31, v137, s81, v30
	v_add_u32_e32 v31, 0x9000, v31
	s_waitcnt lgkmcnt(0)
	v_mfma_f32_16x16x32_bf16 v[58:61], v[106:109], v[102:105], v[58:61]
	v_cvt_pk_bf16_f32 v102, v125, v126
	v_cvt_pk_bf16_f32 v103, v127, v128
	v_cvt_pk_bf16_f32 v104, v129, v131
	v_cvt_pk_bf16_f32 v105, v133, v134
	ds_read2_b64 v[106:109], v31 offset1:4
	v_add_u32_e32 v31, v30, v80
	v_add_u32_e32 v31, 0x9000, v31
	s_waitcnt lgkmcnt(0)
	v_mfma_f32_16x16x32_bf16 v[62:65], v[106:109], v[102:105], v[62:65]
	ds_read2_b64 v[106:109], v31 offset1:4
	v_add_u32_e32 v31, v30, v79
	v_add_u32_e32 v31, 0x9000, v31
	s_waitcnt lgkmcnt(0)
	v_mfma_f32_16x16x32_bf16 v[66:69], v[106:109], v[102:105], v[66:69]
	ds_read2_b64 v[106:109], v31 offset1:4
	v_add_u32_e32 v30, v30, v78
	v_add_u32_e32 v30, 0x9000, v30
	s_waitcnt lgkmcnt(0)
	v_mfma_f32_16x16x32_bf16 v[98:101], v[106:109], v[102:105], v[98:101]
	ds_read2_b64 v[106:109], v30 offset1:4
	v_lshl_add_u32 v30, s29, 5, v74
	v_mad_u32_u24 v31, v137, s81, v30
	v_add_u32_e32 v31, 0x9000, v31
	s_waitcnt lgkmcnt(0)
	v_mfma_f32_16x16x32_bf16 v[58:61], v[106:109], v[102:105], v[58:61]
	v_cvt_pk_bf16_f32 v102, v135, v136
	v_cvt_pk_bf16_f32 v103, v138, v139
	v_cvt_pk_bf16_f32 v104, v140, v141
	v_cvt_pk_bf16_f32 v105, v142, v143
	ds_read2_b64 v[106:109], v31 offset1:4
	v_add_u32_e32 v31, v30, v80
	v_add_u32_e32 v31, 0x9000, v31
	s_waitcnt lgkmcnt(0)
	v_mfma_f32_16x16x32_bf16 v[62:65], v[106:109], v[102:105], v[62:65]
	ds_read2_b64 v[106:109], v31 offset1:4
	v_add_u32_e32 v31, v30, v79
	v_add_u32_e32 v31, 0x9000, v31
	s_waitcnt lgkmcnt(0)
	v_mfma_f32_16x16x32_bf16 v[66:69], v[106:109], v[102:105], v[66:69]
	ds_read2_b64 v[106:109], v31 offset1:4
	v_add_u32_e32 v30, v30, v78
	v_add_u32_e32 v30, 0x9000, v30
	s_waitcnt lgkmcnt(0)
	v_mfma_f32_16x16x32_bf16 v[98:101], v[106:109], v[102:105], v[98:101]
	ds_read2_b64 v[106:109], v30 offset1:4
	v_div_scale_f32 v30, s[28:29], v33, v33, 1.0
	v_rcp_f32_e32 v31, v30
	s_waitcnt lgkmcnt(0)
; __device__ __forceinline__ void p2_block(LAS unsigned char* lds, const bf16_t* __restrict__ PROJ, bf16_t* __restrict__ ATT, bf16_t* __restrict__ SGU, const float* __restrict__ qn, const float* __restrict__ kn, ...
;     ...
;         const int i0 = rbase + 16 * c, irow = i0 + fr, pos = n * 128 + irow; const size_t grow = (size_t)b * pg8::SEQ + pos;
;         bf16x8 qf0, qf1;
;         {
;             float x1[8], x2[8]; unpack8(qa[c], x1); unpack8(qb[c], x2);
;             float ss = 0.f;
; #pragma unroll
;             for (int j = 0; j < 8; ++j) ss += x1[j] * x1[j] + x2[j] * x2[j];
;             ss += __shfl_xor(ss, 16); ss += __shfl_xor(ss, 32);
;             const float rinv = rsqrtf(ss * (1.0f / 64.0f) + pg8::EPS) * 0.125f;
;             const float* cp = COS + pos * 32 + 8 * fq; const float* sp = SIN + pos * 32 + 8 * fq;
;             float o1[8], o2[8];
; #pragma unroll
;             for (int j = 0; j < 8; ++j) { const float a1 = x1[j] * rinv * qn[8 * fq + j], a2 = x2[j] * rinv * qn[32 + 8 * fq + j], cc = cp[j], sn = sp[j]; o1[j] = a1 * cc - a2 * sn; o2[j] = a2 * cc + a1 * sn; }
;             u32x4 w0, w1;
;     ...
;         const float inv = 1.0f / (sum + __builtin_amdgcn_exp2f((sink - mx) * LOG2E));
;         f32x4 o[4];
; #pragma unroll
;         for (int dt = 0; dt < 4; ++dt) o[dt] = (f32x4){0.f, 0.f, 0.f, 0.f};
; #pragma unroll
;         for (int j = 0; j < 5; ++j) {
;             u32x4 pw; pw.x = cvt_pk_bf16(sc_[2 * j][0], sc_[2 * j][1]); pw.y = cvt_pk_bf16(sc_[2 * j][2], sc_[2 * j][3]); pw.z = cvt_pk_bf16(sc_[2 * j + 1][0], sc_[2 * j + 1][1]); pw.w = cvt_pk_bf16(sc_[2 * j + 1][2], sc_[2 * j + 1][3]);
;             const bf16x8 pf = __builtin_bit_cast(bf16x8, pw);
; #pragma unroll
;             for (int dt = 0; dt < 4; ++dt) { const LAS unsigned char* vb = VT + (16 * dt + fr) * VT_STRIDE + (16 * (t0 + 2 * j) + 4 * fq) * 2;
;                 const u32x2 va = *(const LAS u32x2*)vb, vc = *(const LAS u32x2*)(vb + 32); u32x4 vw; vw.x = va.x; vw.y = va.y; vw.z = vc.x; vw.w = vc.y;
;                 o[dt] = MFMA16(__builtin_bit_cast(bf16x8, vw), pf, o[dt]); }
;         }
;         bf16_t* op = ATT + grow * 1024 + hq * 64 + 4 * fq;
; #pragma unroll
;         for (int dt = 0; dt < 4; ++dt) { u32x2 ow; ow.x = cvt_pk_bf16(o[dt][0] * inv, o[dt][1] * inv); ow.y = cvt_pk_bf16(o[dt][2] * inv, o[dt][3] * inv); *(u32x2*)(op + 16 * dt) = ow; }
	v_mfma_f32_16x16x32_bf16 v[58:61], v[106:109], v[102:105], v[58:61]
	v_fma_f32 v97, -v30, v31, 1.0
	v_fmac_f32_e32 v31, v97, v31
	v_div_scale_f32 v97, vcc, 1.0, v33, 1.0
	v_mul_f32_e32 v102, v97, v31
	v_fma_f32 v103, -v30, v102, v97
	v_fmac_f32_e32 v102, v103, v31
	v_fma_f32 v30, -v30, v102, v97
	v_div_fmas_f32 v30, v30, v31, v102
	v_div_fixup_f32 v33, v30, v33, 1.0
	v_lshlrev_b64 v[30:31], 11, v[44:45]
	v_mul_f32_e32 v44, v33, v62
	v_mul_f32_e32 v62, v33, v63
	v_lshl_add_u64 v[30:31], v[42:43], 0, v[30:31]
	v_cvt_pk_bf16_f32 v62, v44, v62
	v_mul_f32_e32 v44, v33, v64
	v_mul_f32_e32 v63, v33, v65
	v_cvt_pk_bf16_f32 v63, v44, v63
	global_store_dwordx2 v[30:31], v[62:63], off
	v_mul_f32_e32 v44, v33, v66
	v_mul_f32_e32 v62, v33, v67
	v_cvt_pk_bf16_f32 v62, v44, v62
	v_mul_f32_e32 v44, v33, v68
	v_mul_f32_e32 v63, v33, v69
	v_cvt_pk_bf16_f32 v63, v44, v63
	global_store_dwordx2 v[30:31], v[62:63], off offset:32
	v_mul_f32_e32 v44, v33, v98
	v_mul_f32_e32 v62, v33, v99
	v_cvt_pk_bf16_f32 v62, v44, v62
	v_mul_f32_e32 v44, v33, v100
	v_mul_f32_e32 v63, v33, v101
	v_cvt_pk_bf16_f32 v63, v44, v63
	v_mul_f32_e32 v44, v33, v58
	v_mul_f32_e32 v58, v33, v59
	global_store_dwordx2 v[30:31], v[62:63], off offset:64
	v_cvt_pk_bf16_f32 v58, v44, v58
	v_mul_f32_e32 v44, v33, v60
	v_mul_f32_e32 v33, v33, v61
	v_cvt_pk_bf16_f32 v59, v44, v33
	v_or_b32_e32 v44, s4, v137
	v_or_b32_e32 v33, s17, v44
	global_store_dwordx2 v[30:31], v[58:59], off offset:96
	v_lshlrev_b32_e32 v30, 7, v33
	v_mov_b32_e32 v31, v1
	v_lshl_add_u64 v[62:63], v[46:47], 0, v[30:31]
	v_lshl_add_u64 v[30:31], v[48:49], 0, v[30:31]
	global_load_dwordx4 v[58:61], v[62:63], off offset:16
	s_nop 0
	global_load_dwordx4 v[62:65], v[62:63], off
	s_nop 0
	global_load_dwordx4 v[66:69], v[30:31], off offset:16
	global_load_dwordx4 v[98:101], v[30:31], off
	v_lshlrev_b32_e32 v30, 16, v29
	v_and_b32_e32 v104, 0xffff0000, v29
	v_lshlrev_b32_e32 v31, 16, v25
	v_and_b32_e32 v105, 0xffff0000, v25
	v_mov_b32_e32 v108, v104
	v_mov_b32_e32 v109, v30
	v_mov_b32_e32 v106, v105
	v_mov_b32_e32 v107, v31
	v_pk_mul_f32 v[108:109], v[108:109], v[108:109]
	v_and_b32_e32 v25, 0xffff0000, v24
	v_pk_fma_f32 v[106:107], v[106:107], v[106:107], v[108:109]
	v_lshlrev_b32_e32 v109, 16, v24
	v_lshlrev_b32_e32 v108, 16, v28
	v_and_b32_e32 v24, 0xffff0000, v28
	v_mov_b32_e32 v112, v24
	v_mov_b32_e32 v113, v108
	v_mov_b32_e32 v28, v25
	v_mov_b32_e32 v29, v109
	v_pk_mul_f32 v[112:113], v[112:113], v[112:113]
	v_and_b32_e32 v116, 0xffff0000, v27
	v_pk_fma_f32 v[28:29], v[28:29], v[28:29], v[112:113]
	v_lshlrev_b32_e32 v112, 16, v27
	v_lshlrev_b32_e32 v113, 16, v23
	v_and_b32_e32 v117, 0xffff0000, v23
	v_mov_b32_e32 v120, v116
	v_mov_b32_e32 v121, v112
	v_mov_b32_e32 v118, v117
	v_mov_b32_e32 v119, v113
	v_pk_mul_f32 v[120:121], v[120:121], v[120:121]
	v_and_b32_e32 v23, 0xffff0000, v22
	v_pk_fma_f32 v[118:119], v[118:119], v[118:119], v[120:121]
	v_lshlrev_b32_e32 v121, 16, v22
	v_lshlrev_b32_e32 v120, 16, v26
	v_and_b32_e32 v22, 0xffff0000, v26
	v_mov_b32_e32 v124, v120
	v_mov_b32_e32 v125, v22
	v_mov_b32_e32 v26, v121
	v_mov_b32_e32 v27, v23
	v_pk_mul_f32 v[124:125], v[124:125], v[124:125]
	s_or_b32 s27, s49, 2
	v_pk_fma_f32 v[26:27], v[26:27], v[26:27], v[124:125]
	s_add_i32 s28, s26, 64
	v_add_f32_e32 v26, v26, v27
	v_add_f32_e32 v26, v119, v26
	v_add_f32_e32 v26, v118, v26
	v_add_f32_e32 v26, v29, v26
	v_add_f32_e32 v26, v28, v26
	v_add_f32_e32 v26, v107, v26
	v_add_f32_e32 v26, v106, v26
	ds_bpermute_b32 v27, v76, v26
	s_add_i32 s29, s26, 0x60
	s_waitcnt lgkmcnt(0)
	v_add_f32_e32 v26, v26, v27
	ds_bpermute_b32 v27, v77, v26
	s_waitcnt lgkmcnt(0)
	v_add_f32_e32 v26, v26, v27
	v_fmamk_f32 v26, v26, 0x3c800000, v209
	v_cmp_gt_f32_e32 vcc, s82, v26
	v_mul_f32_e32 v27, 0x4b800000, v26
	s_waitcnt vmcnt(3)
	v_mov_b32_e32 v110, v58
	v_cndmask_b32_e32 v26, v26, v27, vcc
	v_rsq_f32_e32 v26, v26
	s_waitcnt vmcnt(0)
	v_mov_b32_e32 v106, v98
	v_mov_b32_e32 v107, v62
	v_mov_b32_e32 v122, v62
	v_mul_f32_e32 v27, 0x45800000, v26
	v_cndmask_b32_e32 v26, v26, v27, vcc
	v_mul_f32_e32 v26, 0x3e000000, v26
	v_pk_mul_f32 v[28:29], v[26:27], v[120:121] op_sel_hi:[0,1]
	v_pk_mul_f32 v[28:29], v[56:57], v[28:29]
	v_mov_b32_e32 v123, v98
	v_pk_mul_f32 v[106:107], v[106:107], v[28:29]
	v_pk_mul_f32 v[28:29], v[122:123], v[28:29]
	v_sub_f32_e32 v27, v107, v106
	v_pk_mul_f32 v[22:23], v[26:27], v[22:23] op_sel_hi:[0,1]
	v_pk_mul_f32 v[22:23], v[18:19], v[22:23]
	v_mov_b32_e32 v62, v99
	v_mov_b32_e32 v98, v63
	v_add_f32_e32 v97, v28, v29
	v_pk_mul_f32 v[28:29], v[62:63], v[22:23]
	v_pk_mul_f32 v[22:23], v[98:99], v[22:23]
	v_mov_b32_e32 v114, v64
	v_add_f32_e32 v63, v22, v23
	v_pk_mul_f32 v[22:23], v[26:27], v[112:113] op_sel_hi:[0,1]
	v_mov_b32_e32 v115, v100
	v_sub_f32_e32 v62, v29, v28
	v_pk_mul_f32 v[22:23], v[54:55], v[22:23]
	v_mov_b32_e32 v28, v100
	v_mov_b32_e32 v29, v64
	v_pk_mul_f32 v[28:29], v[28:29], v[22:23]
	v_pk_mul_f32 v[22:23], v[114:115], v[22:23]
	v_mov_b32_e32 v64, v101
	v_add_f32_e32 v99, v22, v23
	v_pk_mul_f32 v[22:23], v[26:27], v[116:117] op_sel_hi:[0,1]
	v_pk_mul_f32 v[22:23], v[20:21], v[22:23]
	v_mov_b32_e32 v100, v65
	v_sub_f32_e32 v98, v29, v28
	v_pk_mul_f32 v[28:29], v[64:65], v[22:23]
	v_pk_mul_f32 v[22:23], v[100:101], v[22:23]
	v_mov_b32_e32 v111, v66
	v_add_f32_e32 v65, v22, v23
	v_pk_mul_f32 v[22:23], v[26:27], v[108:109] op_sel_hi:[0,1]
	v_sub_f32_e32 v64, v29, v28
	v_pk_mul_f32 v[22:23], v[52:53], v[22:23]
	v_mov_b32_e32 v28, v66
	v_mov_b32_e32 v29, v58
	v_pk_mul_f32 v[28:29], v[28:29], v[22:23]
	v_pk_mul_f32 v[22:23], v[110:111], v[22:23]
	v_sub_f32_e32 v28, v29, v28
	v_add_f32_e32 v29, v22, v23
	v_pk_mul_f32 v[22:23], v[26:27], v[24:25] op_sel_hi:[0,1]
	v_pk_mul_f32 v[22:23], v[14:15], v[22:23]
	v_mov_b32_e32 v58, v67
	v_mov_b32_e32 v66, v59
	v_pk_mul_f32 v[24:25], v[58:59], v[22:23]
	v_pk_mul_f32 v[22:23], v[66:67], v[22:23]
	v_mov_b32_e32 v102, v60
	v_add_f32_e32 v59, v22, v23
	v_pk_mul_f32 v[22:23], v[26:27], v[30:31] op_sel_hi:[0,1]
	v_mov_b32_e32 v103, v68
	v_sub_f32_e32 v58, v25, v24
	v_pk_mul_f32 v[22:23], v[50:51], v[22:23]
	v_mov_b32_e32 v24, v68
	v_mov_b32_e32 v25, v60
	v_pk_mul_f32 v[24:25], v[22:23], v[24:25]
	v_pk_mul_f32 v[22:23], v[22:23], v[102:103]
	v_mov_b32_e32 v60, v69
	v_add_f32_e32 v31, v22, v23
	v_pk_mul_f32 v[22:23], v[26:27], v[104:105] op_sel_hi:[0,1]
	v_pk_mul_f32 v[22:23], v[16:17], v[22:23]
	v_sub_f32_e32 v30, v25, v24
	v_pk_mul_f32 v[24:25], v[22:23], v[60:61]
	v_mov_b32_e32 v68, v61
	v_sub_f32_e32 v25, v25, v24
	v_pk_mul_f32 v[22:23], v[22:23], v[68:69]
	s_nop 0
	v_add_f32_e32 v60, v22, v23
	v_cvt_pk_bf16_f32 v22, v27, v62
	v_cvt_pk_bf16_f32 v23, v98, v64
	v_cvt_pk_bf16_f32 v24, v28, v58
	v_cvt_pk_bf16_f32 v25, v30, v25
	v_mad_u32_u24 v30, v44, s59, v81
	v_cvt_pk_bf16_f32 v26, v97, v63
	v_cvt_pk_bf16_f32 v27, v99, v65
	v_cvt_pk_bf16_f32 v28, v29, v59
	v_cvt_pk_bf16_f32 v29, v31, v60
	ds_read_b128 v[58:61], v30
	ds_read_b128 v[62:65], v30 offset:64
	s_waitcnt lgkmcnt(1)
; #define LAS __attribute__((address_space(3)))
; #define MFMA16(a, b, c) __builtin_amdgcn_mfma_f32_16x16x32_bf16((a), (b), (c), 0, 0, 0)
; __device__ __forceinline__ void p2_block(LAS unsigned char* lds, const bf16_t* __restrict__ PROJ, bf16_t* __restrict__ ATT, bf16_t* __restrict__ SGU, const float* __restrict__ qn, const float* __restrict__ kn, ...
;     ...
;         const int t0 = (i0 >> 4) < 6 ? (i0 >> 4) : 6;
;         f32x4 sc_[10];
;         const LAS unsigned char* kbase = KS + (16 * t0 + fr) * KS_STRIDE + 16 * fq;
; #pragma unroll
;         for (int t = 0; t < 10; ++t) { const bf16x8 k0 = *(const LAS bf16x8*)(kbase + t * 16 * KS_STRIDE), k1 = *(const LAS bf16x8*)(kbase + t * 16 * KS_STRIDE + 64);
;             f32x4 z = (f32x4){0.f, 0.f, 0.f, 0.f}; z = MFMA16(k0, qf0, z); sc_[t] = MFMA16(k1, qf1, z); }
;         float mx = -1e30f;
; #pragma unroll
;         for (int t = 0; t < 10; ++t)
; #pragma unroll
;             for (int e = 0; e < 4; ++e) { const int kx = 16 * (t0 + t) + 4 * fq + e, d = kx - irow; const bool ok = (d >= 1) && (d <= 128) && (n > 0 || kx >= 128);
;                 const float v = ok ? sc_[t][e] : -1e30f; sc_[t][e] = v; mx = fmaxf(mx, v); }
	v_mfma_f32_16x16x32_bf16 v[58:61], v[58:61], v[22:25], 0
	v_sub_u32_e32 v31, v44, v82
	s_waitcnt lgkmcnt(0)
	v_mfma_f32_16x16x32_bf16 v[58:61], v[62:65], v[26:29], v[58:61]
	ds_read_b128 v[62:65], v30 offset:2304
	ds_read_b128 v[66:69], v30 offset:2368
	s_waitcnt lgkmcnt(1)
	v_mfma_f32_16x16x32_bf16 v[62:65], v[62:65], v[22:25], 0
	s_waitcnt lgkmcnt(0)
	v_mfma_f32_16x16x32_bf16 v[62:65], v[66:69], v[26:29], v[62:65]
	ds_read_b128 v[66:69], v30 offset:4608
	ds_read_b128 v[98:101], v30 offset:4672
	s_waitcnt lgkmcnt(1)
	v_mfma_f32_16x16x32_bf16 v[66:69], v[66:69], v[22:25], 0
	s_waitcnt lgkmcnt(0)
	v_mfma_f32_16x16x32_bf16 v[66:69], v[98:101], v[26:29], v[66:69]
	ds_read_b128 v[98:101], v30 offset:6912
	ds_read_b128 v[102:105], v30 offset:6976
	s_waitcnt lgkmcnt(1)
	v_mfma_f32_16x16x32_bf16 v[98:101], v[98:101], v[22:25], 0
	s_waitcnt lgkmcnt(0)
	v_mfma_f32_16x16x32_bf16 v[98:101], v[102:105], v[26:29], v[98:101]
	ds_read_b128 v[102:105], v30 offset:9216
	ds_read_b128 v[106:109], v30 offset:9280
	s_waitcnt lgkmcnt(1)
	v_mfma_f32_16x16x32_bf16 v[102:105], v[102:105], v[22:25], 0
	s_waitcnt lgkmcnt(0)
	v_mfma_f32_16x16x32_bf16 v[102:105], v[106:109], v[26:29], v[102:105]
	ds_read_b128 v[106:109], v30 offset:11520
	ds_read_b128 v[110:113], v30 offset:11584
	s_waitcnt lgkmcnt(1)
	v_mfma_f32_16x16x32_bf16 v[106:109], v[106:109], v[22:25], 0
	s_waitcnt lgkmcnt(0)
	v_mfma_f32_16x16x32_bf16 v[106:109], v[110:113], v[26:29], v[106:109]
	ds_read_b128 v[110:113], v30 offset:13824
	ds_read_b128 v[114:117], v30 offset:13888
	s_waitcnt lgkmcnt(1)
	v_mfma_f32_16x16x32_bf16 v[110:113], v[110:113], v[22:25], 0
	s_waitcnt lgkmcnt(0)
	v_mfma_f32_16x16x32_bf16 v[110:113], v[114:117], v[26:29], v[110:113]
	ds_read_b128 v[114:117], v30 offset:16128
	ds_read_b128 v[118:121], v30 offset:16192
	s_waitcnt lgkmcnt(1)
	v_mfma_f32_16x16x32_bf16 v[114:117], v[114:117], v[22:25], 0
	s_waitcnt lgkmcnt(0)
	v_mfma_f32_16x16x32_bf16 v[114:117], v[118:121], v[26:29], v[114:117]
	ds_read_b128 v[118:121], v30 offset:18432
	ds_read_b128 v[122:125], v30 offset:18496
	s_waitcnt lgkmcnt(1)
	v_mfma_f32_16x16x32_bf16 v[118:121], v[118:121], v[22:25], 0
	s_waitcnt lgkmcnt(0)
	v_mfma_f32_16x16x32_bf16 v[118:121], v[122:125], v[26:29], v[118:121]
	ds_read_b128 v[122:125], v30 offset:20736
	ds_read_b128 v[126:129], v30 offset:20800
	v_add_u32_e32 v30, 0x7d, v32
	s_waitcnt lgkmcnt(1)
	v_mfma_f32_16x16x32_bf16 v[22:25], v[122:125], v[22:25], 0
	s_waitcnt lgkmcnt(0)
	v_mfma_f32_16x16x32_bf16 v[22:25], v[126:129], v[26:29], v[22:25]
	v_add_u32_e32 v29, 0x7e, v32
	v_cmp_gt_u32_e32 vcc, s84, v29
	s_and_b64 s[44:45], s[50:51], vcc
	v_cmp_gt_u32_e32 vcc, s84, v30
	v_add_u32_e32 v32, 0x60, v31
	s_and_b64 s[46:47], s[50:51], vcc
	v_cmp_gt_u32_e32 vcc, s84, v32
	v_cndmask_b32_e64 v26, v213, v58, s[40:41]
	s_and_b64 vcc, s[50:51], vcc
	v_add_u32_e32 v58, 0x5f, v31
	v_cndmask_b32_e32 v32, v213, v62, vcc
	v_cmp_gt_u32_e32 vcc, s84, v58
	v_cndmask_b32_e64 v27, v213, v59, s[42:43]
	s_and_b64 vcc, s[50:51], vcc
	v_add_u32_e32 v59, 0x5e, v31
	v_cndmask_b32_e32 v58, v213, v63, vcc
	v_cmp_gt_u32_e32 vcc, s84, v59
	v_cndmask_b32_e64 v29, v213, v60, s[44:45]
	s_and_b64 vcc, s[50:51], vcc
	v_add_u32_e32 v60, 0x5d, v31
	v_cndmask_b32_e64 v30, v213, v61, s[46:47]
	v_cndmask_b32_e32 v59, v213, v64, vcc
	v_cmp_gt_u32_e32 vcc, s84, v60
	v_lshl_or_b32 v61, s27, 4, v73
	s_and_b64 vcc, s[50:51], vcc
	v_sub_u32_e32 v62, v44, v61
	v_cndmask_b32_e32 v60, v213, v65, vcc
	v_cmp_lt_u32_e32 vcc, s79, v62
	s_and_b64 vcc, s[50:51], vcc
	v_sub_u32_e32 v63, v61, v44
	v_cndmask_b32_e32 v62, v213, v66, vcc
	v_cmp_gt_u32_e32 vcc, s84, v63
	v_add_u32_e32 v64, -2, v44
	s_and_b64 vcc, s[50:51], vcc
	v_sub_u32_e32 v65, v64, v61
	v_cndmask_b32_e32 v63, v213, v67, vcc
	v_cmp_lt_u32_e32 vcc, s79, v65
	v_add_u32_e32 v66, -3, v44
	s_and_b64 vcc, s[50:51], vcc
	v_sub_u32_e32 v61, v66, v61
	v_cndmask_b32_e32 v65, v213, v68, vcc
	v_cmp_lt_u32_e32 vcc, s79, v61
	v_or_b32_e32 v67, s28, v73
	s_and_b64 vcc, s[50:51], vcc
	v_sub_u32_e32 v68, v44, v67
	v_cndmask_b32_e32 v61, v213, v69, vcc
	v_cmp_lt_u32_e32 vcc, s79, v68
	s_and_b64 vcc, vcc, s[6:7]
	v_sub_u32_e32 v67, v67, v44
	v_cndmask_b32_e32 v69, v213, v98, vcc
	v_cmp_gt_u32_e32 vcc, s84, v67
	s_and_b64 vcc, vcc, s[6:7]
	v_add_u32_e32 v97, 0x7e, v68
	v_cndmask_b32_e32 v67, v213, v99, vcc
	v_cmp_gt_u32_e32 vcc, s84, v97
	s_and_b64 vcc, vcc, s[6:7]
	v_add_u32_e32 v68, 0x7d, v68
	s_add_i32 s28, s49, 4
	v_cndmask_b32_e32 v97, v213, v100, vcc
	v_cmp_gt_u32_e32 vcc, s84, v68
	v_lshl_or_b32 v98, s28, 4, v73
	s_and_b64 vcc, vcc, s[6:7]
	v_sub_u32_e32 v99, v44, v98
	v_cndmask_b32_e32 v68, v213, v101, vcc
	v_cmp_lt_u32_e32 vcc, s79, v99
	s_and_b64 vcc, vcc, s[6:7]
	v_sub_u32_e32 v100, v98, v44
	v_cndmask_b32_e32 v99, v213, v102, vcc
	v_cmp_gt_u32_e32 vcc, s84, v100
	s_and_b64 vcc, vcc, s[6:7]
	v_sub_u32_e32 v101, v64, v98
	v_cndmask_b32_e32 v100, v213, v103, vcc
	v_cmp_lt_u32_e32 vcc, s79, v101
	s_and_b64 vcc, vcc, s[6:7]
	v_sub_u32_e32 v98, v66, v98
	v_cndmask_b32_e32 v101, v213, v104, vcc
	v_cmp_lt_u32_e32 vcc, s79, v98
	v_or_b32_e32 v102, s29, v73
	s_and_b64 vcc, vcc, s[6:7]
	v_sub_u32_e32 v103, v44, v102
	v_cndmask_b32_e32 v98, v213, v105, vcc
	v_cmp_lt_u32_e32 vcc, s79, v103
	s_and_b64 vcc, vcc, s[6:7]
	v_sub_u32_e32 v102, v102, v44
	v_cndmask_b32_e32 v104, v213, v106, vcc
	v_cmp_gt_u32_e32 vcc, s84, v102
	s_and_b64 vcc, vcc, s[6:7]
	v_add_u32_e32 v105, 0x7e, v103
	v_cndmask_b32_e32 v102, v213, v107, vcc
	v_cmp_gt_u32_e32 vcc, s84, v105
	s_and_b64 vcc, vcc, s[6:7]
	v_add_u32_e32 v103, 0x7d, v103
	s_add_i32 s29, s49, 6
	v_cndmask_b32_e32 v105, v213, v108, vcc
	v_cmp_gt_u32_e32 vcc, s84, v103
; __device__ __forceinline__ void p2_block(LAS unsigned char* lds, const bf16_t* __restrict__ PROJ, bf16_t* __restrict__ ATT, bf16_t* __restrict__ SGU, const float* __restrict__ qn, const float* __restrict__ kn, ...
;     ...
;         float mx = -1e30f;
; #pragma unroll
;         for (int t = 0; t < 10; ++t)
; #pragma unroll
;             for (int e = 0; e < 4; ++e) { const int kx = 16 * (t0 + t) + 4 * fq + e, d = kx - irow; const bool ok = (d >= 1) && (d <= 128) && (n > 0 || kx >= 128);
;                 const float v = ok ? sc_[t][e] : -1e30f; sc_[t][e] = v; mx = fmaxf(mx, v); }
;         mx = fmaxf(mx, __shfl_xor(mx, 16)); mx = fmaxf(mx, __shfl_xor(mx, 32)); mx = fmaxf(mx, sink);
;         float sum = 0.f;
; #pragma unroll
;         for (int t = 0; t < 10; ++t)
; #pragma unroll
;             for (int e = 0; e < 4; ++e) { const float p = __builtin_amdgcn_exp2f((sc_[t][e] - mx) * LOG2E); sc_[t][e] = p; sum += p; }
	v_lshl_or_b32 v106, s29, 4, v73
	s_and_b64 vcc, vcc, s[6:7]
	v_sub_u32_e32 v107, v44, v106
	v_cndmask_b32_e32 v103, v213, v109, vcc
	v_cmp_lt_u32_e32 vcc, s79, v107
	s_and_b64 vcc, vcc, s[6:7]
	v_sub_u32_e32 v108, v106, v44
	v_max3_f32 v28, v26, s52, v27
	v_cndmask_b32_e32 v107, v213, v110, vcc
	v_cmp_gt_u32_e32 vcc, s84, v108
	v_max3_f32 v28, v28, v29, v30
	s_and_b64 vcc, vcc, s[6:7]
	v_sub_u32_e32 v109, v64, v106
	v_max3_f32 v28, v28, v32, v58
	v_cndmask_b32_e32 v108, v213, v111, vcc
	v_cmp_lt_u32_e32 vcc, s79, v109
	v_max3_f32 v28, v28, v59, v60
	s_and_b64 vcc, vcc, s[6:7]
	v_sub_u32_e32 v106, v66, v106
	v_max3_f32 v28, v28, v62, v63
	v_cndmask_b32_e32 v109, v213, v112, vcc
	v_cmp_lt_u32_e32 vcc, s79, v106
	v_max3_f32 v28, v28, v65, v61
	s_and_b64 vcc, vcc, s[6:7]
	v_max3_f32 v28, v28, v69, v67
	v_cndmask_b32_e32 v106, v213, v113, vcc
	v_cmp_gt_u32_e32 vcc, s84, v31
	v_sub_u32_e32 v111, v82, v44
	v_max3_f32 v28, v28, v97, v68
	v_cndmask_b32_e32 v110, v213, v114, vcc
	v_cmp_lt_u32_e32 vcc, s79, v111
	v_add_u32_e32 v112, -2, v31
	s_or_b32 s49, s49, 8
	v_max3_f32 v28, v28, v99, v100
	v_cndmask_b32_e32 v111, v213, v115, vcc
	v_cmp_gt_u32_e32 vcc, s84, v112
	v_add_u32_e32 v113, -3, v31
	v_lshl_or_b32 v114, s49, 4, v73
	v_max3_f32 v28, v28, v101, v98
	v_cndmask_b32_e32 v112, v213, v116, vcc
	v_cmp_gt_u32_e32 vcc, s84, v113
	v_sub_u32_e32 v115, v44, v114
	v_max3_f32 v28, v28, v104, v102
	v_cndmask_b32_e32 v113, v213, v117, vcc
	v_cmp_lt_u32_e32 vcc, s79, v115
	v_sub_u32_e32 v44, v114, v44
	v_max3_f32 v28, v28, v105, v103
	v_cndmask_b32_e32 v115, v213, v118, vcc
	v_cmp_gt_u32_e32 vcc, s84, v44
	v_sub_u32_e32 v64, v64, v114
	v_max3_f32 v28, v28, v107, v108
	v_cndmask_b32_e32 v44, v213, v119, vcc
	v_cmp_lt_u32_e32 vcc, s79, v64
	v_sub_u32_e32 v66, v66, v114
	v_max3_f32 v28, v28, v109, v106
	v_cndmask_b32_e32 v64, v213, v120, vcc
	v_cmp_lt_u32_e32 vcc, s79, v66
	v_subrev_u32_e32 v114, 32, v31
	v_max3_f32 v28, v28, v110, v111
	v_cndmask_b32_e32 v66, v213, v121, vcc
	v_cmp_gt_u32_e32 vcc, s84, v114
	v_subrev_u32_e32 v114, 33, v31
	v_max3_f32 v28, v28, v112, v113
	v_cndmask_b32_e32 v22, v213, v22, vcc
	v_cmp_gt_u32_e32 vcc, s84, v114
	v_subrev_u32_e32 v114, 34, v31
	v_max3_f32 v28, v28, v115, v44
	v_cndmask_b32_e32 v23, v213, v23, vcc
	v_cmp_gt_u32_e32 vcc, s84, v114
	v_subrev_u32_e32 v31, 35, v31
	v_max3_f32 v28, v28, v64, v66
	v_cndmask_b32_e32 v24, v213, v24, vcc
	v_cmp_gt_u32_e32 vcc, s84, v31
	v_max3_f32 v28, v28, v22, v23
	s_nop 0
	v_cndmask_b32_e32 v25, v213, v25, vcc
	v_max3_f32 v28, v28, v24, v25
	ds_bpermute_b32 v31, v76, v28
	s_waitcnt lgkmcnt(0)
	v_max_f32_e32 v31, v31, v31
	v_max_f32_e32 v28, v28, v31
	ds_bpermute_b32 v31, v77, v28
	s_waitcnt lgkmcnt(0)
	v_max3_f32 v28, v28, v31, v75
	v_sub_f32_e32 v61, v61, v28
	v_mul_f32_e32 v61, 0x3fb8aa3b, v61
	v_exp_f32_e32 v118, v61
	v_sub_f32_e32 v61, v69, v28
	v_mul_f32_e32 v61, 0x3fb8aa3b, v61
	v_exp_f32_e32 v69, v61
	v_sub_f32_e32 v61, v67, v28
	v_mul_f32_e32 v61, 0x3fb8aa3b, v61
	v_exp_f32_e32 v67, v61
	v_sub_f32_e32 v61, v97, v28
	v_mul_f32_e32 v61, 0x3fb8aa3b, v61
	v_exp_f32_e32 v97, v61
	v_sub_f32_e32 v61, v68, v28
	v_mul_f32_e32 v61, 0x3fb8aa3b, v61
	v_sub_f32_e32 v26, v26, v28
	v_exp_f32_e32 v68, v61
	v_sub_f32_e32 v61, v99, v28
	v_mul_f32_e32 v26, 0x3fb8aa3b, v26
	v_sub_f32_e32 v27, v27, v28
	v_mul_f32_e32 v61, 0x3fb8aa3b, v61
	v_exp_f32_e32 v26, v26
	v_mul_f32_e32 v27, 0x3fb8aa3b, v27
	v_sub_f32_e32 v29, v29, v28
	v_exp_f32_e32 v99, v61
	v_sub_f32_e32 v61, v100, v28
	v_exp_f32_e32 v27, v27
	v_mul_f32_e32 v29, 0x3fb8aa3b, v29
	v_sub_f32_e32 v30, v30, v28
	v_mul_f32_e32 v61, 0x3fb8aa3b, v61
	v_exp_f32_e32 v29, v29
	v_mul_f32_e32 v30, 0x3fb8aa3b, v30
	v_sub_f32_e32 v32, v32, v28
	v_exp_f32_e32 v100, v61
	v_sub_f32_e32 v61, v101, v28
	v_exp_f32_e32 v30, v30
	v_mul_f32_e32 v32, 0x3fb8aa3b, v32
	v_sub_f32_e32 v58, v58, v28
	v_mul_f32_e32 v61, 0x3fb8aa3b, v61
	v_add_f32_e32 v31, 0, v26
	v_exp_f32_e32 v32, v32
	v_mul_f32_e32 v58, 0x3fb8aa3b, v58
	v_sub_f32_e32 v59, v59, v28
	v_sub_f32_e32 v62, v62, v28
	v_exp_f32_e32 v101, v61
	v_sub_f32_e32 v61, v98, v28
	v_add_f32_e32 v31, v27, v31
	v_exp_f32_e32 v58, v58
	v_mul_f32_e32 v59, 0x3fb8aa3b, v59
	v_sub_f32_e32 v60, v60, v28
	v_mul_f32_e32 v62, 0x3fb8aa3b, v62
	v_mul_f32_e32 v61, 0x3fb8aa3b, v61
	v_add_f32_e32 v31, v29, v31
	v_exp_f32_e32 v59, v59
	v_mul_f32_e32 v60, 0x3fb8aa3b, v60
	v_exp_f32_e32 v114, v62
	v_sub_f32_e32 v62, v63, v28
	v_exp_f32_e32 v98, v61
	v_sub_f32_e32 v61, v104, v28
	v_add_f32_e32 v31, v30, v31
	v_exp_f32_e32 v60, v60
	v_mul_f32_e32 v62, 0x3fb8aa3b, v62
	v_mul_f32_e32 v61, 0x3fb8aa3b, v61
	v_add_f32_e32 v31, v32, v31
	v_exp_f32_e32 v116, v62
	v_sub_f32_e32 v62, v65, v28
	v_exp_f32_e32 v104, v61
	v_sub_f32_e32 v61, v102, v28
	v_add_f32_e32 v31, v58, v31
	v_mul_f32_e32 v62, 0x3fb8aa3b, v62
	v_mul_f32_e32 v61, 0x3fb8aa3b, v61
	v_add_f32_e32 v31, v59, v31
	v_exp_f32_e32 v117, v62
	v_exp_f32_e32 v102, v61
	v_sub_f32_e32 v61, v105, v28
	v_add_f32_e32 v31, v60, v31
	v_mul_f32_e32 v61, 0x3fb8aa3b, v61
	v_add_f32_e32 v31, v114, v31
	v_exp_f32_e32 v105, v61
	v_sub_f32_e32 v61, v103, v28
	v_add_f32_e32 v31, v116, v31
	v_mul_f32_e32 v61, 0x3fb8aa3b, v61
	v_add_f32_e32 v31, v117, v31
	v_exp_f32_e32 v103, v61
	v_sub_f32_e32 v61, v107, v28
	v_add_f32_e32 v31, v118, v31
	v_mul_f32_e32 v61, 0x3fb8aa3b, v61
	v_add_f32_e32 v31, v69, v31
	v_exp_f32_e32 v107, v61
	v_sub_f32_e32 v61, v108, v28
	v_add_f32_e32 v31, v67, v31
	v_mul_f32_e32 v61, 0x3fb8aa3b, v61
	v_add_f32_e32 v31, v97, v31
	v_exp_f32_e32 v108, v61
	v_sub_f32_e32 v61, v109, v28
	v_add_f32_e32 v31, v68, v31
	v_mul_f32_e32 v61, 0x3fb8aa3b, v61
	v_add_f32_e32 v31, v99, v31
; __device__ __forceinline__ unsigned cvt_pk_bf16(float lo, float hi) { unsigned r; asm volatile("v_cvt_pk_bf16_f32 %0, %1, %2" : "=v"(r) : "v"(lo), "v"(hi)); return r; }
; #define LAS __attribute__((address_space(3)))
; #define MFMA16(a, b, c) __builtin_amdgcn_mfma_f32_16x16x32_bf16((a), (b), (c), 0, 0, 0)
; __device__ __forceinline__ void p2_block(LAS unsigned char* lds, const bf16_t* __restrict__ PROJ, bf16_t* __restrict__ ATT, bf16_t* __restrict__ SGU, const float* __restrict__ qn, const float* __restrict__ kn, ...
;     ...
;         for (int t = 0; t < 10; ++t)
; #pragma unroll
;             for (int e = 0; e < 4; ++e) { const float p = __builtin_amdgcn_exp2f((sc_[t][e] - mx) * LOG2E); sc_[t][e] = p; sum += p; }
;         sum += __shfl_xor(sum, 16); sum += __shfl_xor(sum, 32);
;         const float inv = 1.0f / (sum + __builtin_amdgcn_exp2f((sink - mx) * LOG2E));
;         f32x4 o[4];
; #pragma unroll
;         for (int dt = 0; dt < 4; ++dt) o[dt] = (f32x4){0.f, 0.f, 0.f, 0.f};
; #pragma unroll
;         for (int j = 0; j < 5; ++j) {
;             u32x4 pw; pw.x = cvt_pk_bf16(sc_[2 * j][0], sc_[2 * j][1]); pw.y = cvt_pk_bf16(sc_[2 * j][2], sc_[2 * j][3]); pw.z = cvt_pk_bf16(sc_[2 * j + 1][0], sc_[2 * j + 1][1]); pw.w = cvt_pk_bf16(sc_[2 * j + 1][2], sc_[2 * j + 1][3]);
;             const bf16x8 pf = __builtin_bit_cast(bf16x8, pw);
; #pragma unroll
;             for (int dt = 0; dt < 4; ++dt) { const LAS unsigned char* vb = VT + (16 * dt + fr) * VT_STRIDE + (16 * (t0 + 2 * j) + 4 * fq) * 2;
;                 const u32x2 va = *(const LAS u32x2*)vb, vc = *(const LAS u32x2*)(vb + 32); u32x4 vw; vw.x = va.x; vw.y = va.y; vw.z = vc.x; vw.w = vc.y;
;                 o[dt] = MFMA16(__builtin_bit_cast(bf16x8, vw), pf, o[dt]); }
;         }
	v_exp_f32_e32 v109, v61
	v_sub_f32_e32 v61, v106, v28
	v_add_f32_e32 v31, v100, v31
	v_mul_f32_e32 v61, 0x3fb8aa3b, v61
	v_add_f32_e32 v31, v101, v31
	v_exp_f32_e32 v106, v61
	v_sub_f32_e32 v61, v110, v28
	v_add_f32_e32 v31, v98, v31
	v_mul_f32_e32 v61, 0x3fb8aa3b, v61
	v_add_f32_e32 v31, v104, v31
	v_exp_f32_e32 v110, v61
	v_sub_f32_e32 v61, v111, v28
	v_add_f32_e32 v31, v102, v31
	v_mul_f32_e32 v61, 0x3fb8aa3b, v61
	v_add_f32_e32 v31, v105, v31
	v_exp_f32_e32 v111, v61
	v_sub_f32_e32 v61, v112, v28
	v_add_f32_e32 v31, v103, v31
	v_mul_f32_e32 v61, 0x3fb8aa3b, v61
	v_add_f32_e32 v31, v107, v31
	v_exp_f32_e32 v112, v61
	v_sub_f32_e32 v61, v113, v28
	v_add_f32_e32 v31, v108, v31
	v_mul_f32_e32 v61, 0x3fb8aa3b, v61
	v_sub_f32_e32 v44, v44, v28
	v_add_f32_e32 v31, v109, v31
	v_exp_f32_e32 v113, v61
	v_sub_f32_e32 v61, v115, v28
	v_mul_f32_e32 v44, 0x3fb8aa3b, v44
	v_add_f32_e32 v31, v106, v31
	v_mul_f32_e32 v61, 0x3fb8aa3b, v61
	v_exp_f32_e32 v119, v44
	v_sub_f32_e32 v44, v64, v28
	v_add_f32_e32 v31, v110, v31
	v_exp_f32_e32 v115, v61
	v_mul_f32_e32 v44, 0x3fb8aa3b, v44
	v_add_f32_e32 v31, v111, v31
	v_exp_f32_e32 v120, v44
	v_sub_f32_e32 v44, v66, v28
	v_sub_f32_e32 v23, v23, v28
	v_add_f32_e32 v31, v112, v31
	v_mul_f32_e32 v44, 0x3fb8aa3b, v44
	v_sub_f32_e32 v22, v22, v28
	v_mul_f32_e32 v23, 0x3fb8aa3b, v23
	v_add_f32_e32 v31, v113, v31
	v_exp_f32_e32 v121, v44
	v_mul_f32_e32 v22, 0x3fb8aa3b, v22
	v_exp_f32_e32 v123, v23
	v_sub_f32_e32 v23, v24, v28
	v_add_f32_e32 v31, v115, v31
	v_exp_f32_e32 v122, v22
	v_mul_f32_e32 v23, 0x3fb8aa3b, v23
	v_add_f32_e32 v31, v119, v31
	v_exp_f32_e32 v124, v23
	v_sub_f32_e32 v23, v25, v28
	v_add_f32_e32 v31, v120, v31
	v_mul_f32_e32 v23, 0x3fb8aa3b, v23
	v_add_f32_e32 v31, v121, v31
	v_exp_f32_e32 v125, v23
	v_add_f32_e32 v22, v122, v31
	v_add_f32_e32 v22, v123, v22
	v_add_f32_e32 v22, v124, v22
	v_add_f32_e32 v22, v125, v22
	ds_bpermute_b32 v23, v76, v22
	v_lshl_add_u32 v62, s4, 1, v74
	v_or_b32_e32 v44, s48, v33
	s_or_b32 s4, s26, 32
	s_waitcnt lgkmcnt(0)
	v_add_f32_e32 v22, v22, v23
	ds_bpermute_b32 v23, v77, v22
	s_waitcnt lgkmcnt(0)
	v_add_f32_e32 v22, v22, v23
	v_sub_f32_e32 v23, v75, v28
	v_mul_f32_e32 v23, 0x3fb8aa3b, v23
	v_exp_f32_e32 v23, v23
	s_nop 0
	v_add_f32_e32 v126, v23, v22
	v_cvt_pk_bf16_f32 v22, v26, v27
	v_cvt_pk_bf16_f32 v23, v29, v30
	v_cvt_pk_bf16_f32 v24, v32, v58
	v_mad_u32_u24 v26, v137, s81, v62
	v_add_u32_e32 v30, v62, v80
	v_add_u32_e32 v58, v62, v79
	v_add_u32_e32 v62, v62, v78
	v_add_u32_e32 v26, 0x9000, v26
	v_add_u32_e32 v30, 0x9000, v30
	v_add_u32_e32 v58, 0x9000, v58
	v_add_u32_e32 v62, 0x9000, v62
	v_cvt_pk_bf16_f32 v25, v59, v60
	ds_read2_b64 v[26:29], v26 offset1:4
	ds_read2_b64 v[30:33], v30 offset1:4
	ds_read2_b64 v[58:61], v58 offset1:4
	ds_read2_b64 v[62:65], v62 offset1:4
	s_waitcnt lgkmcnt(3)
	v_mfma_f32_16x16x32_bf16 v[26:29], v[26:29], v[22:25], 0
	s_waitcnt lgkmcnt(2)
	v_mfma_f32_16x16x32_bf16 v[30:33], v[30:33], v[22:25], 0
	s_waitcnt lgkmcnt(1)
	v_mfma_f32_16x16x32_bf16 v[58:61], v[58:61], v[22:25], 0
	s_waitcnt lgkmcnt(0)
	v_mfma_f32_16x16x32_bf16 v[22:25], v[62:65], v[22:25], 0
	v_cvt_pk_bf16_f32 v62, v114, v116
	v_cvt_pk_bf16_f32 v63, v117, v118
	v_cvt_pk_bf16_f32 v64, v69, v67
	v_cvt_pk_bf16_f32 v65, v97, v68
	v_lshl_add_u32 v97, s27, 5, v74
	v_mad_u32_u24 v66, v137, s81, v97
	v_add_u32_e32 v66, 0x9000, v66
	ds_read2_b64 v[66:69], v66 offset1:4
	s_lshr_b32 s27, s4, 4
	s_waitcnt lgkmcnt(0)
	v_mfma_f32_16x16x32_bf16 v[26:29], v[66:69], v[62:65], v[26:29]
	v_add_u32_e32 v66, v97, v80
	v_add_u32_e32 v66, 0x9000, v66
	ds_read2_b64 v[66:69], v66 offset1:4
	s_waitcnt lgkmcnt(0)
	v_mfma_f32_16x16x32_bf16 v[30:33], v[66:69], v[62:65], v[30:33]
	v_add_u32_e32 v66, v97, v79
	v_add_u32_e32 v66, 0x9000, v66
	ds_read2_b64 v[66:69], v66 offset1:4
	s_waitcnt lgkmcnt(0)
	v_mfma_f32_16x16x32_bf16 v[58:61], v[66:69], v[62:65], v[58:61]
	v_add_u32_e32 v66, v97, v78
	v_add_u32_e32 v66, 0x9000, v66
	ds_read2_b64 v[66:69], v66 offset1:4
	v_lshl_add_u32 v97, s28, 5, v74
	s_waitcnt lgkmcnt(0)
	v_mfma_f32_16x16x32_bf16 v[22:25], v[66:69], v[62:65], v[22:25]
	v_mad_u32_u24 v66, v137, s81, v97
	v_add_u32_e32 v66, 0x9000, v66
	v_cvt_pk_bf16_f32 v62, v99, v100
	v_cvt_pk_bf16_f32 v63, v101, v98
	v_cvt_pk_bf16_f32 v64, v104, v102
	v_cvt_pk_bf16_f32 v65, v105, v103
	ds_read2_b64 v[66:69], v66 offset1:4
	s_waitcnt lgkmcnt(0)
	v_mfma_f32_16x16x32_bf16 v[26:29], v[66:69], v[62:65], v[26:29]
	v_add_u32_e32 v66, v97, v80
	v_add_u32_e32 v66, 0x9000, v66
	ds_read2_b64 v[66:69], v66 offset1:4
	v_or_b32_e32 v98, s4, v137
	s_waitcnt lgkmcnt(0)
	v_mfma_f32_16x16x32_bf16 v[30:33], v[66:69], v[62:65], v[30:33]
	v_add_u32_e32 v66, v97, v79
	v_add_u32_e32 v66, 0x9000, v66
	ds_read2_b64 v[66:69], v66 offset1:4
	s_waitcnt lgkmcnt(0)
	v_mfma_f32_16x16x32_bf16 v[58:61], v[66:69], v[62:65], v[58:61]
	v_add_u32_e32 v66, v97, v78
	v_add_u32_e32 v66, 0x9000, v66
	ds_read2_b64 v[66:69], v66 offset1:4
	v_lshl_add_u32 v97, s29, 5, v74
	s_waitcnt lgkmcnt(0)
	v_mfma_f32_16x16x32_bf16 v[22:25], v[66:69], v[62:65], v[22:25]
	v_mad_u32_u24 v66, v137, s81, v97
	v_add_u32_e32 v66, 0x9000, v66
	v_cvt_pk_bf16_f32 v62, v107, v108
	v_cvt_pk_bf16_f32 v63, v109, v106
	v_cvt_pk_bf16_f32 v64, v110, v111
	v_cvt_pk_bf16_f32 v65, v112, v113
	ds_read2_b64 v[66:69], v66 offset1:4
	s_waitcnt lgkmcnt(0)
	v_mfma_f32_16x16x32_bf16 v[26:29], v[66:69], v[62:65], v[26:29]
	v_add_u32_e32 v66, v97, v80
	v_add_u32_e32 v66, 0x9000, v66
	ds_read2_b64 v[66:69], v66 offset1:4
	s_waitcnt lgkmcnt(0)
	v_mfma_f32_16x16x32_bf16 v[30:33], v[66:69], v[62:65], v[30:33]
	v_add_u32_e32 v66, v97, v79
	v_add_u32_e32 v66, 0x9000, v66
	ds_read2_b64 v[66:69], v66 offset1:4
	s_waitcnt lgkmcnt(0)
; __device__ __forceinline__ void p2_block(LAS unsigned char* lds, const bf16_t* __restrict__ PROJ, bf16_t* __restrict__ ATT, bf16_t* __restrict__ SGU, const float* __restrict__ qn, const float* __restrict__ kn, ...
;     ...
;         const int i0 = rbase + 16 * c, irow = i0 + fr, pos = n * 128 + irow; const size_t grow = (size_t)b * pg8::SEQ + pos;
;         bf16x8 qf0, qf1;
;         {
;             float x1[8], x2[8]; unpack8(qa[c], x1); unpack8(qb[c], x2);
;             float ss = 0.f;
; #pragma unroll
;             for (int j = 0; j < 8; ++j) ss += x1[j] * x1[j] + x2[j] * x2[j];
;             ss += __shfl_xor(ss, 16); ss += __shfl_xor(ss, 32);
;             const float rinv = rsqrtf(ss * (1.0f / 64.0f) + pg8::EPS) * 0.125f;
;             const float* cp = COS + pos * 32 + 8 * fq; const float* sp = SIN + pos * 32 + 8 * fq;
;             float o1[8], o2[8];
; #pragma unroll
;             for (int j = 0; j < 8; ++j) { const float a1 = x1[j] * rinv * qn[8 * fq + j], a2 = x2[j] * rinv * qn[32 + 8 * fq + j], cc = cp[j], sn = sp[j]; o1[j] = a1 * cc - a2 * sn; o2[j] = a2 * cc + a1 * sn; }
;             u32x4 w0, w1;
;     ...
;         const float inv = 1.0f / (sum + __builtin_amdgcn_exp2f((sink - mx) * LOG2E));
;         f32x4 o[4];
; #pragma unroll
;         for (int dt = 0; dt < 4; ++dt) o[dt] = (f32x4){0.f, 0.f, 0.f, 0.f};
; #pragma unroll
;         for (int j = 0; j < 5; ++j) {
;             u32x4 pw; pw.x = cvt_pk_bf16(sc_[2 * j][0], sc_[2 * j][1]); pw.y = cvt_pk_bf16(sc_[2 * j][2], sc_[2 * j][3]); pw.z = cvt_pk_bf16(sc_[2 * j + 1][0], sc_[2 * j + 1][1]); pw.w = cvt_pk_bf16(sc_[2 * j + 1][2], sc_[2 * j + 1][3]);
;             const bf16x8 pf = __builtin_bit_cast(bf16x8, pw);
; #pragma unroll
;             for (int dt = 0; dt < 4; ++dt) { const LAS unsigned char* vb = VT + (16 * dt + fr) * VT_STRIDE + (16 * (t0 + 2 * j) + 4 * fq) * 2;
;                 const u32x2 va = *(const LAS u32x2*)vb, vc = *(const LAS u32x2*)(vb + 32); u32x4 vw; vw.x = va.x; vw.y = va.y; vw.z = vc.x; vw.w = vc.y;
;                 o[dt] = MFMA16(__builtin_bit_cast(bf16x8, vw), pf, o[dt]); }
;         }
;         bf16_t* op = ATT + grow * 1024 + hq * 64 + 4 * fq;
; #pragma unroll
;         for (int dt = 0; dt < 4; ++dt) { u32x2 ow; ow.x = cvt_pk_bf16(o[dt][0] * inv, o[dt][1] * inv); ow.y = cvt_pk_bf16(o[dt][2] * inv, o[dt][3] * inv); *(u32x2*)(op + 16 * dt) = ow; }
	v_mfma_f32_16x16x32_bf16 v[58:61], v[66:69], v[62:65], v[58:61]
	v_add_u32_e32 v66, v97, v78
	v_add_u32_e32 v66, 0x9000, v66
	ds_read2_b64 v[66:69], v66 offset1:4
	v_lshl_add_u32 v97, s49, 5, v74
	s_waitcnt lgkmcnt(0)
	v_mfma_f32_16x16x32_bf16 v[22:25], v[66:69], v[62:65], v[22:25]
	v_mad_u32_u24 v66, v137, s81, v97
	v_add_u32_e32 v66, 0x9000, v66
	v_cvt_pk_bf16_f32 v62, v115, v119
	v_cvt_pk_bf16_f32 v63, v120, v121
	v_cvt_pk_bf16_f32 v64, v122, v123
	v_cvt_pk_bf16_f32 v65, v124, v125
	ds_read2_b64 v[66:69], v66 offset1:4
	s_waitcnt lgkmcnt(0)
	v_mfma_f32_16x16x32_bf16 v[26:29], v[66:69], v[62:65], v[26:29]
	v_add_u32_e32 v66, v97, v80
	v_add_u32_e32 v66, 0x9000, v66
	ds_read2_b64 v[66:69], v66 offset1:4
	s_waitcnt lgkmcnt(0)
	v_mfma_f32_16x16x32_bf16 v[30:33], v[66:69], v[62:65], v[30:33]
	v_add_u32_e32 v66, v97, v79
	v_add_u32_e32 v66, 0x9000, v66
	ds_read2_b64 v[66:69], v66 offset1:4
	s_waitcnt lgkmcnt(0)
	v_mfma_f32_16x16x32_bf16 v[58:61], v[66:69], v[62:65], v[58:61]
	v_add_u32_e32 v66, v97, v78
	v_add_u32_e32 v66, 0x9000, v66
	ds_read2_b64 v[66:69], v66 offset1:4
	v_or_b32_e32 v97, s17, v98
	s_waitcnt lgkmcnt(0)
	v_mfma_f32_16x16x32_bf16 v[22:25], v[66:69], v[62:65], v[22:25]
	v_div_scale_f32 v62, s[28:29], v126, v126, 1.0
	v_rcp_f32_e32 v63, v62
	v_lshlrev_b32_e32 v68, 16, v34
	v_and_b32_e32 v69, 0xffff0000, v34
	v_and_b32_e32 v67, 0xffff0000, v38
	v_fma_f32 v64, -v62, v63, 1.0
	v_fmac_f32_e32 v63, v64, v63
	v_div_scale_f32 v64, vcc, 1.0, v126, 1.0
	v_mul_f32_e32 v65, v64, v63
	v_fma_f32 v66, -v62, v65, v64
	v_fmac_f32_e32 v65, v66, v63
	v_fma_f32 v62, -v62, v65, v64
	v_div_fmas_f32 v62, v62, v63, v65
	v_div_fixup_f32 v64, v62, v126, 1.0
	v_mul_f32_e32 v26, v64, v26
	v_mul_f32_e32 v27, v64, v27
	v_lshlrev_b64 v[62:63], 11, v[44:45]
	v_cvt_pk_bf16_f32 v26, v26, v27
	v_mul_f32_e32 v27, v64, v28
	v_lshl_add_u64 v[62:63], v[42:43], 0, v[62:63]
	v_mul_f32_e32 v28, v64, v29
	v_cvt_pk_bf16_f32 v27, v27, v28
	global_store_dwordx2 v[62:63], v[26:27], off
	v_mul_f32_e32 v26, v64, v30
	v_mul_f32_e32 v27, v64, v31
	v_cvt_pk_bf16_f32 v26, v26, v27
	v_mul_f32_e32 v27, v64, v32
	v_mul_f32_e32 v28, v64, v33
	v_cvt_pk_bf16_f32 v27, v27, v28
	global_store_dwordx2 v[62:63], v[26:27], off offset:32
	v_mul_f32_e32 v26, v64, v58
	v_mul_f32_e32 v27, v64, v59
	v_cvt_pk_bf16_f32 v26, v26, v27
	v_mul_f32_e32 v27, v64, v60
	v_mul_f32_e32 v22, v64, v22
	v_mul_f32_e32 v23, v64, v23
	v_mul_f32_e32 v28, v64, v61
	v_cvt_pk_bf16_f32 v27, v27, v28
	global_store_dwordx2 v[62:63], v[26:27], off offset:64
	v_cvt_pk_bf16_f32 v22, v22, v23
	v_mul_f32_e32 v23, v64, v24
	v_mul_f32_e32 v24, v64, v25
	v_cvt_pk_bf16_f32 v23, v23, v24
	global_store_dwordx2 v[62:63], v[22:23], off offset:96
	v_lshlrev_b32_e32 v66, 16, v38
	v_lshlrev_b32_e32 v65, 16, v35
	v_and_b32_e32 v64, 0xffff0000, v35
	v_pk_mul_f32 v[22:23], v[68:69], v[68:69]
	v_lshlrev_b32_e32 v63, 16, v39
	v_and_b32_e32 v62, 0xffff0000, v39
	v_pk_fma_f32 v[22:23], v[66:67], v[66:67], v[22:23]
	v_pk_mul_f32 v[24:25], v[64:65], v[64:65]
	v_lshlrev_b32_e32 v61, 16, v36
	v_and_b32_e32 v60, 0xffff0000, v36
	v_pk_fma_f32 v[24:25], v[62:63], v[62:63], v[24:25]
	v_add_f32_e32 v22, v22, v23
	v_lshlrev_b32_e32 v59, 16, v40
	v_and_b32_e32 v58, 0xffff0000, v40
	v_pk_mul_f32 v[26:27], v[60:61], v[60:61]
	v_add_f32_e32 v22, v25, v22
	v_lshlrev_b32_e32 v39, 16, v41
	v_and_b32_e32 v38, 0xffff0000, v41
	v_lshlrev_b32_e32 v41, 16, v37
	v_and_b32_e32 v40, 0xffff0000, v37
	v_pk_fma_f32 v[26:27], v[58:59], v[58:59], v[26:27]
	v_add_f32_e32 v22, v24, v22
	v_pk_mul_f32 v[28:29], v[40:41], v[40:41]
	v_add_f32_e32 v22, v27, v22
	v_pk_fma_f32 v[28:29], v[38:39], v[38:39], v[28:29]
	v_add_f32_e32 v22, v26, v22
	v_add_f32_e32 v22, v29, v22
	v_add_f32_e32 v22, v28, v22
	ds_bpermute_b32 v23, v76, v22
	v_mov_b32_e32 v100, v68
	v_mov_b32_e32 v101, v66
	v_mov_b32_e32 v66, v69
	s_add_i32 s29, s27, 4
	s_waitcnt lgkmcnt(0)
	v_add_f32_e32 v22, v22, v23
	ds_bpermute_b32 v23, v77, v22
	s_waitcnt lgkmcnt(0)
	v_add_f32_e32 v22, v22, v23
	v_fmamk_f32 v22, v22, 0x3c800000, v209
	v_cmp_gt_f32_e32 vcc, s82, v22
	v_mul_f32_e32 v23, 0x4b800000, v22
	s_nop 0
	v_cndmask_b32_e32 v22, v22, v23, vcc
	v_rsq_f32_e32 v22, v22
	s_nop 0
	v_mul_f32_e32 v23, 0x45800000, v22
	v_cndmask_b32_e32 v22, v22, v23, vcc
	v_mul_f32_e32 v44, 0x3e000000, v22
	v_lshlrev_b32_e32 v22, 7, v97
	v_mov_b32_e32 v23, v1
	v_lshl_add_u64 v[26:27], v[46:47], 0, v[22:23]
	v_lshl_add_u64 v[34:35], v[48:49], 0, v[22:23]
	global_load_dwordx4 v[22:25], v[26:27], off offset:16
	global_load_dwordx4 v[30:33], v[26:27], off
	s_nop 0
	global_load_dwordx4 v[26:29], v[34:35], off offset:16
	s_nop 0
	global_load_dwordx4 v[34:37], v[34:35], off
	v_pk_mul_f32 v[100:101], v[44:45], v[100:101] op_sel_hi:[0,1]
	v_pk_mul_f32 v[66:67], v[44:45], v[66:67] op_sel_hi:[0,1]
	v_pk_mul_f32 v[100:101], v[56:57], v[100:101]
	v_pk_mul_f32 v[66:67], v[18:19], v[66:67]
	s_waitcnt vmcnt(2)
	v_mov_b32_e32 v57, v30
	v_mov_b32_e32 v102, v30
	s_waitcnt vmcnt(0)
; __device__ __forceinline__ unsigned cvt_pk_bf16(float lo, float hi) { unsigned r; asm volatile("v_cvt_pk_bf16_f32 %0, %1, %2" : "=v"(r) : "v"(lo), "v"(hi)); return r; }
; #define LAS __attribute__((address_space(3)))
; #define MFMA16(a, b, c) __builtin_amdgcn_mfma_f32_16x16x32_bf16((a), (b), (c), 0, 0, 0)
; __device__ __forceinline__ void p2_block(LAS unsigned char* lds, const bf16_t* __restrict__ PROJ, bf16_t* __restrict__ ATT, bf16_t* __restrict__ SGU, const float* __restrict__ qn, const float* __restrict__ kn, ...
;     ...
;             const float* cp = COS + pos * 32 + 8 * fq; const float* sp = SIN + pos * 32 + 8 * fq;
;             float o1[8], o2[8];
; #pragma unroll
;             for (int j = 0; j < 8; ++j) { const float a1 = x1[j] * rinv * qn[8 * fq + j], a2 = x2[j] * rinv * qn[32 + 8 * fq + j], cc = cp[j], sn = sp[j]; o1[j] = a1 * cc - a2 * sn; o2[j] = a2 * cc + a1 * sn; }
;             u32x4 w0, w1;
;             w0.x = cvt_pk_bf16(o1[0], o1[1]); w0.y = cvt_pk_bf16(o1[2], o1[3]); w0.z = cvt_pk_bf16(o1[4], o1[5]); w0.w = cvt_pk_bf16(o1[6], o1[7]);
;             w1.x = cvt_pk_bf16(o2[0], o2[1]); w1.y = cvt_pk_bf16(o2[2], o2[3]); w1.z = cvt_pk_bf16(o2[4], o2[5]); w1.w = cvt_pk_bf16(o2[6], o2[7]);
;             qf0 = __builtin_bit_cast(bf16x8, w0); qf1 = __builtin_bit_cast(bf16x8, w1);
;         }
;         const int t0 = (i0 >> 4) < 6 ? (i0 >> 4) : 6;
;         f32x4 sc_[10];
;         const LAS unsigned char* kbase = KS + (16 * t0 + fr) * KS_STRIDE + 16 * fq;
; #pragma unroll
;         for (int t = 0; t < 10; ++t) { const bf16x8 k0 = *(const LAS bf16x8*)(kbase + t * 16 * KS_STRIDE), k1 = *(const LAS bf16x8*)(kbase + t * 16 * KS_STRIDE + 64);
;             f32x4 z = (f32x4){0.f, 0.f, 0.f, 0.f}; z = MFMA16(k0, qf0, z); sc_[t] = MFMA16(k1, qf1, z); }
	v_mov_b32_e32 v56, v34
	v_mov_b32_e32 v103, v34
	v_mov_b32_e32 v30, v35
	v_mov_b32_e32 v34, v31
	v_pk_mul_f32 v[18:19], v[30:31], v[66:67]
	v_pk_mul_f32 v[30:31], v[34:35], v[66:67]
	v_sub_f32_e32 v19, v19, v18
	v_add_f32_e32 v18, v30, v31
	v_mov_b32_e32 v30, v65
	v_mov_b32_e32 v31, v63
	v_pk_mul_f32 v[30:31], v[44:45], v[30:31] op_sel_hi:[0,1]
	v_pk_mul_f32 v[30:31], v[54:55], v[30:31]
	v_mov_b32_e32 v34, v36
	v_mov_b32_e32 v35, v32
	v_pk_mul_f32 v[34:35], v[34:35], v[30:31]
	v_mov_b32_e32 v65, v62
	v_sub_f32_e32 v54, v35, v34
	v_mov_b32_e32 v34, v32
	v_mov_b32_e32 v35, v36
	v_pk_mul_f32 v[30:31], v[34:35], v[30:31]
	v_mov_b32_e32 v32, v37
	v_add_f32_e32 v34, v30, v31
	v_pk_mul_f32 v[30:31], v[44:45], v[64:65] op_sel_hi:[0,1]
	v_pk_mul_f32 v[20:21], v[20:21], v[30:31]
	v_mov_b32_e32 v36, v33
	v_pk_mul_f32 v[30:31], v[32:33], v[20:21]
	v_pk_mul_f32 v[20:21], v[36:37], v[20:21]
	v_sub_f32_e32 v32, v31, v30
	v_add_f32_e32 v33, v20, v21
	v_mov_b32_e32 v20, v61
	v_mov_b32_e32 v21, v59
	v_pk_mul_f32 v[20:21], v[44:45], v[20:21] op_sel_hi:[0,1]
	v_pk_mul_f32 v[20:21], v[52:53], v[20:21]
	v_mov_b32_e32 v30, v26
	v_mov_b32_e32 v31, v22
	v_pk_mul_f32 v[30:31], v[30:31], v[20:21]
	v_mov_b32_e32 v61, v58
	v_sub_f32_e32 v35, v31, v30
	v_mov_b32_e32 v30, v22
	v_mov_b32_e32 v31, v26
	v_pk_mul_f32 v[20:21], v[30:31], v[20:21]
	v_mov_b32_e32 v22, v27
	v_add_f32_e32 v30, v20, v21
	v_pk_mul_f32 v[20:21], v[44:45], v[60:61] op_sel_hi:[0,1]
	v_pk_mul_f32 v[14:15], v[14:15], v[20:21]
	v_mov_b32_e32 v26, v23
	v_pk_mul_f32 v[20:21], v[22:23], v[14:15]
	v_pk_mul_f32 v[14:15], v[26:27], v[14:15]
	v_sub_f32_e32 v22, v21, v20
	v_add_f32_e32 v23, v14, v15
	v_mov_b32_e32 v14, v41
	v_mov_b32_e32 v15, v39
	v_pk_mul_f32 v[14:15], v[44:45], v[14:15] op_sel_hi:[0,1]
	v_pk_mul_f32 v[14:15], v[50:51], v[14:15]
	v_mov_b32_e32 v20, v28
	v_mov_b32_e32 v21, v24
	v_pk_mul_f32 v[20:21], v[14:15], v[20:21]
	v_mov_b32_e32 v41, v38
	v_sub_f32_e32 v26, v21, v20
	v_mov_b32_e32 v20, v24
	v_mov_b32_e32 v21, v28
	v_pk_mul_f32 v[14:15], v[14:15], v[20:21]
	v_mov_b32_e32 v24, v29
	v_add_f32_e32 v21, v14, v15
	v_pk_mul_f32 v[14:15], v[44:45], v[40:41] op_sel_hi:[0,1]
	v_pk_mul_f32 v[14:15], v[16:17], v[14:15]
	v_mov_b32_e32 v28, v25
	v_pk_mul_f32 v[16:17], v[14:15], v[24:25]
	v_pk_mul_f32 v[14:15], v[14:15], v[28:29]
	v_pk_mul_f32 v[56:57], v[56:57], v[100:101]
	v_pk_mul_f32 v[100:101], v[102:103], v[100:101]
	v_sub_f32_e32 v17, v17, v16
	v_add_f32_e32 v24, v14, v15
	v_mad_u32_u24 v44, v98, s59, v81
	v_sub_f32_e32 v57, v57, v56
	v_add_f32_e32 v56, v100, v101
	v_cvt_pk_bf16_f32 v14, v57, v19
	v_cvt_pk_bf16_f32 v15, v54, v32
	v_cvt_pk_bf16_f32 v16, v35, v22
	v_cvt_pk_bf16_f32 v17, v26, v17
	v_cvt_pk_bf16_f32 v18, v56, v18
	v_cvt_pk_bf16_f32 v19, v34, v33
	v_cvt_pk_bf16_f32 v20, v30, v23
	v_cvt_pk_bf16_f32 v21, v21, v24
	ds_read_b128 v[22:25], v44
	ds_read_b128 v[26:29], v44 offset:64
	s_waitcnt lgkmcnt(1)
	v_mfma_f32_16x16x32_bf16 v[22:25], v[22:25], v[14:17], 0
	s_waitcnt lgkmcnt(0)
	v_mfma_f32_16x16x32_bf16 v[22:25], v[26:29], v[18:21], v[22:25]
	ds_read_b128 v[26:29], v44 offset:2304
	ds_read_b128 v[30:33], v44 offset:2368
	s_waitcnt lgkmcnt(1)
	v_mfma_f32_16x16x32_bf16 v[26:29], v[26:29], v[14:17], 0
	s_waitcnt lgkmcnt(0)
	v_mfma_f32_16x16x32_bf16 v[26:29], v[30:33], v[18:21], v[26:29]
	ds_read_b128 v[30:33], v44 offset:4608
	ds_read_b128 v[34:37], v44 offset:4672
	s_waitcnt lgkmcnt(1)
	v_mfma_f32_16x16x32_bf16 v[30:33], v[30:33], v[14:17], 0
	s_waitcnt lgkmcnt(0)
	v_mfma_f32_16x16x32_bf16 v[30:33], v[34:37], v[18:21], v[30:33]
	ds_read_b128 v[34:37], v44 offset:6912
	ds_read_b128 v[38:41], v44 offset:6976
	s_waitcnt lgkmcnt(1)
	v_mfma_f32_16x16x32_bf16 v[34:37], v[34:37], v[14:17], 0
	s_waitcnt lgkmcnt(0)
	v_mfma_f32_16x16x32_bf16 v[34:37], v[38:41], v[18:21], v[34:37]
	ds_read_b128 v[38:41], v44 offset:9216
	ds_read_b128 v[50:53], v44 offset:9280
	s_waitcnt lgkmcnt(1)
	v_mfma_f32_16x16x32_bf16 v[38:41], v[38:41], v[14:17], 0
	s_waitcnt lgkmcnt(0)
	v_mfma_f32_16x16x32_bf16 v[38:41], v[50:53], v[18:21], v[38:41]
	ds_read_b128 v[50:53], v44 offset:11520
	ds_read_b128 v[54:57], v44 offset:11584
	s_waitcnt lgkmcnt(1)
	v_mfma_f32_16x16x32_bf16 v[50:53], v[50:53], v[14:17], 0
	s_waitcnt lgkmcnt(0)
	v_mfma_f32_16x16x32_bf16 v[50:53], v[54:57], v[18:21], v[50:53]
	ds_read_b128 v[54:57], v44 offset:13824
	ds_read_b128 v[58:61], v44 offset:13888
	s_waitcnt lgkmcnt(1)
	v_mfma_f32_16x16x32_bf16 v[54:57], v[54:57], v[14:17], 0
	s_waitcnt lgkmcnt(0)
	v_mfma_f32_16x16x32_bf16 v[54:57], v[58:61], v[18:21], v[54:57]
	ds_read_b128 v[58:61], v44 offset:16128
	ds_read_b128 v[62:65], v44 offset:16192
	s_waitcnt lgkmcnt(1)
	v_mfma_f32_16x16x32_bf16 v[58:61], v[58:61], v[14:17], 0
	s_waitcnt lgkmcnt(0)
	v_mfma_f32_16x16x32_bf16 v[58:61], v[62:65], v[18:21], v[58:61]
	ds_read_b128 v[62:65], v44 offset:18432
	ds_read_b128 v[66:69], v44 offset:18496
	s_waitcnt lgkmcnt(1)
	v_mfma_f32_16x16x32_bf16 v[62:65], v[62:65], v[14:17], 0
	s_waitcnt lgkmcnt(0)
	v_mfma_f32_16x16x32_bf16 v[62:65], v[66:69], v[18:21], v[62:65]
	ds_read_b128 v[66:69], v44 offset:20736
	ds_read_b128 v[100:103], v44 offset:20800
	s_waitcnt lgkmcnt(1)
	v_mfma_f32_16x16x32_bf16 v[14:17], v[66:69], v[14:17], 0
	s_waitcnt lgkmcnt(0)
; __device__ __forceinline__ void p2_block(LAS unsigned char* lds, const bf16_t* __restrict__ PROJ, bf16_t* __restrict__ ATT, bf16_t* __restrict__ SGU, const float* __restrict__ qn, const float* __restrict__ kn, ...
;     ...
;         float mx = -1e30f;
; #pragma unroll
;         for (int t = 0; t < 10; ++t)
; #pragma unroll
;             for (int e = 0; e < 4; ++e) { const int kx = 16 * (t0 + t) + 4 * fq + e, d = kx - irow; const bool ok = (d >= 1) && (d <= 128) && (n > 0 || kx >= 128);
;                 const float v = ok ? sc_[t][e] : -1e30f; sc_[t][e] = v; mx = fmaxf(mx, v); }
;         mx = fmaxf(mx, __shfl_xor(mx, 16)); mx = fmaxf(mx, __shfl_xor(mx, 32)); mx = fmaxf(mx, sink);
	v_mfma_f32_16x16x32_bf16 v[14:17], v[100:103], v[18:21], v[14:17]
	v_cndmask_b32_e64 v19, v213, v23, s[42:43]
	v_sub_u32_e32 v23, v98, v83
	v_cmp_lt_u32_e32 vcc, s79, v23
	v_cndmask_b32_e64 v21, v213, v24, s[44:45]
	s_and_b64 vcc, s[50:51], vcc
	v_sub_u32_e32 v24, v98, v84
	v_cndmask_b32_e32 v23, v213, v26, vcc
	v_cmp_lt_u32_e32 vcc, s79, v24
	v_cndmask_b32_e64 v18, v213, v22, s[40:41]
	v_cndmask_b32_e64 v22, v213, v25, s[46:47]
	s_and_b64 vcc, s[50:51], vcc
	v_sub_u32_e32 v25, v98, v85
	v_cndmask_b32_e32 v24, v213, v27, vcc
	v_cmp_lt_u32_e32 vcc, s79, v25
	s_and_b64 vcc, s[50:51], vcc
	v_sub_u32_e32 v26, v98, v87
	s_add_i32 s40, s27, 2
	v_cndmask_b32_e32 v25, v213, v28, vcc
	v_cmp_lt_u32_e32 vcc, s79, v26
	v_lshl_or_b32 v27, s40, 4, v73
	s_and_b64 vcc, s[50:51], vcc
	v_sub_u32_e32 v28, v98, v27
	v_cndmask_b32_e32 v26, v213, v29, vcc
	v_cmp_lt_u32_e32 vcc, s79, v28
	s_and_b64 vcc, vcc, s[6:7]
	v_sub_u32_e32 v29, v27, v98
	v_cndmask_b32_e32 v28, v213, v30, vcc
	v_cmp_gt_u32_e32 vcc, s84, v29
	s_and_b64 vcc, vcc, s[6:7]
	v_add_u32_e32 v30, -2, v98
	v_cndmask_b32_e32 v29, v213, v31, vcc
	v_sub_u32_e32 v31, v30, v27
	v_cmp_lt_u32_e32 vcc, s79, v31
	v_add_u32_e32 v31, -3, v98
	s_and_b64 vcc, vcc, s[6:7]
	v_sub_u32_e32 v27, v31, v27
	v_cndmask_b32_e32 v44, v213, v32, vcc
	v_cmp_lt_u32_e32 vcc, s79, v27
	s_and_b64 vcc, vcc, s[6:7]
	v_sub_u32_e32 v32, v98, v86
	v_cndmask_b32_e32 v27, v213, v33, vcc
	v_cmp_lt_u32_e32 vcc, s79, v32
	s_and_b64 vcc, vcc, s[6:7]
	v_sub_u32_e32 v32, v86, v98
	v_cndmask_b32_e32 v33, v213, v34, vcc
	v_cmp_gt_u32_e32 vcc, s84, v32
	s_and_b64 vcc, vcc, s[6:7]
	v_sub_u32_e32 v32, v98, v89
	v_cndmask_b32_e32 v35, v213, v35, vcc
	v_cmp_lt_u32_e32 vcc, s79, v32
	s_and_b64 vcc, vcc, s[6:7]
	v_sub_u32_e32 v32, v98, v90
	v_cndmask_b32_e32 v66, v213, v36, vcc
	v_cmp_lt_u32_e32 vcc, s79, v32
	s_and_b64 vcc, vcc, s[6:7]
	v_lshl_or_b32 v32, s29, 4, v73
	s_cmp_gt_u32 s4, 48
	v_sub_u32_e32 v34, v98, v32
	s_cselect_b64 s[42:43], -1, 0
	v_cndmask_b32_e32 v37, v213, v37, vcc
	v_cmp_lt_u32_e32 vcc, s79, v34
	s_or_b64 s[42:43], s[50:51], s[42:43]
	s_and_b64 vcc, vcc, s[42:43]
	v_sub_u32_e32 v34, v32, v98
	v_cndmask_b32_e32 v67, v213, v38, vcc
	v_cmp_gt_u32_e32 vcc, s84, v34
	s_and_b64 vcc, vcc, s[42:43]
	v_sub_u32_e32 v34, v30, v32
	v_cndmask_b32_e32 v68, v213, v39, vcc
	v_cmp_lt_u32_e32 vcc, s79, v34
	s_and_b64 vcc, vcc, s[42:43]
	v_sub_u32_e32 v32, v31, v32
	v_cndmask_b32_e32 v40, v213, v40, vcc
	v_cmp_lt_u32_e32 vcc, s79, v32
	s_and_b64 vcc, vcc, s[42:43]
	v_sub_u32_e32 v32, v98, v88
	v_cndmask_b32_e32 v69, v213, v41, vcc
	v_cmp_lt_u32_e32 vcc, s79, v32
	s_and_b64 vcc, vcc, s[6:7]
	v_sub_u32_e32 v32, v88, v98
	v_cndmask_b32_e32 v83, v213, v50, vcc
	v_cmp_gt_u32_e32 vcc, s84, v32
	s_and_b64 vcc, vcc, s[6:7]
	v_sub_u32_e32 v32, v98, v91
	v_cndmask_b32_e32 v51, v213, v51, vcc
	v_cmp_lt_u32_e32 vcc, s79, v32
	s_and_b64 vcc, vcc, s[6:7]
	v_sub_u32_e32 v32, v98, v92
	s_add_i32 s28, s27, 6
	v_cndmask_b32_e32 v84, v213, v52, vcc
	v_cmp_lt_u32_e32 vcc, s79, v32
	v_lshl_or_b32 v32, s28, 4, v73
	v_max3_f32 v20, v18, s52, v19
	s_and_b64 vcc, vcc, s[6:7]
	v_sub_u32_e32 v34, v98, v32
	v_max3_f32 v20, v20, v21, v22
	v_cndmask_b32_e32 v85, v213, v53, vcc
	v_cmp_lt_u32_e32 vcc, s79, v34
	v_sub_u32_e32 v34, v32, v98
	v_max3_f32 v20, v20, v23, v24
	v_cndmask_b32_e32 v54, v213, v54, vcc
	v_cmp_gt_u32_e32 vcc, s84, v34
	v_sub_u32_e32 v34, v30, v32
	v_max3_f32 v20, v20, v25, v26
	v_cndmask_b32_e32 v55, v213, v55, vcc
	v_cmp_lt_u32_e32 vcc, s79, v34
	v_sub_u32_e32 v32, v31, v32
	v_max3_f32 v20, v20, v28, v29
	v_cndmask_b32_e32 v56, v213, v56, vcc
	v_cmp_lt_u32_e32 vcc, s79, v32
	v_sub_u32_e32 v32, v98, v93
	v_max3_f32 v20, v20, v44, v27
	v_cndmask_b32_e32 v57, v213, v57, vcc
	v_cmp_lt_u32_e32 vcc, s79, v32
	v_sub_u32_e32 v32, v98, v94
	v_max3_f32 v20, v20, v33, v35
	v_cndmask_b32_e32 v58, v213, v58, vcc
	v_cmp_lt_u32_e32 vcc, s79, v32
	v_sub_u32_e32 v32, v98, v95
	v_max3_f32 v20, v20, v66, v37
	v_cndmask_b32_e32 v59, v213, v59, vcc
	v_cmp_lt_u32_e32 vcc, s79, v32
	v_sub_u32_e32 v32, v98, v96
	s_or_b32 s27, s27, 8
	v_max3_f32 v20, v20, v67, v68
	v_cndmask_b32_e32 v60, v213, v60, vcc
	v_cmp_lt_u32_e32 vcc, s79, v32
	v_lshl_or_b32 v32, s27, 4, v73
	v_max3_f32 v20, v20, v40, v69
	v_sub_u32_e32 v34, v98, v32
	v_max3_f32 v20, v20, v83, v51
	v_cndmask_b32_e32 v61, v213, v61, vcc
	v_cmp_lt_u32_e32 vcc, s79, v34
	v_sub_u32_e32 v34, v32, v98
	v_max3_f32 v20, v20, v84, v85
	v_cndmask_b32_e32 v62, v213, v62, vcc
	v_cmp_gt_u32_e32 vcc, s84, v34
	v_sub_u32_e32 v30, v30, v32
	v_max3_f32 v20, v20, v54, v55
	v_cndmask_b32_e32 v63, v213, v63, vcc
	v_cmp_lt_u32_e32 vcc, s79, v30
	v_sub_u32_e32 v30, v31, v32
	v_max3_f32 v20, v20, v56, v57
	v_cndmask_b32_e32 v64, v213, v64, vcc
	v_cmp_lt_u32_e32 vcc, s79, v30
	v_sub_u32_e32 v30, v98, v82
	v_max3_f32 v20, v20, v58, v59
	v_subrev_u32_e32 v31, 48, v30
	v_max3_f32 v20, v20, v60, v61
	v_cndmask_b32_e32 v65, v213, v65, vcc
	v_cmp_gt_u32_e32 vcc, s84, v31
	v_subrev_u32_e32 v31, 49, v30
	v_max3_f32 v20, v20, v62, v63
	v_cndmask_b32_e32 v14, v213, v14, vcc
	v_cmp_gt_u32_e32 vcc, s84, v31
	v_max3_f32 v20, v20, v64, v65
	s_nop 0
	v_cndmask_b32_e32 v82, v213, v15, vcc
	v_max3_f32 v15, v20, v14, v82
	v_subrev_u32_e32 v20, 50, v30
	v_cmp_gt_u32_e32 vcc, s84, v20
	s_nop 1
	v_cndmask_b32_e32 v86, v213, v16, vcc
	v_subrev_u32_e32 v16, 51, v30
	v_cmp_gt_u32_e32 vcc, s84, v16
	s_nop 1
	v_cndmask_b32_e32 v87, v213, v17, vcc
	v_max3_f32 v15, v15, v86, v87
	ds_bpermute_b32 v16, v76, v15
	s_waitcnt lgkmcnt(0)
	v_max_f32_e32 v16, v16, v16
	v_max_f32_e32 v15, v15, v16
	ds_bpermute_b32 v16, v77, v15
	s_waitcnt lgkmcnt(0)
; __device__ __forceinline__ unsigned cvt_pk_bf16(float lo, float hi) { unsigned r; asm volatile("v_cvt_pk_bf16_f32 %0, %1, %2" : "=v"(r) : "v"(lo), "v"(hi)); return r; }
; #define LAS __attribute__((address_space(3)))
; #define MFMA16(a, b, c) __builtin_amdgcn_mfma_f32_16x16x32_bf16((a), (b), (c), 0, 0, 0)
; __device__ __forceinline__ void p2_block(LAS unsigned char* lds, const bf16_t* __restrict__ PROJ, bf16_t* __restrict__ ATT, bf16_t* __restrict__ SGU, const float* __restrict__ qn, const float* __restrict__ kn, ...
;     ...
;         mx = fmaxf(mx, __shfl_xor(mx, 16)); mx = fmaxf(mx, __shfl_xor(mx, 32)); mx = fmaxf(mx, sink);
;         float sum = 0.f;
; #pragma unroll
;         for (int t = 0; t < 10; ++t)
; #pragma unroll
;             for (int e = 0; e < 4; ++e) { const float p = __builtin_amdgcn_exp2f((sc_[t][e] - mx) * LOG2E); sc_[t][e] = p; sum += p; }
;         sum += __shfl_xor(sum, 16); sum += __shfl_xor(sum, 32);
;         const float inv = 1.0f / (sum + __builtin_amdgcn_exp2f((sink - mx) * LOG2E));
;         f32x4 o[4];
; #pragma unroll
;         for (int dt = 0; dt < 4; ++dt) o[dt] = (f32x4){0.f, 0.f, 0.f, 0.f};
; #pragma unroll
;         for (int j = 0; j < 5; ++j) {
;             u32x4 pw; pw.x = cvt_pk_bf16(sc_[2 * j][0], sc_[2 * j][1]); pw.y = cvt_pk_bf16(sc_[2 * j][2], sc_[2 * j][3]); pw.z = cvt_pk_bf16(sc_[2 * j + 1][0], sc_[2 * j + 1][1]); pw.w = cvt_pk_bf16(sc_[2 * j + 1][2], sc_[2 * j + 1][3]);
;             const bf16x8 pf = __builtin_bit_cast(bf16x8, pw);
; #pragma unroll
;             for (int dt = 0; dt < 4; ++dt) { const LAS unsigned char* vb = VT + (16 * dt + fr) * VT_STRIDE + (16 * (t0 + 2 * j) + 4 * fq) * 2;
;                 const u32x2 va = *(const LAS u32x2*)vb, vc = *(const LAS u32x2*)(vb + 32); u32x4 vw; vw.x = va.x; vw.y = va.y; vw.z = vc.x; vw.w = vc.y;
;                 o[dt] = MFMA16(__builtin_bit_cast(bf16x8, vw), pf, o[dt]); }
;         }
	v_max3_f32 v88, v15, v16, v75
	v_sub_f32_e32 v16, v19, v88
	v_mul_f32_e32 v16, 0x3fb8aa3b, v16
	v_exp_f32_e32 v36, v16
	v_sub_f32_e32 v16, v21, v88
	v_mul_f32_e32 v16, 0x3fb8aa3b, v16
	v_exp_f32_e32 v38, v16
	v_sub_f32_e32 v16, v22, v88
	v_mul_f32_e32 v16, 0x3fb8aa3b, v16
	v_exp_f32_e32 v50, v16
	v_sub_f32_e32 v16, v23, v88
	v_mul_f32_e32 v16, 0x3fb8aa3b, v16
	v_exp_f32_e32 v53, v16
	v_sub_f32_e32 v16, v24, v88
	v_mul_f32_e32 v16, 0x3fb8aa3b, v16
	v_exp_f32_e32 v89, v16
	v_sub_f32_e32 v16, v25, v88
	v_mul_f32_e32 v16, 0x3fb8aa3b, v16
	v_exp_f32_e32 v90, v16
	v_sub_f32_e32 v16, v26, v88
	v_mul_f32_e32 v16, 0x3fb8aa3b, v16
	v_exp_f32_e32 v91, v16
	v_sub_f32_e32 v16, v28, v88
	v_mul_f32_e32 v16, 0x3fb8aa3b, v16
	v_exp_f32_e32 v23, v16
	v_sub_f32_e32 v16, v29, v88
	v_mul_f32_e32 v16, 0x3fb8aa3b, v16
	v_exp_f32_e32 v31, v16
	v_sub_f32_e32 v16, v44, v88
	v_mul_f32_e32 v16, 0x3fb8aa3b, v16
	v_exp_f32_e32 v34, v16
	v_sub_f32_e32 v16, v27, v88
	v_mul_f32_e32 v16, 0x3fb8aa3b, v16
	v_sub_f32_e32 v15, v18, v88
	v_exp_f32_e32 v39, v16
	v_sub_f32_e32 v16, v33, v88
	v_mul_f32_e32 v15, 0x3fb8aa3b, v15
	v_mul_f32_e32 v16, 0x3fb8aa3b, v16
	v_exp_f32_e32 v32, v15
	v_exp_f32_e32 v41, v16
	v_sub_f32_e32 v16, v35, v88
	v_mul_f32_e32 v16, 0x3fb8aa3b, v16
	v_exp_f32_e32 v92, v16
	v_sub_f32_e32 v16, v66, v88
	v_mul_f32_e32 v16, 0x3fb8aa3b, v16
	v_add_f32_e32 v15, 0, v32
	v_exp_f32_e32 v93, v16
	v_sub_f32_e32 v16, v37, v88
	v_add_f32_e32 v15, v36, v15
	v_mul_f32_e32 v16, 0x3fb8aa3b, v16
	v_add_f32_e32 v15, v38, v15
	v_exp_f32_e32 v94, v16
	v_sub_f32_e32 v16, v67, v88
	v_add_f32_e32 v15, v50, v15
	v_mul_f32_e32 v16, 0x3fb8aa3b, v16
	v_add_f32_e32 v15, v53, v15
	v_exp_f32_e32 v19, v16
	v_sub_f32_e32 v16, v68, v88
	v_add_f32_e32 v15, v89, v15
	v_mul_f32_e32 v16, 0x3fb8aa3b, v16
	v_add_f32_e32 v15, v90, v15
	v_exp_f32_e32 v28, v16
	v_sub_f32_e32 v16, v40, v88
	v_add_f32_e32 v15, v91, v15
	v_mul_f32_e32 v16, 0x3fb8aa3b, v16
	v_add_f32_e32 v15, v23, v15
	v_exp_f32_e32 v29, v16
	v_sub_f32_e32 v16, v69, v88
	v_add_f32_e32 v15, v31, v15
	v_mul_f32_e32 v16, 0x3fb8aa3b, v16
	v_add_f32_e32 v15, v34, v15
	v_exp_f32_e32 v35, v16
	v_sub_f32_e32 v16, v83, v88
	v_add_f32_e32 v15, v39, v15
	v_mul_f32_e32 v16, 0x3fb8aa3b, v16
	v_add_f32_e32 v15, v41, v15
	v_exp_f32_e32 v37, v16
	v_sub_f32_e32 v16, v51, v88
	v_add_f32_e32 v15, v92, v15
	v_mul_f32_e32 v16, 0x3fb8aa3b, v16
	v_sub_f32_e32 v17, v55, v88
	v_add_f32_e32 v15, v93, v15
	v_exp_f32_e32 v52, v16
	v_sub_f32_e32 v16, v84, v88
	v_mul_f32_e32 v17, 0x3fb8aa3b, v17
	v_add_f32_e32 v15, v94, v15
	v_mul_f32_e32 v16, 0x3fb8aa3b, v16
	v_exp_f32_e32 v22, v17
	v_sub_f32_e32 v17, v56, v88
	v_add_f32_e32 v15, v19, v15
	v_exp_f32_e32 v95, v16
	v_sub_f32_e32 v16, v85, v88
	v_mul_f32_e32 v17, 0x3fb8aa3b, v17
	v_add_f32_e32 v15, v28, v15
	v_mul_f32_e32 v16, 0x3fb8aa3b, v16
	v_exp_f32_e32 v26, v17
	v_sub_f32_e32 v17, v57, v88
	v_add_f32_e32 v15, v29, v15
	v_exp_f32_e32 v96, v16
	v_sub_f32_e32 v16, v54, v88
	v_mul_f32_e32 v17, 0x3fb8aa3b, v17
	v_add_f32_e32 v15, v35, v15
	v_mul_f32_e32 v16, 0x3fb8aa3b, v16
	v_exp_f32_e32 v30, v17
	v_sub_f32_e32 v17, v58, v88
	v_add_f32_e32 v15, v37, v15
	v_exp_f32_e32 v16, v16
	v_mul_f32_e32 v17, 0x3fb8aa3b, v17
	v_add_f32_e32 v15, v52, v15
	v_exp_f32_e32 v33, v17
	v_sub_f32_e32 v17, v59, v88
	v_add_f32_e32 v15, v95, v15
	v_mul_f32_e32 v17, 0x3fb8aa3b, v17
	v_add_f32_e32 v15, v96, v15
	v_exp_f32_e32 v40, v17
	v_sub_f32_e32 v17, v60, v88
	v_add_f32_e32 v15, v16, v15
	v_mul_f32_e32 v17, 0x3fb8aa3b, v17
	v_add_f32_e32 v15, v22, v15
	v_exp_f32_e32 v51, v17
	v_sub_f32_e32 v17, v61, v88
	v_add_f32_e32 v15, v26, v15
	v_mul_f32_e32 v17, 0x3fb8aa3b, v17
	v_add_f32_e32 v15, v30, v15
	v_exp_f32_e32 v98, v17
	v_add_f32_e32 v15, v33, v15
	v_add_f32_e32 v15, v40, v15
	v_add_f32_e32 v15, v51, v15
	v_add_f32_e32 v17, v98, v15
	v_sub_f32_e32 v15, v62, v88
	v_mul_f32_e32 v15, 0x3fb8aa3b, v15
	v_exp_f32_e32 v15, v15
	v_sub_f32_e32 v14, v14, v88
	v_mul_f32_e32 v14, 0x3fb8aa3b, v14
	v_sub_f32_e32 v25, v86, v88
	v_add_f32_e32 v18, v15, v17
	v_sub_f32_e32 v17, v63, v88
	v_mul_f32_e32 v17, 0x3fb8aa3b, v17
	v_exp_f32_e32 v17, v17
	v_cvt_pk_bf16_f32 v54, v32, v36
	v_lshl_add_u32 v32, s4, 1, v74
	v_mul_f32_e32 v25, 0x3fb8aa3b, v25
	v_add_f32_e32 v20, v17, v18
	v_sub_f32_e32 v18, v64, v88
	v_mul_f32_e32 v18, 0x3fb8aa3b, v18
	v_exp_f32_e32 v18, v18
	v_sub_f32_e32 v27, v87, v88
	v_mad_u32_u24 v36, v137, s81, v32
	v_exp_f32_e32 v25, v25
	v_add_f32_e32 v21, v18, v20
	v_sub_f32_e32 v20, v65, v88
	v_mul_f32_e32 v20, 0x3fb8aa3b, v20
	v_exp_f32_e32 v20, v20
	v_mul_f32_e32 v27, 0x3fb8aa3b, v27
	v_add_u32_e32 v36, 0x9000, v36
	v_exp_f32_e32 v27, v27
	v_add_f32_e32 v24, v20, v21
	v_exp_f32_e32 v21, v14
	v_cvt_pk_bf16_f32 v55, v38, v50
	v_cvt_pk_bf16_f32 v56, v53, v89
	v_cvt_pk_bf16_f32 v57, v90, v91
	ds_read2_b64 v[58:61], v36 offset1:4
	v_add_f32_e32 v14, v21, v24
	v_sub_f32_e32 v24, v82, v88
	v_mul_f32_e32 v24, 0x3fb8aa3b, v24
	v_exp_f32_e32 v24, v24
	v_add_u32_e32 v36, v32, v80
	v_add_u32_e32 v36, 0x9000, v36
	ds_read2_b64 v[62:65], v36 offset1:4
	v_add_f32_e32 v14, v24, v14
	v_add_u32_e32 v36, v32, v79
	v_add_u32_e32 v32, v32, v78
	v_add_f32_e32 v14, v25, v14
	v_add_u32_e32 v36, 0x9000, v36
	v_add_u32_e32 v32, 0x9000, v32
	v_add_f32_e32 v14, v27, v14
	ds_read2_b64 v[66:69], v36 offset1:4
	ds_read2_b64 v[82:85], v32 offset1:4
	ds_bpermute_b32 v44, v76, v14
	s_waitcnt lgkmcnt(4)
	v_mfma_f32_16x16x32_bf16 v[58:61], v[58:61], v[54:57], 0
	s_or_b32 s4, s26, 48
	s_waitcnt lgkmcnt(0)
	v_add_f32_e32 v14, v14, v44
	ds_bpermute_b32 v44, v77, v14
	v_mfma_f32_16x16x32_bf16 v[62:65], v[62:65], v[54:57], 0
	s_waitcnt lgkmcnt(0)
; __device__ __forceinline__ unsigned cvt_pk_bf16(float lo, float hi) { unsigned r; asm volatile("v_cvt_pk_bf16_f32 %0, %1, %2" : "=v"(r) : "v"(lo), "v"(hi)); return r; }
; #define LAS __attribute__((address_space(3)))
; #define MFMA16(a, b, c) __builtin_amdgcn_mfma_f32_16x16x32_bf16((a), (b), (c), 0, 0, 0)
; __device__ __forceinline__ void unpack8(const u32x4 w, float* f) { f[0] = bf_lo(w.x); f[1] = bf_hi(w.x); f[2] = bf_lo(w.y); f[3] = bf_hi(w.y); f[4] = bf_lo(w.z); f[5] = bf_hi(w.z); f[6] = bf_lo(w.w); f[7] = bf_hi(w.w); }
; __device__ __forceinline__ void p2_block(LAS unsigned char* lds, const bf16_t* __restrict__ PROJ, bf16_t* __restrict__ ATT, bf16_t* __restrict__ SGU, const float* __restrict__ qn, const float* __restrict__ kn, ...
;     ...
;             float x1[8], x2[8]; unpack8(qa[c], x1); unpack8(qb[c], x2);
;             float ss = 0.f;
; #pragma unroll
;             for (int j = 0; j < 8; ++j) ss += x1[j] * x1[j] + x2[j] * x2[j];
;             ss += __shfl_xor(ss, 16); ss += __shfl_xor(ss, 32);
;     ...
;         const float inv = 1.0f / (sum + __builtin_amdgcn_exp2f((sink - mx) * LOG2E));
;         f32x4 o[4];
; #pragma unroll
;         for (int dt = 0; dt < 4; ++dt) o[dt] = (f32x4){0.f, 0.f, 0.f, 0.f};
; #pragma unroll
;         for (int j = 0; j < 5; ++j) {
;             u32x4 pw; pw.x = cvt_pk_bf16(sc_[2 * j][0], sc_[2 * j][1]); pw.y = cvt_pk_bf16(sc_[2 * j][2], sc_[2 * j][3]); pw.z = cvt_pk_bf16(sc_[2 * j + 1][0], sc_[2 * j + 1][1]); pw.w = cvt_pk_bf16(sc_[2 * j + 1][2], sc_[2 * j + 1][3]);
;             const bf16x8 pf = __builtin_bit_cast(bf16x8, pw);
; #pragma unroll
;             for (int dt = 0; dt < 4; ++dt) { const LAS unsigned char* vb = VT + (16 * dt + fr) * VT_STRIDE + (16 * (t0 + 2 * j) + 4 * fq) * 2;
;                 const u32x2 va = *(const LAS u32x2*)vb, vc = *(const LAS u32x2*)(vb + 32); u32x4 vw; vw.x = va.x; vw.y = va.y; vw.z = vc.x; vw.w = vc.y;
;                 o[dt] = MFMA16(__builtin_bit_cast(bf16x8, vw), pf, o[dt]); }
;         }
	v_add_f32_e32 v14, v14, v44
	v_mfma_f32_16x16x32_bf16 v[66:69], v[66:69], v[54:57], 0
	v_sub_f32_e32 v44, v75, v88
	v_mul_f32_e32 v44, 0x3fb8aa3b, v44
	v_exp_f32_e32 v44, v44
	v_mfma_f32_16x16x32_bf16 v[54:57], v[82:85], v[54:57], 0
	v_cvt_pk_bf16_f32 v82, v23, v31
	v_lshl_add_u32 v23, s40, 5, v74
	v_mad_u32_u24 v31, v137, s81, v23
	v_add_u32_e32 v31, 0x9000, v31
	v_cvt_pk_bf16_f32 v83, v34, v39
	v_cvt_pk_bf16_f32 v84, v41, v92
	v_cvt_pk_bf16_f32 v85, v93, v94
	ds_read2_b64 v[86:89], v31 offset1:4
	v_add_u32_e32 v31, v23, v80
	v_add_u32_e32 v31, 0x9000, v31
	s_waitcnt lgkmcnt(0)
	v_mfma_f32_16x16x32_bf16 v[58:61], v[86:89], v[82:85], v[58:61]
	ds_read2_b64 v[86:89], v31 offset1:4
	v_add_u32_e32 v31, v23, v79
	v_add_u32_e32 v31, 0x9000, v31
	s_waitcnt lgkmcnt(0)
	v_mfma_f32_16x16x32_bf16 v[62:65], v[86:89], v[82:85], v[62:65]
	ds_read2_b64 v[86:89], v31 offset1:4
	v_add_u32_e32 v23, v23, v78
	v_add_u32_e32 v23, 0x9000, v23
	s_waitcnt lgkmcnt(0)
	v_mfma_f32_16x16x32_bf16 v[66:69], v[86:89], v[82:85], v[66:69]
	ds_read2_b64 v[86:89], v23 offset1:4
	v_cvt_pk_bf16_f32 v34, v19, v28
	v_lshl_add_u32 v19, s29, 5, v74
	v_mad_u32_u24 v23, v137, s81, v19
	v_add_u32_e32 v23, 0x9000, v23
	s_waitcnt lgkmcnt(0)
	v_mfma_f32_16x16x32_bf16 v[54:57], v[86:89], v[82:85], v[54:57]
	v_cvt_pk_bf16_f32 v35, v29, v35
	v_cvt_pk_bf16_f32 v36, v37, v52
	v_cvt_pk_bf16_f32 v37, v95, v96
	ds_read2_b64 v[82:85], v23 offset1:4
	v_add_u32_e32 v23, v19, v80
	v_add_u32_e32 v23, 0x9000, v23
	s_waitcnt lgkmcnt(0)
	v_mfma_f32_16x16x32_bf16 v[58:61], v[82:85], v[34:37], v[58:61]
	ds_read2_b64 v[82:85], v23 offset1:4
	v_add_u32_e32 v23, v19, v79
	v_add_u32_e32 v23, 0x9000, v23
	s_waitcnt lgkmcnt(0)
	v_mfma_f32_16x16x32_bf16 v[62:65], v[82:85], v[34:37], v[62:65]
	ds_read2_b64 v[82:85], v23 offset1:4
	v_add_u32_e32 v19, v19, v78
	v_add_u32_e32 v19, 0x9000, v19
	s_waitcnt lgkmcnt(0)
	v_mfma_f32_16x16x32_bf16 v[66:69], v[82:85], v[34:37], v[66:69]
	ds_read2_b64 v[82:85], v19 offset1:4
	v_cvt_pk_bf16_f32 v28, v16, v22
	v_lshl_add_u32 v16, s28, 5, v74
	v_mad_u32_u24 v19, v137, s81, v16
	v_add_u32_e32 v19, 0x9000, v19
	v_cvt_pk_bf16_f32 v29, v26, v30
	v_cvt_pk_bf16_f32 v30, v33, v40
	v_cvt_pk_bf16_f32 v31, v51, v98
	ds_read2_b64 v[38:41], v19 offset1:4
	v_add_u32_e32 v19, v16, v80
	v_add_u32_e32 v19, 0x9000, v19
	ds_read2_b64 v[50:53], v19 offset1:4
	v_add_u32_e32 v19, v16, v79
	v_add_u32_e32 v16, v16, v78
	v_add_u32_e32 v19, 0x9000, v19
	v_add_u32_e32 v16, 0x9000, v16
	s_waitcnt lgkmcnt(2)
	v_mfma_f32_16x16x32_bf16 v[34:37], v[82:85], v[34:37], v[54:57]
	v_add_f32_e32 v14, v44, v14
	v_or_b32_e32 v44, s48, v97
	s_waitcnt lgkmcnt(1)
	v_mfma_f32_16x16x32_bf16 v[38:41], v[38:41], v[28:31], v[58:61]
	ds_read2_b64 v[54:57], v19 offset1:4
	s_nop 1
	ds_read2_b64 v[58:61], v16 offset1:4
	v_cvt_pk_bf16_f32 v16, v15, v17
	v_lshl_add_u32 v15, s27, 5, v74
	v_cvt_pk_bf16_f32 v17, v18, v20
	v_mad_u32_u24 v20, v137, s81, v15
	v_add_u32_e32 v20, 0x9000, v20
	v_cvt_pk_bf16_f32 v18, v21, v24
	v_cvt_pk_bf16_f32 v19, v25, v27
	ds_read2_b64 v[20:23], v20 offset1:4
	v_add_u32_e32 v32, v15, v79
	v_add_u32_e32 v24, v15, v80
	v_add_u32_e32 v32, 0x9000, v32
	s_waitcnt lgkmcnt(3)
	v_mfma_f32_16x16x32_bf16 v[50:53], v[50:53], v[28:31], v[62:65]
	v_add_u32_e32 v24, 0x9000, v24
	ds_read2_b64 v[24:27], v24 offset1:4
	v_add_u32_e32 v15, v15, v78
	s_waitcnt lgkmcnt(3)
	v_mfma_f32_16x16x32_bf16 v[54:57], v[54:57], v[28:31], v[66:69]
	v_add_u32_e32 v15, 0x9000, v15
	v_or_b32_e32 v63, s4, v137
	v_or_b32_e32 v62, s17, v63
	s_waitcnt lgkmcnt(2)
	v_mfma_f32_16x16x32_bf16 v[28:31], v[58:61], v[28:31], v[34:37]
	v_lshlrev_b32_e32 v60, 16, v6
	v_and_b32_e32 v61, 0xffff0000, v6
	v_lshlrev_b32_e32 v58, 16, v10
	ds_read2_b64 v[32:35], v32 offset1:4
	s_waitcnt lgkmcnt(2)
	v_mfma_f32_16x16x32_bf16 v[20:23], v[20:23], v[16:19], v[38:41]
	v_and_b32_e32 v59, 0xffff0000, v10
	s_lshr_b32 s17, s4, 4
	s_min_u32 s17, s17, 6
	ds_read2_b64 v[36:39], v15 offset1:4
	s_waitcnt lgkmcnt(1)
	v_mfma_f32_16x16x32_bf16 v[32:35], v[32:35], v[16:19], v[54:57]
	s_nop 2
	v_lshlrev_b32_e32 v57, 16, v7
	v_and_b32_e32 v56, 0xffff0000, v7
	v_pk_mul_f32 v[6:7], v[60:61], v[60:61]
	v_mfma_f32_16x16x32_bf16 v[24:27], v[24:27], v[16:19], v[50:53]
	v_lshlrev_b32_e32 v55, 16, v11
	v_and_b32_e32 v54, 0xffff0000, v11
	v_lshlrev_b32_e32 v41, 16, v9
	v_lshlrev_b32_e32 v53, 16, v8
	v_and_b32_e32 v52, 0xffff0000, v8
	v_and_b32_e32 v40, 0xffff0000, v9
	v_pk_fma_f32 v[6:7], v[58:59], v[58:59], v[6:7]
	v_pk_mul_f32 v[8:9], v[56:57], v[56:57]
	v_add_f32_e32 v6, v6, v7
	v_pk_fma_f32 v[8:9], v[54:55], v[54:55], v[8:9]
	v_lshlrev_b32_e32 v51, 16, v12
	v_and_b32_e32 v50, 0xffff0000, v12
	v_pk_mul_f32 v[10:11], v[52:53], v[52:53]
	v_add_f32_e32 v6, v9, v6
	v_pk_fma_f32 v[10:11], v[50:51], v[50:51], v[10:11]
	v_add_f32_e32 v6, v8, v6
	s_waitcnt lgkmcnt(0)
	v_mfma_f32_16x16x32_bf16 v[16:19], v[36:39], v[16:19], v[28:31]
	v_lshlrev_b32_e32 v39, 16, v13
	v_and_b32_e32 v38, 0xffff0000, v13
	v_pk_mul_f32 v[12:13], v[40:41], v[40:41]
	v_add_f32_e32 v6, v11, v6
	v_pk_fma_f32 v[12:13], v[38:39], v[38:39], v[12:13]
	v_add_f32_e32 v6, v10, v6
	v_add_f32_e32 v6, v13, v6
	v_add_f32_e32 v6, v12, v6
	v_div_scale_f32 v15, s[28:29], v14, v14, 1.0
	ds_bpermute_b32 v7, v76, v6
	v_rcp_f32_e32 v28, v15
	s_lshl_b32 s28, s17, 4
	s_add_i32 s26, s28, 16
	s_add_i32 s27, s17, 2
	v_fma_f32 v29, -v15, v28, 1.0
	s_waitcnt lgkmcnt(0)
	v_add_f32_e32 v6, v6, v7
	v_fmac_f32_e32 v28, v29, v28
	v_div_scale_f32 v29, vcc, 1.0, v14, 1.0
	ds_bpermute_b32 v7, v77, v6
	v_mul_f32_e32 v30, v29, v28
	v_fma_f32 v31, -v15, v30, v29
	v_fmac_f32_e32 v30, v31, v28
	v_fma_f32 v15, -v15, v30, v29
	v_div_fmas_f32 v15, v15, v28, v30
	s_waitcnt lgkmcnt(0)
; #define LAS __attribute__((address_space(3)))
; #define MFMA16(a, b, c) __builtin_amdgcn_mfma_f32_16x16x32_bf16((a), (b), (c), 0, 0, 0)
; __device__ __forceinline__ void p2_block(LAS unsigned char* lds, const bf16_t* __restrict__ PROJ, bf16_t* __restrict__ ATT, bf16_t* __restrict__ SGU, const float* __restrict__ qn, const float* __restrict__ kn, ...
;     ...
;         const int i0 = rbase + 16 * c, irow = i0 + fr, pos = n * 128 + irow; const size_t grow = (size_t)b * pg8::SEQ + pos;
;         bf16x8 qf0, qf1;
;         {
;             float x1[8], x2[8]; unpack8(qa[c], x1); unpack8(qb[c], x2);
;             float ss = 0.f;
; #pragma unroll
;             for (int j = 0; j < 8; ++j) ss += x1[j] * x1[j] + x2[j] * x2[j];
;             ss += __shfl_xor(ss, 16); ss += __shfl_xor(ss, 32);
;             const float rinv = rsqrtf(ss * (1.0f / 64.0f) + pg8::EPS) * 0.125f;
;             const float* cp = COS + pos * 32 + 8 * fq; const float* sp = SIN + pos * 32 + 8 * fq;
;             float o1[8], o2[8];
; #pragma unroll
;             for (int j = 0; j < 8; ++j) { const float a1 = x1[j] * rinv * qn[8 * fq + j], a2 = x2[j] * rinv * qn[32 + 8 * fq + j], cc = cp[j], sn = sp[j]; o1[j] = a1 * cc - a2 * sn; o2[j] = a2 * cc + a1 * sn; }
;             u32x4 w0, w1;
;             w0.x = cvt_pk_bf16(o1[0], o1[1]); w0.y = cvt_pk_bf16(o1[2], o1[3]); w0.z = cvt_pk_bf16(o1[4], o1[5]); w0.w = cvt_pk_bf16(o1[6], o1[7]);
;             w1.x = cvt_pk_bf16(o2[0], o2[1]); w1.y = cvt_pk_bf16(o2[2], o2[3]); w1.z = cvt_pk_bf16(o2[4], o2[5]); w1.w = cvt_pk_bf16(o2[6], o2[7]);
;             qf0 = __builtin_bit_cast(bf16x8, w0); qf1 = __builtin_bit_cast(bf16x8, w1);
;         }
;         const int t0 = (i0 >> 4) < 6 ? (i0 >> 4) : 6;
;         f32x4 sc_[10];
;         const LAS unsigned char* kbase = KS + (16 * t0 + fr) * KS_STRIDE + 16 * fq;
; #pragma unroll
;         for (int t = 0; t < 10; ++t) { const bf16x8 k0 = *(const LAS bf16x8*)(kbase + t * 16 * KS_STRIDE), k1 = *(const LAS bf16x8*)(kbase + t * 16 * KS_STRIDE + 64);
;             f32x4 z = (f32x4){0.f, 0.f, 0.f, 0.f}; z = MFMA16(k0, qf0, z); sc_[t] = MFMA16(k1, qf1, z); }
;     ...
;         bf16_t* op = ATT + grow * 1024 + hq * 64 + 4 * fq;
; #pragma unroll
;         for (int dt = 0; dt < 4; ++dt) { u32x2 ow; ow.x = cvt_pk_bf16(o[dt][0] * inv, o[dt][1] * inv); ow.y = cvt_pk_bf16(o[dt][2] * inv, o[dt][3] * inv); *(u32x2*)(op + 16 * dt) = ow; }
	v_add_f32_e32 v6, v6, v7
	v_div_fixup_f32 v28, v15, v14, 1.0
	v_fmamk_f32 v6, v6, 0x3c800000, v209
	v_mul_f32_e32 v20, v28, v20
	v_mul_f32_e32 v21, v28, v21
	v_cmp_gt_f32_e32 vcc, s82, v6
	v_mul_f32_e32 v7, 0x4b800000, v6
	v_lshlrev_b64 v[14:15], 11, v[44:45]
	v_cvt_pk_bf16_f32 v20, v20, v21
	v_mul_f32_e32 v21, v28, v22
	v_cndmask_b32_e32 v6, v6, v7, vcc
	v_lshl_add_u64 v[14:15], v[42:43], 0, v[14:15]
	v_mul_f32_e32 v22, v28, v23
	v_cvt_pk_bf16_f32 v21, v21, v22
	v_rsq_f32_e32 v6, v6
	global_store_dwordx2 v[14:15], v[20:21], off
	v_mul_f32_e32 v20, v28, v24
	v_mul_f32_e32 v21, v28, v25
	v_cvt_pk_bf16_f32 v20, v20, v21
	v_mul_f32_e32 v21, v28, v26
	v_mul_f32_e32 v22, v28, v27
	v_cvt_pk_bf16_f32 v21, v21, v22
	global_store_dwordx2 v[14:15], v[20:21], off offset:32
	v_mul_f32_e32 v20, v28, v32
	v_mul_f32_e32 v21, v28, v33
	v_mul_f32_e32 v7, 0x45800000, v6
	v_cvt_pk_bf16_f32 v20, v20, v21
	v_mul_f32_e32 v21, v28, v34
	v_mul_f32_e32 v16, v28, v16
	v_mul_f32_e32 v17, v28, v17
	v_cndmask_b32_e32 v6, v6, v7, vcc
	v_mul_f32_e32 v22, v28, v35
	v_cvt_pk_bf16_f32 v21, v21, v22
	global_store_dwordx2 v[14:15], v[20:21], off offset:64
	v_cvt_pk_bf16_f32 v16, v16, v17
	v_mul_f32_e32 v17, v28, v18
	v_mul_f32_e32 v18, v28, v19
	v_mul_f32_e32 v44, 0x3e000000, v6
	v_lshlrev_b32_e32 v6, 7, v62
	v_mov_b32_e32 v7, v1
	v_cvt_pk_bf16_f32 v17, v17, v18
	global_store_dwordx2 v[14:15], v[16:17], off offset:96
	v_lshl_add_u64 v[18:19], v[46:47], 0, v[6:7]
	v_lshl_add_u64 v[34:35], v[48:49], 0, v[6:7]
	global_load_dwordx4 v[6:9], v0, s[38:39] offset:16
	global_load_dwordx4 v[22:25], v0, s[38:39]
	global_load_dwordx4 v[10:13], v0, s[38:39] offset:144
	global_load_dwordx4 v[30:33], v0, s[38:39] offset:128
	global_load_dwordx4 v[14:17], v[18:19], off offset:16
	global_load_dwordx4 v[26:29], v[18:19], off
	s_nop 0
	global_load_dwordx4 v[18:21], v[34:35], off offset:16
	s_nop 0
	global_load_dwordx4 v[34:37], v[34:35], off
	v_mov_b32_e32 v46, v60
	v_mov_b32_e32 v47, v58
	v_pk_mul_f32 v[46:47], v[44:45], v[46:47] op_sel_hi:[0,1]
	v_mov_b32_e32 v58, v61
	s_waitcnt vmcnt(6)
	v_mov_b32_e32 v49, v22
	s_waitcnt vmcnt(4)
	v_mov_b32_e32 v48, v30
	v_pk_mul_f32 v[46:47], v[48:49], v[46:47]
	s_waitcnt vmcnt(2)
	v_mov_b32_e32 v49, v26
	v_mov_b32_e32 v22, v31
	s_waitcnt vmcnt(0)
	v_mov_b32_e32 v48, v34
	v_pk_mul_f32 v[48:49], v[48:49], v[46:47]
	s_nop 0
	v_sub_f32_e32 v60, v49, v48
	v_mov_b32_e32 v48, v26
	v_mov_b32_e32 v49, v34
	v_pk_mul_f32 v[46:47], v[48:49], v[46:47]
	v_mov_b32_e32 v26, v35
	v_add_f32_e32 v48, v46, v47
	v_pk_mul_f32 v[46:47], v[44:45], v[58:59] op_sel_hi:[0,1]
	v_pk_mul_f32 v[22:23], v[22:23], v[46:47]
	v_mov_b32_e32 v34, v27
	v_pk_mul_f32 v[30:31], v[26:27], v[22:23]
	v_pk_mul_f32 v[22:23], v[34:35], v[22:23]
	v_sub_f32_e32 v30, v31, v30
	v_add_f32_e32 v31, v22, v23
	v_mov_b32_e32 v22, v57
	v_mov_b32_e32 v23, v55
	v_pk_mul_f32 v[22:23], v[44:45], v[22:23] op_sel_hi:[0,1]
	v_mov_b32_e32 v26, v32
	v_mov_b32_e32 v27, v24
	v_pk_mul_f32 v[22:23], v[26:27], v[22:23]
	v_mov_b32_e32 v26, v36
	v_mov_b32_e32 v27, v28
	v_pk_mul_f32 v[26:27], v[26:27], v[22:23]
	v_mov_b32_e32 v57, v54
	v_sub_f32_e32 v32, v27, v26
	v_mov_b32_e32 v26, v28
	v_mov_b32_e32 v27, v36
	v_pk_mul_f32 v[22:23], v[26:27], v[22:23]
	v_mov_b32_e32 v24, v33
	v_add_f32_e32 v26, v22, v23
	v_pk_mul_f32 v[22:23], v[44:45], v[56:57] op_sel_hi:[0,1]
	v_pk_mul_f32 v[22:23], v[22:23], v[24:25]
	v_mov_b32_e32 v28, v37
	v_mov_b32_e32 v36, v29
	v_pk_mul_f32 v[24:25], v[22:23], v[28:29]
	v_pk_mul_f32 v[22:23], v[22:23], v[36:37]
	v_sub_f32_e32 v27, v25, v24
	v_add_f32_e32 v28, v22, v23
	v_mov_b32_e32 v22, v53
	v_mov_b32_e32 v23, v51
	v_pk_mul_f32 v[22:23], v[44:45], v[22:23] op_sel_hi:[0,1]
	v_mov_b32_e32 v24, v10
	v_mov_b32_e32 v25, v6
	v_pk_mul_f32 v[22:23], v[22:23], v[24:25]
	v_mov_b32_e32 v24, v18
	v_mov_b32_e32 v25, v14
	v_pk_mul_f32 v[24:25], v[22:23], v[24:25]
	v_mov_b32_e32 v53, v50
	v_sub_f32_e32 v29, v25, v24
	v_mov_b32_e32 v24, v14
	v_mov_b32_e32 v25, v18
	v_pk_mul_f32 v[22:23], v[22:23], v[24:25]
	v_mov_b32_e32 v6, v11
	v_add_f32_e32 v24, v22, v23
	v_pk_mul_f32 v[22:23], v[44:45], v[52:53] op_sel_hi:[0,1]
	v_pk_mul_f32 v[6:7], v[22:23], v[6:7]
	v_mov_b32_e32 v14, v19
	v_mov_b32_e32 v18, v15
	v_pk_mul_f32 v[10:11], v[6:7], v[14:15]
	v_pk_mul_f32 v[6:7], v[6:7], v[18:19]
	v_sub_f32_e32 v14, v11, v10
	v_add_f32_e32 v15, v6, v7
	v_mov_b32_e32 v6, v41
	v_mov_b32_e32 v7, v39
	v_pk_mul_f32 v[6:7], v[44:45], v[6:7] op_sel_hi:[0,1]
	v_mov_b32_e32 v10, v12
	v_mov_b32_e32 v11, v8
	v_pk_mul_f32 v[6:7], v[6:7], v[10:11]
	v_mov_b32_e32 v10, v20
	v_mov_b32_e32 v11, v16
	v_pk_mul_f32 v[10:11], v[6:7], v[10:11]
	v_mov_b32_e32 v41, v38
	v_sub_f32_e32 v12, v11, v10
	v_mov_b32_e32 v10, v16
	v_mov_b32_e32 v11, v20
	v_pk_mul_f32 v[6:7], v[6:7], v[10:11]
	v_mov_b32_e32 v8, v13
	v_add_f32_e32 v18, v6, v7
	v_pk_mul_f32 v[6:7], v[44:45], v[40:41] op_sel_hi:[0,1]
	v_pk_mul_f32 v[6:7], v[6:7], v[8:9]
	v_mov_b32_e32 v16, v21
	v_mov_b32_e32 v20, v17
	v_pk_mul_f32 v[8:9], v[6:7], v[16:17]
	v_pk_mul_f32 v[6:7], v[6:7], v[20:21]
	v_sub_f32_e32 v9, v9, v8
	v_add_f32_e32 v13, v6, v7
	v_cvt_pk_bf16_f32 v6, v60, v30
	v_cvt_pk_bf16_f32 v7, v32, v27
	v_cvt_pk_bf16_f32 v8, v29, v14
	v_or_b32_e32 v14, s28, v137
	v_mad_u32_u24 v44, v14, s59, v81
	v_cvt_pk_bf16_f32 v9, v12, v9
	v_cvt_pk_bf16_f32 v10, v48, v31
	v_cvt_pk_bf16_f32 v11, v26, v28
	v_cvt_pk_bf16_f32 v12, v24, v15
	v_cvt_pk_bf16_f32 v13, v18, v13
	ds_read_b128 v[14:17], v44
	ds_read_b128 v[18:21], v44 offset:64
	s_waitcnt lgkmcnt(1)
	v_mfma_f32_16x16x32_bf16 v[14:17], v[14:17], v[6:9], 0
	s_waitcnt lgkmcnt(0)
; #define LAS __attribute__((address_space(3)))
; #define MFMA16(a, b, c) __builtin_amdgcn_mfma_f32_16x16x32_bf16((a), (b), (c), 0, 0, 0)
; __device__ __forceinline__ void p2_block(LAS unsigned char* lds, const bf16_t* __restrict__ PROJ, bf16_t* __restrict__ ATT, bf16_t* __restrict__ SGU, const float* __restrict__ qn, const float* __restrict__ kn, ...
;     ...
;         const int t0 = (i0 >> 4) < 6 ? (i0 >> 4) : 6;
;         f32x4 sc_[10];
;         const LAS unsigned char* kbase = KS + (16 * t0 + fr) * KS_STRIDE + 16 * fq;
; #pragma unroll
;         for (int t = 0; t < 10; ++t) { const bf16x8 k0 = *(const LAS bf16x8*)(kbase + t * 16 * KS_STRIDE), k1 = *(const LAS bf16x8*)(kbase + t * 16 * KS_STRIDE + 64);
;             f32x4 z = (f32x4){0.f, 0.f, 0.f, 0.f}; z = MFMA16(k0, qf0, z); sc_[t] = MFMA16(k1, qf1, z); }
;         float mx = -1e30f;
; #pragma unroll
;         for (int t = 0; t < 10; ++t)
; #pragma unroll
;             for (int e = 0; e < 4; ++e) { const int kx = 16 * (t0 + t) + 4 * fq + e, d = kx - irow; const bool ok = (d >= 1) && (d <= 128) && (n > 0 || kx >= 128);
;                 const float v = ok ? sc_[t][e] : -1e30f; sc_[t][e] = v; mx = fmaxf(mx, v); }
	v_mfma_f32_16x16x32_bf16 v[14:17], v[18:21], v[10:13], v[14:17]
	ds_read_b128 v[18:21], v44 offset:2304
	ds_read_b128 v[22:25], v44 offset:2368
	s_waitcnt lgkmcnt(1)
	v_mfma_f32_16x16x32_bf16 v[18:21], v[18:21], v[6:9], 0
	s_waitcnt lgkmcnt(0)
	v_mfma_f32_16x16x32_bf16 v[18:21], v[22:25], v[10:13], v[18:21]
	ds_read_b128 v[22:25], v44 offset:4608
	ds_read_b128 v[26:29], v44 offset:4672
	s_waitcnt lgkmcnt(1)
	v_mfma_f32_16x16x32_bf16 v[22:25], v[22:25], v[6:9], 0
	s_waitcnt lgkmcnt(0)
	v_mfma_f32_16x16x32_bf16 v[22:25], v[26:29], v[10:13], v[22:25]
	ds_read_b128 v[26:29], v44 offset:6912
	ds_read_b128 v[30:33], v44 offset:6976
	s_waitcnt lgkmcnt(1)
	v_mfma_f32_16x16x32_bf16 v[26:29], v[26:29], v[6:9], 0
	s_waitcnt lgkmcnt(0)
	v_mfma_f32_16x16x32_bf16 v[26:29], v[30:33], v[10:13], v[26:29]
	ds_read_b128 v[30:33], v44 offset:9216
	ds_read_b128 v[34:37], v44 offset:9280
	s_waitcnt lgkmcnt(1)
	v_mfma_f32_16x16x32_bf16 v[30:33], v[30:33], v[6:9], 0
	s_waitcnt lgkmcnt(0)
	v_mfma_f32_16x16x32_bf16 v[30:33], v[34:37], v[10:13], v[30:33]
	ds_read_b128 v[34:37], v44 offset:11520
	ds_read_b128 v[38:41], v44 offset:11584
	s_waitcnt lgkmcnt(1)
	v_mfma_f32_16x16x32_bf16 v[34:37], v[34:37], v[6:9], 0
	s_waitcnt lgkmcnt(0)
	v_mfma_f32_16x16x32_bf16 v[34:37], v[38:41], v[10:13], v[34:37]
	ds_read_b128 v[38:41], v44 offset:13824
	ds_read_b128 v[46:49], v44 offset:13888
	s_waitcnt lgkmcnt(1)
	v_mfma_f32_16x16x32_bf16 v[38:41], v[38:41], v[6:9], 0
	s_waitcnt lgkmcnt(0)
	v_mfma_f32_16x16x32_bf16 v[38:41], v[46:49], v[10:13], v[38:41]
	ds_read_b128 v[46:49], v44 offset:16128
	ds_read_b128 v[50:53], v44 offset:16192
	s_waitcnt lgkmcnt(1)
	v_mfma_f32_16x16x32_bf16 v[46:49], v[46:49], v[6:9], 0
	s_waitcnt lgkmcnt(0)
	v_mfma_f32_16x16x32_bf16 v[46:49], v[50:53], v[10:13], v[46:49]
	ds_read_b128 v[50:53], v44 offset:18432
	ds_read_b128 v[54:57], v44 offset:18496
	s_waitcnt lgkmcnt(1)
	v_mfma_f32_16x16x32_bf16 v[50:53], v[50:53], v[6:9], 0
	s_waitcnt lgkmcnt(0)
	v_mfma_f32_16x16x32_bf16 v[50:53], v[54:57], v[10:13], v[50:53]
	ds_read_b128 v[54:57], v44 offset:20736
	ds_read_b128 v[58:61], v44 offset:20800
	s_waitcnt lgkmcnt(1)
	v_mfma_f32_16x16x32_bf16 v[6:9], v[54:57], v[6:9], 0
	s_waitcnt lgkmcnt(0)
	v_mfma_f32_16x16x32_bf16 v[6:9], v[58:61], v[10:13], v[6:9]
	v_or_b32_e32 v10, s28, v73
	v_sub_u32_e32 v11, v63, v10
	v_cmp_lt_u32_e32 vcc, s79, v11
	s_and_b64 vcc, s[50:51], vcc
	v_sub_u32_e32 v12, v10, v63
	v_cndmask_b32_e32 v11, v213, v14, vcc
	v_cmp_gt_u32_e32 vcc, s84, v12
	s_and_b64 vcc, s[50:51], vcc
	v_add_u32_e32 v14, -2, v63
	v_cndmask_b32_e32 v12, v213, v15, vcc
	v_sub_u32_e32 v15, v14, v10
	v_cmp_lt_u32_e32 vcc, s79, v15
	s_and_b64 vcc, s[50:51], vcc
	v_max3_f32 v13, v11, s52, v12
	v_cndmask_b32_e32 v15, v213, v16, vcc
	v_add_u32_e32 v16, -3, v63
	v_sub_u32_e32 v10, v16, v10
	v_cmp_lt_u32_e32 vcc, s79, v10
	s_and_b64 vcc, s[50:51], vcc
	s_nop 0
	v_cndmask_b32_e32 v10, v213, v17, vcc
	v_or_b32_e32 v17, s26, v73
	v_sub_u32_e32 v44, v63, v17
	v_cmp_lt_u32_e32 vcc, s79, v44
	s_and_b64 vcc, s[50:51], vcc
	v_sub_u32_e32 v44, v17, v63
	v_cndmask_b32_e32 v18, v213, v18, vcc
	v_cmp_gt_u32_e32 vcc, s84, v44
	s_and_b64 vcc, s[50:51], vcc
	v_sub_u32_e32 v44, v14, v17
	v_cndmask_b32_e32 v19, v213, v19, vcc
	v_cmp_lt_u32_e32 vcc, s79, v44
	s_and_b64 vcc, s[50:51], vcc
	v_sub_u32_e32 v17, v16, v17
	v_cndmask_b32_e32 v20, v213, v20, vcc
	v_cmp_lt_u32_e32 vcc, s79, v17
	s_and_b64 vcc, s[50:51], vcc
	s_cmpk_gt_u32 s4, 0x50
	v_cndmask_b32_e32 v17, v213, v21, vcc
	v_lshl_or_b32 v21, s27, 4, v73
	v_sub_u32_e32 v44, v63, v21
	s_cselect_b64 s[40:41], -1, 0
	v_cmp_lt_u32_e32 vcc, s79, v44
	s_or_b64 s[40:41], s[50:51], s[40:41]
	s_and_b64 vcc, vcc, s[40:41]
	v_sub_u32_e32 v44, v21, v63
	v_cndmask_b32_e32 v22, v213, v22, vcc
	v_cmp_gt_u32_e32 vcc, s84, v44
	s_and_b64 vcc, vcc, s[40:41]
	v_sub_u32_e32 v44, v14, v21
	v_cndmask_b32_e32 v23, v213, v23, vcc
	v_cmp_lt_u32_e32 vcc, s79, v44
	s_and_b64 vcc, vcc, s[40:41]
	v_sub_u32_e32 v21, v16, v21
	v_cndmask_b32_e32 v44, v213, v24, vcc
	v_cmp_lt_u32_e32 vcc, s79, v21
	s_and_b64 vcc, vcc, s[40:41]
	s_add_i32 s26, s28, 48
	v_or_b32_e32 v21, s26, v73
	s_cmp_gt_u32 s4, 64
	v_sub_u32_e32 v24, v63, v21
	s_cselect_b64 s[40:41], -1, 0
	v_cndmask_b32_e32 v25, v213, v25, vcc
	v_cmp_lt_u32_e32 vcc, s79, v24
	s_or_b64 s[40:41], s[50:51], s[40:41]
	s_and_b64 vcc, vcc, s[40:41]
	v_sub_u32_e32 v24, v21, v63
	v_cndmask_b32_e32 v54, v213, v26, vcc
	v_cmp_gt_u32_e32 vcc, s84, v24
	s_and_b64 vcc, vcc, s[40:41]
	v_sub_u32_e32 v24, v14, v21
	v_cndmask_b32_e32 v27, v213, v27, vcc
	v_cmp_lt_u32_e32 vcc, s79, v24
	s_and_b64 vcc, vcc, s[40:41]
	v_sub_u32_e32 v21, v16, v21
	s_add_i32 s26, s17, 4
	v_cndmask_b32_e32 v55, v213, v28, vcc
	v_cmp_lt_u32_e32 vcc, s79, v21
	v_lshl_or_b32 v21, s26, 4, v73
	s_and_b64 vcc, vcc, s[40:41]
	v_sub_u32_e32 v24, v63, v21
	v_cndmask_b32_e32 v29, v213, v29, vcc
	v_cmp_lt_u32_e32 vcc, s79, v24
	s_and_b64 vcc, vcc, s[6:7]
	v_sub_u32_e32 v24, v21, v63
	v_cndmask_b32_e32 v56, v213, v30, vcc
	v_cmp_gt_u32_e32 vcc, s84, v24
	s_and_b64 vcc, vcc, s[6:7]
	v_sub_u32_e32 v24, v14, v21
	v_cndmask_b32_e32 v57, v213, v31, vcc
	v_cmp_lt_u32_e32 vcc, s79, v24
	s_and_b64 vcc, vcc, s[6:7]
	v_sub_u32_e32 v21, v16, v21
	s_add_i32 s4, s28, 0x50
	v_cndmask_b32_e32 v32, v213, v32, vcc
	v_cmp_lt_u32_e32 vcc, s79, v21
	v_or_b32_e32 v21, s4, v73
	s_and_b64 vcc, vcc, s[6:7]
	v_sub_u32_e32 v24, v63, v21
	v_cndmask_b32_e32 v58, v213, v33, vcc
	v_cmp_lt_u32_e32 vcc, s79, v24
	v_sub_u32_e32 v24, v21, v63
	s_add_i32 s6, s17, 6
	v_cndmask_b32_e32 v59, v213, v34, vcc
	v_cmp_gt_u32_e32 vcc, s84, v24
	v_sub_u32_e32 v24, v14, v21
	v_sub_u32_e32 v21, v16, v21
; __device__ __forceinline__ void p2_block(LAS unsigned char* lds, const bf16_t* __restrict__ PROJ, bf16_t* __restrict__ ATT, bf16_t* __restrict__ SGU, const float* __restrict__ qn, const float* __restrict__ kn, ...
;     ...
;         float mx = -1e30f;
; #pragma unroll
;         for (int t = 0; t < 10; ++t)
; #pragma unroll
;             for (int e = 0; e < 4; ++e) { const int kx = 16 * (t0 + t) + 4 * fq + e, d = kx - irow; const bool ok = (d >= 1) && (d <= 128) && (n > 0 || kx >= 128);
;                 const float v = ok ? sc_[t][e] : -1e30f; sc_[t][e] = v; mx = fmaxf(mx, v); }
;         mx = fmaxf(mx, __shfl_xor(mx, 16)); mx = fmaxf(mx, __shfl_xor(mx, 32)); mx = fmaxf(mx, sink);
;         float sum = 0.f;
; #pragma unroll
;         for (int t = 0; t < 10; ++t)
; #pragma unroll
;             for (int e = 0; e < 4; ++e) { const float p = __builtin_amdgcn_exp2f((sc_[t][e] - mx) * LOG2E); sc_[t][e] = p; sum += p; }
	v_cndmask_b32_e32 v35, v213, v35, vcc
	v_cmp_lt_u32_e32 vcc, s79, v24
	v_max3_f32 v13, v13, v15, v10
	v_max3_f32 v13, v13, v18, v19
	v_cndmask_b32_e32 v60, v213, v36, vcc
	v_cmp_lt_u32_e32 vcc, s79, v21
	v_lshl_or_b32 v21, s6, 4, v73
	v_sub_u32_e32 v24, v63, v21
	v_cndmask_b32_e32 v61, v213, v37, vcc
	v_cmp_lt_u32_e32 vcc, s79, v24
	v_sub_u32_e32 v24, v21, v63
	s_add_i32 s4, s28, 0x70
	v_cndmask_b32_e32 v38, v213, v38, vcc
	v_cmp_gt_u32_e32 vcc, s84, v24
	v_sub_u32_e32 v24, v14, v21
	v_sub_u32_e32 v21, v16, v21
	v_cndmask_b32_e32 v39, v213, v39, vcc
	v_cmp_lt_u32_e32 vcc, s79, v24
	v_max3_f32 v13, v13, v20, v17
	v_max3_f32 v13, v13, v22, v23
	v_cndmask_b32_e32 v40, v213, v40, vcc
	v_cmp_lt_u32_e32 vcc, s79, v21
	v_or_b32_e32 v21, s4, v73
	v_sub_u32_e32 v24, v63, v21
	v_max3_f32 v13, v13, v44, v25
	v_cndmask_b32_e32 v41, v213, v41, vcc
	v_cmp_lt_u32_e32 vcc, s79, v24
	v_sub_u32_e32 v24, v21, v63
	v_max3_f32 v13, v13, v54, v27
	v_cndmask_b32_e32 v46, v213, v46, vcc
	v_cmp_gt_u32_e32 vcc, s84, v24
	v_sub_u32_e32 v24, v14, v21
	v_max3_f32 v13, v13, v55, v29
	v_cndmask_b32_e32 v47, v213, v47, vcc
	v_cmp_lt_u32_e32 vcc, s79, v24
	v_sub_u32_e32 v21, v16, v21
	s_or_b32 s4, s17, 8
	v_max3_f32 v13, v13, v56, v57
	v_cndmask_b32_e32 v48, v213, v48, vcc
	v_cmp_lt_u32_e32 vcc, s79, v21
	v_lshl_or_b32 v21, s4, 4, v73
	v_max3_f32 v13, v13, v32, v58
	v_sub_u32_e32 v24, v63, v21
	v_max3_f32 v13, v13, v59, v35
	v_cndmask_b32_e32 v49, v213, v49, vcc
	v_cmp_lt_u32_e32 vcc, s79, v24
	v_sub_u32_e32 v24, v21, v63
	v_max3_f32 v13, v13, v60, v61
	v_cndmask_b32_e32 v50, v213, v50, vcc
	v_cmp_gt_u32_e32 vcc, s84, v24
	v_sub_u32_e32 v24, v14, v21
	v_max3_f32 v13, v13, v38, v39
	v_cndmask_b32_e32 v51, v213, v51, vcc
	v_cmp_lt_u32_e32 vcc, s79, v24
	v_sub_u32_e32 v21, v16, v21
	s_addk_i32 s28, 0x90
	v_max3_f32 v13, v13, v40, v41
	v_cndmask_b32_e32 v52, v213, v52, vcc
	v_cmp_lt_u32_e32 vcc, s79, v21
	v_or_b32_e32 v21, s28, v73
	v_max3_f32 v13, v13, v46, v47
	v_sub_u32_e32 v24, v63, v21
	v_max3_f32 v13, v13, v48, v49
	v_cndmask_b32_e32 v53, v213, v53, vcc
	v_cmp_lt_u32_e32 vcc, s79, v24
	v_sub_u32_e32 v24, v21, v63
	v_max3_f32 v13, v13, v50, v51
	v_cndmask_b32_e32 v6, v213, v6, vcc
	v_cmp_gt_u32_e32 vcc, s84, v24
	v_max3_f32 v13, v13, v52, v53
	s_nop 0
	v_cndmask_b32_e32 v63, v213, v7, vcc
	v_max3_f32 v7, v13, v6, v63
	v_sub_u32_e32 v13, v14, v21
	v_cmp_lt_u32_e32 vcc, s79, v13
	s_nop 1
	v_cndmask_b32_e32 v64, v213, v8, vcc
	v_sub_u32_e32 v8, v16, v21
	v_cmp_lt_u32_e32 vcc, s79, v8
	s_nop 1
	v_cndmask_b32_e32 v65, v213, v9, vcc
	v_max3_f32 v7, v7, v64, v65
	ds_bpermute_b32 v8, v76, v7
	s_waitcnt lgkmcnt(0)
	v_max_f32_e32 v8, v8, v8
	v_max_f32_e32 v7, v7, v8
	ds_bpermute_b32 v8, v77, v7
	s_waitcnt lgkmcnt(0)
	v_max3_f32 v66, v7, v8, v75
	v_sub_f32_e32 v8, v12, v66
	v_mul_f32_e32 v8, 0x3fb8aa3b, v8
	v_exp_f32_e32 v28, v8
	v_sub_f32_e32 v8, v15, v66
	v_mul_f32_e32 v8, 0x3fb8aa3b, v8
	v_exp_f32_e32 v30, v8
	v_sub_f32_e32 v8, v10, v66
	v_mul_f32_e32 v8, 0x3fb8aa3b, v8
	v_exp_f32_e32 v34, v8
	v_sub_f32_e32 v8, v18, v66
	v_mul_f32_e32 v8, 0x3fb8aa3b, v8
	v_exp_f32_e32 v37, v8
	v_sub_f32_e32 v8, v19, v66
	v_mul_f32_e32 v8, 0x3fb8aa3b, v8
	v_exp_f32_e32 v67, v8
	v_sub_f32_e32 v8, v20, v66
	v_mul_f32_e32 v8, 0x3fb8aa3b, v8
	v_exp_f32_e32 v68, v8
	v_sub_f32_e32 v8, v17, v66
	v_mul_f32_e32 v8, 0x3fb8aa3b, v8
	v_exp_f32_e32 v69, v8
	v_sub_f32_e32 v8, v22, v66
	v_mul_f32_e32 v8, 0x3fb8aa3b, v8
	v_exp_f32_e32 v15, v8
	v_sub_f32_e32 v8, v23, v66
	v_mul_f32_e32 v8, 0x3fb8aa3b, v8
	v_exp_f32_e32 v24, v8
	v_sub_f32_e32 v8, v44, v66
	v_mul_f32_e32 v8, 0x3fb8aa3b, v8
	v_exp_f32_e32 v26, v8
	v_sub_f32_e32 v8, v25, v66
	v_mul_f32_e32 v8, 0x3fb8aa3b, v8
	v_sub_f32_e32 v7, v11, v66
	v_exp_f32_e32 v31, v8
	v_sub_f32_e32 v8, v54, v66
	v_mul_f32_e32 v7, 0x3fb8aa3b, v7
	v_mul_f32_e32 v8, 0x3fb8aa3b, v8
	v_exp_f32_e32 v21, v7
	v_exp_f32_e32 v33, v8
	v_sub_f32_e32 v8, v27, v66
	v_mul_f32_e32 v8, 0x3fb8aa3b, v8
	v_exp_f32_e32 v81, v8
	v_sub_f32_e32 v8, v55, v66
	v_mul_f32_e32 v8, 0x3fb8aa3b, v8
	v_add_f32_e32 v7, 0, v21
	v_exp_f32_e32 v82, v8
	v_sub_f32_e32 v8, v29, v66
	v_add_f32_e32 v7, v28, v7
	v_mul_f32_e32 v8, 0x3fb8aa3b, v8
	v_add_f32_e32 v7, v30, v7
	v_exp_f32_e32 v83, v8
	v_sub_f32_e32 v8, v56, v66
	v_add_f32_e32 v7, v34, v7
	v_mul_f32_e32 v8, 0x3fb8aa3b, v8
	v_add_f32_e32 v7, v37, v7
	v_exp_f32_e32 v11, v8
	v_sub_f32_e32 v8, v57, v66
	v_add_f32_e32 v7, v67, v7
	v_mul_f32_e32 v8, 0x3fb8aa3b, v8
	v_add_f32_e32 v7, v68, v7
	v_exp_f32_e32 v20, v8
	v_sub_f32_e32 v8, v32, v66
	v_add_f32_e32 v7, v69, v7
	v_mul_f32_e32 v8, 0x3fb8aa3b, v8
	v_add_f32_e32 v7, v15, v7
	v_exp_f32_e32 v22, v8
	v_sub_f32_e32 v8, v58, v66
	v_add_f32_e32 v7, v24, v7
	v_mul_f32_e32 v8, 0x3fb8aa3b, v8
	v_add_f32_e32 v7, v26, v7
	v_exp_f32_e32 v27, v8
	v_sub_f32_e32 v8, v59, v66
	v_add_f32_e32 v7, v31, v7
	v_mul_f32_e32 v8, 0x3fb8aa3b, v8
	v_add_f32_e32 v7, v33, v7
	v_exp_f32_e32 v29, v8
	v_sub_f32_e32 v8, v35, v66
	v_add_f32_e32 v7, v81, v7
	v_mul_f32_e32 v8, 0x3fb8aa3b, v8
	v_sub_f32_e32 v9, v39, v66
	v_add_f32_e32 v7, v82, v7
	v_exp_f32_e32 v36, v8
	v_sub_f32_e32 v8, v60, v66
	v_mul_f32_e32 v9, 0x3fb8aa3b, v9
	v_add_f32_e32 v7, v83, v7
	v_mul_f32_e32 v8, 0x3fb8aa3b, v8
	v_exp_f32_e32 v14, v9
	v_sub_f32_e32 v9, v40, v66
	v_add_f32_e32 v7, v11, v7
	v_exp_f32_e32 v84, v8
	v_sub_f32_e32 v8, v61, v66
	v_mul_f32_e32 v9, 0x3fb8aa3b, v9
	v_add_f32_e32 v7, v20, v7
	v_mul_f32_e32 v8, 0x3fb8aa3b, v8
	v_exp_f32_e32 v18, v9
	v_sub_f32_e32 v9, v41, v66
	v_add_f32_e32 v7, v22, v7
	v_exp_f32_e32 v85, v8
	v_sub_f32_e32 v8, v38, v66
	v_mul_f32_e32 v9, 0x3fb8aa3b, v9
	v_add_f32_e32 v7, v27, v7
	v_mul_f32_e32 v8, 0x3fb8aa3b, v8
	v_exp_f32_e32 v23, v9
; __device__ __forceinline__ unsigned cvt_pk_bf16(float lo, float hi) { unsigned r; asm volatile("v_cvt_pk_bf16_f32 %0, %1, %2" : "=v"(r) : "v"(lo), "v"(hi)); return r; }
; #define LAS __attribute__((address_space(3)))
; #define MFMA16(a, b, c) __builtin_amdgcn_mfma_f32_16x16x32_bf16((a), (b), (c), 0, 0, 0)
; __device__ __forceinline__ void p2_block(LAS unsigned char* lds, const bf16_t* __restrict__ PROJ, bf16_t* __restrict__ ATT, bf16_t* __restrict__ SGU, const float* __restrict__ qn, const float* __restrict__ kn, ...
;     ...
;         mx = fmaxf(mx, __shfl_xor(mx, 16)); mx = fmaxf(mx, __shfl_xor(mx, 32)); mx = fmaxf(mx, sink);
;         float sum = 0.f;
; #pragma unroll
;         for (int t = 0; t < 10; ++t)
; #pragma unroll
;             for (int e = 0; e < 4; ++e) { const float p = __builtin_amdgcn_exp2f((sc_[t][e] - mx) * LOG2E); sc_[t][e] = p; sum += p; }
;         sum += __shfl_xor(sum, 16); sum += __shfl_xor(sum, 32);
;         const float inv = 1.0f / (sum + __builtin_amdgcn_exp2f((sink - mx) * LOG2E));
;         f32x4 o[4];
; #pragma unroll
;         for (int dt = 0; dt < 4; ++dt) o[dt] = (f32x4){0.f, 0.f, 0.f, 0.f};
; #pragma unroll
;         for (int j = 0; j < 5; ++j) {
;             u32x4 pw; pw.x = cvt_pk_bf16(sc_[2 * j][0], sc_[2 * j][1]); pw.y = cvt_pk_bf16(sc_[2 * j][2], sc_[2 * j][3]); pw.z = cvt_pk_bf16(sc_[2 * j + 1][0], sc_[2 * j + 1][1]); pw.w = cvt_pk_bf16(sc_[2 * j + 1][2], sc_[2 * j + 1][3]);
;             const bf16x8 pf = __builtin_bit_cast(bf16x8, pw);
; #pragma unroll
;             for (int dt = 0; dt < 4; ++dt) { const LAS unsigned char* vb = VT + (16 * dt + fr) * VT_STRIDE + (16 * (t0 + 2 * j) + 4 * fq) * 2;
;                 const u32x2 va = *(const LAS u32x2*)vb, vc = *(const LAS u32x2*)(vb + 32); u32x4 vw; vw.x = va.x; vw.y = va.y; vw.z = vc.x; vw.w = vc.y;
;                 o[dt] = MFMA16(__builtin_bit_cast(bf16x8, vw), pf, o[dt]); }
;         }
	v_sub_f32_e32 v9, v46, v66
	v_add_f32_e32 v7, v29, v7
	v_exp_f32_e32 v8, v8
	v_mul_f32_e32 v9, 0x3fb8aa3b, v9
	v_add_f32_e32 v7, v36, v7
	v_exp_f32_e32 v25, v9
	v_sub_f32_e32 v9, v47, v66
	v_add_f32_e32 v7, v84, v7
	v_mul_f32_e32 v9, 0x3fb8aa3b, v9
	v_add_f32_e32 v7, v85, v7
	v_exp_f32_e32 v32, v9
	v_sub_f32_e32 v9, v48, v66
	v_add_f32_e32 v7, v8, v7
	v_mul_f32_e32 v9, 0x3fb8aa3b, v9
	v_add_f32_e32 v7, v14, v7
	v_exp_f32_e32 v35, v9
	v_sub_f32_e32 v9, v49, v66
	v_add_f32_e32 v7, v18, v7
	v_mul_f32_e32 v9, 0x3fb8aa3b, v9
	v_add_f32_e32 v7, v23, v7
	v_exp_f32_e32 v86, v9
	v_add_f32_e32 v7, v25, v7
	v_add_f32_e32 v7, v32, v7
	v_add_f32_e32 v7, v35, v7
	v_add_f32_e32 v9, v86, v7
	v_sub_f32_e32 v7, v50, v66
	v_mul_f32_e32 v7, 0x3fb8aa3b, v7
	v_exp_f32_e32 v7, v7
	v_sub_f32_e32 v6, v6, v66
	v_mul_f32_e32 v6, 0x3fb8aa3b, v6
	v_sub_f32_e32 v17, v64, v66
	v_add_f32_e32 v10, v7, v9
	v_sub_f32_e32 v9, v51, v66
	v_mul_f32_e32 v9, 0x3fb8aa3b, v9
	v_exp_f32_e32 v9, v9
	v_mul_f32_e32 v17, 0x3fb8aa3b, v17
	v_sub_f32_e32 v19, v65, v66
	v_exp_f32_e32 v17, v17
	v_add_f32_e32 v12, v9, v10
	v_sub_f32_e32 v10, v52, v66
	v_mul_f32_e32 v10, 0x3fb8aa3b, v10
	v_exp_f32_e32 v10, v10
	v_mul_f32_e32 v19, 0x3fb8aa3b, v19
	v_exp_f32_e32 v19, v19
	v_or_b32_e32 v44, s48, v62
	v_add_f32_e32 v13, v10, v12
	v_sub_f32_e32 v12, v53, v66
	v_mul_f32_e32 v12, 0x3fb8aa3b, v12
	v_exp_f32_e32 v12, v12
	s_nop 0
	v_add_f32_e32 v16, v12, v13
	v_exp_f32_e32 v13, v6
	s_nop 0
	v_add_f32_e32 v6, v13, v16
	v_sub_f32_e32 v16, v63, v66
	v_mul_f32_e32 v16, 0x3fb8aa3b, v16
	v_exp_f32_e32 v16, v16
	s_nop 0
	v_add_f32_e32 v6, v16, v6
	v_add_f32_e32 v6, v17, v6
	v_add_f32_e32 v6, v19, v6
	ds_bpermute_b32 v38, v76, v6
	s_waitcnt lgkmcnt(0)
	v_add_f32_e32 v6, v6, v38
	ds_bpermute_b32 v38, v77, v6
	s_waitcnt lgkmcnt(0)
	v_add_f32_e32 v6, v6, v38
	v_sub_f32_e32 v38, v75, v66
	v_mul_f32_e32 v38, 0x3fb8aa3b, v38
	v_exp_f32_e32 v38, v38
	s_nop 0
	v_add_f32_e32 v6, v38, v6
	v_cvt_pk_bf16_f32 v38, v21, v28
	v_lshl_add_u32 v21, s17, 5, v74
	v_mad_u32_u24 v28, v137, s81, v21
	v_add_u32_e32 v28, 0x9000, v28
	v_cvt_pk_bf16_f32 v39, v30, v34
	v_cvt_pk_bf16_f32 v40, v37, v67
	v_cvt_pk_bf16_f32 v41, v68, v69
	ds_read2_b64 v[46:49], v28 offset1:4
	v_add_u32_e32 v28, v21, v80
	v_add_u32_e32 v28, 0x9000, v28
	ds_read2_b64 v[50:53], v28 offset1:4
	v_add_u32_e32 v28, v21, v79
	v_add_u32_e32 v21, v21, v78
	v_add_u32_e32 v28, 0x9000, v28
	v_add_u32_e32 v21, 0x9000, v21
	ds_read2_b64 v[54:57], v28 offset1:4
	ds_read2_b64 v[58:61], v21 offset1:4
	s_waitcnt lgkmcnt(3)
	v_mfma_f32_16x16x32_bf16 v[46:49], v[46:49], v[38:41], 0
	s_waitcnt lgkmcnt(2)
	v_mfma_f32_16x16x32_bf16 v[50:53], v[50:53], v[38:41], 0
	s_waitcnt lgkmcnt(1)
	v_mfma_f32_16x16x32_bf16 v[54:57], v[54:57], v[38:41], 0
	s_waitcnt lgkmcnt(0)
	v_mfma_f32_16x16x32_bf16 v[38:41], v[58:61], v[38:41], 0
	v_cvt_pk_bf16_f32 v58, v15, v24
	v_lshl_add_u32 v15, s27, 5, v74
	v_mad_u32_u24 v21, v137, s81, v15
	v_add_u32_e32 v21, 0x9000, v21
	v_cvt_pk_bf16_f32 v59, v26, v31
	v_cvt_pk_bf16_f32 v60, v33, v81
	v_cvt_pk_bf16_f32 v61, v82, v83
	ds_read2_b64 v[62:65], v21 offset1:4
	v_add_u32_e32 v21, v15, v80
	v_add_u32_e32 v21, 0x9000, v21
	s_waitcnt lgkmcnt(0)
	v_mfma_f32_16x16x32_bf16 v[46:49], v[62:65], v[58:61], v[46:49]
	ds_read2_b64 v[62:65], v21 offset1:4
	v_add_u32_e32 v21, v15, v79
	v_add_u32_e32 v21, 0x9000, v21
	s_waitcnt lgkmcnt(0)
	v_mfma_f32_16x16x32_bf16 v[50:53], v[62:65], v[58:61], v[50:53]
	ds_read2_b64 v[62:65], v21 offset1:4
	v_add_u32_e32 v15, v15, v78
	v_add_u32_e32 v15, 0x9000, v15
	s_waitcnt lgkmcnt(0)
	v_mfma_f32_16x16x32_bf16 v[54:57], v[62:65], v[58:61], v[54:57]
	ds_read2_b64 v[62:65], v15 offset1:4
	v_cvt_pk_bf16_f32 v26, v11, v20
	v_lshl_add_u32 v11, s26, 5, v74
	v_mad_u32_u24 v15, v137, s81, v11
	v_add_u32_e32 v15, 0x9000, v15
	s_waitcnt lgkmcnt(0)
	v_mfma_f32_16x16x32_bf16 v[38:41], v[62:65], v[58:61], v[38:41]
	v_cvt_pk_bf16_f32 v27, v22, v27
	v_cvt_pk_bf16_f32 v28, v29, v36
	v_cvt_pk_bf16_f32 v29, v84, v85
	ds_read2_b64 v[58:61], v15 offset1:4
	v_add_u32_e32 v15, v11, v80
	v_add_u32_e32 v15, 0x9000, v15
	s_waitcnt lgkmcnt(0)
	v_mfma_f32_16x16x32_bf16 v[46:49], v[58:61], v[26:29], v[46:49]
	ds_read2_b64 v[58:61], v15 offset1:4
	v_add_u32_e32 v15, v11, v79
	v_add_u32_e32 v15, 0x9000, v15
	s_waitcnt lgkmcnt(0)
	v_mfma_f32_16x16x32_bf16 v[50:53], v[58:61], v[26:29], v[50:53]
	ds_read2_b64 v[58:61], v15 offset1:4
	v_add_u32_e32 v11, v11, v78
	v_add_u32_e32 v11, 0x9000, v11
	s_waitcnt lgkmcnt(0)
	v_mfma_f32_16x16x32_bf16 v[54:57], v[58:61], v[26:29], v[54:57]
	ds_read2_b64 v[58:61], v11 offset1:4
	v_cvt_pk_bf16_f32 v20, v8, v14
	v_lshl_add_u32 v8, s6, 5, v74
	v_mad_u32_u24 v11, v137, s81, v8
	v_add_u32_e32 v11, 0x9000, v11
	v_cvt_pk_bf16_f32 v21, v18, v23
	v_cvt_pk_bf16_f32 v22, v25, v32
	v_cvt_pk_bf16_f32 v23, v35, v86
	ds_read2_b64 v[30:33], v11 offset1:4
	v_add_u32_e32 v11, v8, v80
	v_add_u32_e32 v11, 0x9000, v11
	ds_read2_b64 v[34:37], v11 offset1:4
	v_add_u32_e32 v11, v8, v79
	v_add_u32_e32 v8, v8, v78
	v_add_u32_e32 v11, 0x9000, v11
	v_add_u32_e32 v8, 0x9000, v8
	s_waitcnt lgkmcnt(2)
	v_mfma_f32_16x16x32_bf16 v[26:29], v[58:61], v[26:29], v[38:41]
	s_waitcnt lgkmcnt(1)
; #define LAS __attribute__((address_space(3)))
; #define MFMA16(a, b, c) __builtin_amdgcn_mfma_f32_16x16x32_bf16((a), (b), (c), 0, 0, 0)
; __device__ __forceinline__ void p2_block(LAS unsigned char* lds, const bf16_t* __restrict__ PROJ, bf16_t* __restrict__ ATT, bf16_t* __restrict__ SGU, const float* __restrict__ qn, const float* __restrict__ kn, ...
;     ...
;         for (int j = 0; j < 5; ++j) {
;             u32x4 pw; pw.x = cvt_pk_bf16(sc_[2 * j][0], sc_[2 * j][1]); pw.y = cvt_pk_bf16(sc_[2 * j][2], sc_[2 * j][3]); pw.z = cvt_pk_bf16(sc_[2 * j + 1][0], sc_[2 * j + 1][1]); pw.w = cvt_pk_bf16(sc_[2 * j + 1][2], sc_[2 * j + 1][3]);
;             const bf16x8 pf = __builtin_bit_cast(bf16x8, pw);
; #pragma unroll
;             for (int dt = 0; dt < 4; ++dt) { const LAS unsigned char* vb = VT + (16 * dt + fr) * VT_STRIDE + (16 * (t0 + 2 * j) + 4 * fq) * 2;
;                 const u32x2 va = *(const LAS u32x2*)vb, vc = *(const LAS u32x2*)(vb + 32); u32x4 vw; vw.x = va.x; vw.y = va.y; vw.z = vc.x; vw.w = vc.y;
;                 o[dt] = MFMA16(__builtin_bit_cast(bf16x8, vw), pf, o[dt]); }
;         }
;         bf16_t* op = ATT + grow * 1024 + hq * 64 + 4 * fq;
; #pragma unroll
;         for (int dt = 0; dt < 4; ++dt) { u32x2 ow; ow.x = cvt_pk_bf16(o[dt][0] * inv, o[dt][1] * inv); ow.y = cvt_pk_bf16(o[dt][2] * inv, o[dt][3] * inv); *(u32x2*)(op + 16 * dt) = ow; }
;     ...
;     for (int gi = 0; gi < 2; ++gi) {
;         const int gg = 2 * kvh + gi, irow = 16 * w + fr, nks = (w >> 1) + 1;
;         const LAS unsigned char* VNT = lds + (gi ? VN_OFF1 : VN_OFF0);
;         f32x4 acc[8];
; #pragma unroll
;         for (int dt = 0; dt < 8; ++dt) acc[dt] = (f32x4){0.f, 0.f, 0.f, 0.f};
;         const float* wrow = wsp + (size_t)gg * 16384 + irow * 128 + 8 * fq;
; #pragma unroll
;         for (int ks = 0; ks < 4; ++ks) if (ks < nks) {
;             const f32x4 wa = *(const f32x4*)(wrow + 32 * ks), wb = *(const f32x4*)(wrow + 32 * ks + 4);
;             const int j0 = 32 * ks + 8 * fq; float wv[8];
; #pragma unroll
;             for (int e = 0; e < 4; ++e) { wv[e] = (j0 + e <= irow) ? wa[e] : 0.f; wv[4 + e] = (j0 + 4 + e <= irow) ? wb[e] : 0.f; }
;             u32x4 ww; ww.x = cvt_pk_bf16(wv[0], wv[1]); ww.y = cvt_pk_bf16(wv[2], wv[3]); ww.z = cvt_pk_bf16(wv[4], wv[5]); ww.w = cvt_pk_bf16(wv[6], wv[7]);
;             const bf16x8 wf = __builtin_bit_cast(bf16x8, ww);
; #pragma unroll
	v_mfma_f32_16x16x32_bf16 v[30:33], v[30:33], v[20:23], v[46:49]
	s_nop 0
	ds_read2_b64 v[38:41], v11 offset1:4
	s_nop 0
	ds_read2_b64 v[46:49], v8 offset1:4
	v_cvt_pk_bf16_f32 v8, v7, v9
	v_lshl_add_u32 v7, s4, 5, v74
	v_cvt_pk_bf16_f32 v9, v10, v12
	v_mad_u32_u24 v12, v137, s81, v7
	v_add_u32_e32 v12, 0x9000, v12
	v_cvt_pk_bf16_f32 v10, v13, v16
	v_cvt_pk_bf16_f32 v11, v17, v19
	ds_read2_b64 v[12:15], v12 offset1:4
	v_add_u32_e32 v16, v7, v80
	v_add_u32_e32 v24, v7, v79
	v_add_u32_e32 v7, v7, v78
	v_add_u32_e32 v16, 0x9000, v16
	v_add_u32_e32 v24, 0x9000, v24
	v_add_u32_e32 v7, 0x9000, v7
	s_waitcnt lgkmcnt(3)
	v_mfma_f32_16x16x32_bf16 v[34:37], v[34:37], v[20:23], v[50:53]
	ds_read2_b64 v[16:19], v16 offset1:4
	s_ashr_i32 s4, s16, 2
	s_waitcnt lgkmcnt(3)
	v_mfma_f32_16x16x32_bf16 v[38:41], v[38:41], v[20:23], v[54:57]
	s_waitcnt lgkmcnt(2)
	v_mfma_f32_16x16x32_bf16 v[20:23], v[46:49], v[20:23], v[26:29]
	v_or_b32_e32 v49, 5, v130
	v_or_b32_e32 v48, 6, v130
	v_or_b32_e32 v46, 7, v130
	s_waitcnt lgkmcnt(1)
	v_mfma_f32_16x16x32_bf16 v[12:15], v[12:15], v[8:11], v[30:33]
	ds_read2_b64 v[24:27], v24 offset1:4
	s_nop 1
	ds_read2_b64 v[28:31], v7 offset1:4
	v_div_scale_f32 v7, s[6:7], v6, v6, 1.0
	s_waitcnt lgkmcnt(2)
	v_mfma_f32_16x16x32_bf16 v[16:19], v[16:19], v[8:11], v[34:37]
	s_waitcnt lgkmcnt(1)
	v_mfma_f32_16x16x32_bf16 v[24:27], v[24:27], v[8:11], v[38:41]
	s_nop 0
	v_bfi_b32 v36, -16, s4, v160
	s_lshl_b32 s4, s73, 17
	s_cmp_gt_i32 s77, -1
	s_waitcnt lgkmcnt(0)
	v_mfma_f32_16x16x32_bf16 v[8:11], v[28:31], v[8:11], v[20:23]
	v_mov_b64_e32 v[32:33], v[4:5]
	s_cselect_b64 s[28:29], -1, 0
	s_cmp_lt_i32 s77, 0
	v_rcp_f32_e32 v20, v7
	v_cmp_le_i32_e64 s[40:41], v72, v36
	v_cmp_lt_i32_e64 s[42:43], v130, v36
	v_cmp_le_i32_e64 s[44:45], v71, v36
	v_fma_f32 v21, -v7, v20, 1.0
	v_fmac_f32_e32 v20, v21, v20
	v_div_scale_f32 v21, vcc, 1.0, v6, 1.0
	v_mul_f32_e32 v22, v21, v20
	v_fma_f32 v23, -v7, v22, v21
	v_fmac_f32_e32 v22, v23, v20
	v_fma_f32 v7, -v7, v22, v21
	v_div_fmas_f32 v7, v7, v20, v22
	v_div_fixup_f32 v20, v7, v6, 1.0
	v_mul_f32_e32 v12, v20, v12
	v_mul_f32_e32 v13, v20, v13
	v_lshlrev_b64 v[6:7], 11, v[44:45]
	v_cvt_pk_bf16_f32 v12, v12, v13
	v_mul_f32_e32 v13, v20, v14
	v_lshl_add_u64 v[6:7], v[42:43], 0, v[6:7]
	v_mul_f32_e32 v14, v20, v15
	v_cvt_pk_bf16_f32 v13, v13, v14
	global_store_dwordx2 v[6:7], v[12:13], off
	v_mul_f32_e32 v12, v20, v16
	v_mul_f32_e32 v13, v20, v17
	v_cvt_pk_bf16_f32 v12, v12, v13
	v_mul_f32_e32 v13, v20, v18
	v_mul_f32_e32 v14, v20, v19
	v_cvt_pk_bf16_f32 v13, v13, v14
	global_store_dwordx2 v[6:7], v[12:13], off offset:32
	v_mul_f32_e32 v12, v20, v24
	v_mul_f32_e32 v13, v20, v25
	v_cvt_pk_bf16_f32 v12, v12, v13
	v_mul_f32_e32 v13, v20, v26
	v_mul_f32_e32 v8, v20, v8
	v_mul_f32_e32 v9, v20, v9
	v_mul_f32_e32 v14, v20, v27
	v_cvt_pk_bf16_f32 v13, v13, v14
	global_store_dwordx2 v[6:7], v[12:13], off offset:64
	v_cvt_pk_bf16_f32 v8, v8, v9
	v_mul_f32_e32 v9, v20, v10
	v_mul_f32_e32 v10, v20, v11
	v_cvt_pk_bf16_f32 v9, v9, v10
	global_store_dwordx2 v[6:7], v[8:9], off offset:96
	v_lshlrev_b32_e32 v6, 7, v36
	v_ashrrev_i32_e32 v7, 31, v6
	v_lshl_add_u64 v[6:7], v[6:7], 2, s[20:21]
	v_lshl_add_u64 v[34:35], v[6:7], 0, v[0:1]
	v_mov_b64_e32 v[8:9], v[4:5]
	v_mov_b64_e32 v[12:13], v[4:5]
	v_mov_b64_e32 v[16:17], v[4:5]
	v_mov_b64_e32 v[20:21], v[4:5]
	v_mov_b64_e32 v[24:25], v[4:5]
	v_mov_b64_e32 v[28:29], v[4:5]
	v_lshl_add_u64 v[38:39], v[34:35], 0, s[4:5]
	v_cmp_le_i32_e32 vcc, v130, v36
	v_cmp_le_i32_e64 s[46:47], v70, v36
	v_mul_u32_u24_e32 v44, 0x110, v137
	v_cmp_le_i32_e64 s[52:53], v49, v36
	v_cmp_le_i32_e64 s[50:51], v48, v36
	v_cmp_le_i32_e64 s[48:49], v46, v36
	v_mov_b64_e32 v[6:7], v[2:3]
	v_mov_b64_e32 v[10:11], v[2:3]
	v_mov_b64_e32 v[14:15], v[2:3]
	v_mov_b64_e32 v[18:19], v[2:3]
	v_mov_b64_e32 v[22:23], v[2:3]
	v_mov_b64_e32 v[26:27], v[2:3]
	v_mov_b64_e32 v[30:31], v[2:3]
	s_cbranch_scc1 .LBB0_332
	global_load_dwordx4 v[2:5], v[38:39], off offset:16
	global_load_dwordx4 v[6:9], v[38:39], off
	s_add_i32 s4, 0, 0x11800
	s_waitcnt vmcnt(1)
	v_cndmask_b32_e64 v5, 0, v5, s[48:49]
	s_waitcnt vmcnt(0)
	v_cndmask_b32_e32 v0, 0, v6, vcc
	v_cndmask_b32_e64 v6, 0, v2, s[40:41]
	v_cndmask_b32_e64 v2, 0, v7, s[42:43]
	v_cndmask_b32_e64 v7, 0, v3, s[52:53]
	v_cndmask_b32_e64 v3, 0, v8, s[44:45]
	v_cndmask_b32_e64 v8, 0, v4, s[50:51]
	v_cndmask_b32_e64 v4, 0, v9, s[46:47]
	v_cvt_pk_bf16_f32 v2, v0, v2
	v_add3_u32 v0, s4, v132, v44
	v_cvt_pk_bf16_f32 v3, v3, v4
	v_cvt_pk_bf16_f32 v4, v6, v7
	v_cvt_pk_bf16_f32 v5, v8, v5
	ds_read_b128 v[6:9], v0
	ds_read_b128 v[40:43], v0 offset:30464
	s_waitcnt lgkmcnt(1)
	v_mfma_f32_16x16x32_bf16 v[30:33], v[6:9], v[2:5], 0
	ds_read_b128 v[6:9], v0 offset:4352
	s_waitcnt lgkmcnt(0)
	v_mfma_f32_16x16x32_bf16 v[26:29], v[6:9], v[2:5], 0
	ds_read_b128 v[6:9], v0 offset:8704
	s_waitcnt lgkmcnt(0)
	v_mfma_f32_16x16x32_bf16 v[22:25], v[6:9], v[2:5], 0
	ds_read_b128 v[6:9], v0 offset:13056
	s_waitcnt lgkmcnt(0)
	v_mfma_f32_16x16x32_bf16 v[18:21], v[6:9], v[2:5], 0
	ds_read_b128 v[6:9], v0 offset:17408
	s_waitcnt lgkmcnt(0)
	v_mfma_f32_16x16x32_bf16 v[14:17], v[6:9], v[2:5], 0
	ds_read_b128 v[6:9], v0 offset:21760
	s_waitcnt lgkmcnt(0)
	v_mfma_f32_16x16x32_bf16 v[10:13], v[6:9], v[2:5], 0
	ds_read_b128 v[6:9], v0 offset:26112
	s_waitcnt lgkmcnt(0)
	v_mfma_f32_16x16x32_bf16 v[6:9], v[6:9], v[2:5], 0
	v_mfma_f32_16x16x32_bf16 v[2:5], v[40:43], v[2:5], 0
